# bulk 16-byte stores of the GEMM phases (epilogues, split-K slabs, converted weights) made write-through (sc1) so the grid barrier L2 write-back finds little dirty data
# baseline (speedup 1.0000x reference)
.LBB0_185:
	v_pk_mul_f32 v[158:159], v[126:127], s[8:9] op_sel_hi:[1,0]
	v_pk_mul_f32 v[160:161], v[124:125], s[8:9] op_sel_hi:[1,0]
	v_pk_mul_f32 v[162:163], v[122:123], s[8:9] op_sel_hi:[1,0]
	v_pk_mul_f32 v[164:165], v[120:121], s[8:9] op_sel_hi:[1,0]
	v_exp_f32_e32 v160, v160
	v_exp_f32_e32 v164, v164
	v_exp_f32_e32 v161, v161
	v_exp_f32_e32 v158, v158
	v_exp_f32_e32 v159, v159
	v_exp_f32_e32 v162, v162
	v_exp_f32_e32 v163, v163
	v_exp_f32_e32 v165, v165
	v_pk_add_f32 v[158:159], v[158:159], 1.0 op_sel_hi:[1,0]
	v_pk_add_f32 v[160:161], v[160:161], 1.0 op_sel_hi:[1,0]
	v_pk_add_f32 v[162:163], v[162:163], 1.0 op_sel_hi:[1,0]
	v_pk_add_f32 v[164:165], v[164:165], 1.0 op_sel_hi:[1,0]
	v_rcp_f32_e32 v160, v160
	v_rcp_f32_e32 v164, v164
	v_rcp_f32_e32 v161, v161
	v_rcp_f32_e32 v165, v165
	v_rcp_f32_e32 v158, v158
	v_rcp_f32_e32 v162, v162
	v_rcp_f32_e32 v159, v159
	v_rcp_f32_e32 v163, v163
	v_readlane_b32 s30, v253, 8
	v_lshl_or_b32 v146, s36, 7, v152
	v_readlane_b32 s31, v253, 9
	v_lshl_add_u32 v166, s52, 8, v150
	v_ashrrev_i32_e32 v147, 31, v146
	v_mov_b64_e32 v[144:145], s[30:31]
	v_pk_mul_f32 v[118:119], v[118:119], v[126:127]
	v_pk_mul_f32 v[116:117], v[116:117], v[124:125]
	v_pk_mul_f32 v[114:115], v[114:115], v[122:123]
	v_pk_mul_f32 v[112:113], v[112:113], v[120:121]
	v_mad_i64_i32 v[156:157], s[30:31], v166, s83, v[144:145]
	v_lshlrev_b64 v[146:147], 1, v[146:147]
	v_pk_mul_f32 v[118:119], v[118:119], v[158:159]
	v_pk_mul_f32 v[116:117], v[116:117], v[160:161]
	v_pk_mul_f32 v[120:121], v[114:115], v[162:163]
	v_pk_mul_f32 v[114:115], v[112:113], v[164:165]
	v_lshl_add_u64 v[156:157], v[156:157], 0, v[146:147]
	v_cvt_pk_bf16_f32 v112, v116, v117
	v_cvt_pk_bf16_f32 v113, v118, v119
	v_cvt_pk_bf16_f32 v114, v114, v115
	v_cvt_pk_bf16_f32 v115, v120, v121
	global_store_dwordx4 v[156:157], v[112:115], off sc1
	v_pk_mul_f32 v[116:117], v[108:109], s[8:9] op_sel_hi:[1,0]
	v_pk_mul_f32 v[118:119], v[106:107], s[8:9] op_sel_hi:[1,0]
	v_pk_mul_f32 v[114:115], v[110:111], s[8:9] op_sel_hi:[1,0]
	v_pk_mul_f32 v[120:121], v[104:105], s[8:9] op_sel_hi:[1,0]
	v_exp_f32_e32 v116, v116
	v_exp_f32_e32 v120, v120
	v_exp_f32_e32 v117, v117
	v_exp_f32_e32 v114, v114
	v_exp_f32_e32 v115, v115
	v_exp_f32_e32 v118, v118
	v_exp_f32_e32 v119, v119
	v_exp_f32_e32 v121, v121
	v_pk_add_f32 v[114:115], v[114:115], 1.0 op_sel_hi:[1,0]
	v_pk_add_f32 v[116:117], v[116:117], 1.0 op_sel_hi:[1,0]
	v_pk_add_f32 v[118:119], v[118:119], 1.0 op_sel_hi:[1,0]
	v_pk_add_f32 v[120:121], v[120:121], 1.0 op_sel_hi:[1,0]
	v_rcp_f32_e32 v116, v116
	v_rcp_f32_e32 v120, v120
	v_rcp_f32_e32 v117, v117
	v_rcp_f32_e32 v121, v121
	v_rcp_f32_e32 v114, v114
	v_rcp_f32_e32 v118, v118
	v_rcp_f32_e32 v115, v115
	v_rcp_f32_e32 v119, v119
	v_or_b32_e32 v112, 16, v166
	v_pk_mul_f32 v[102:103], v[102:103], v[110:111]
	v_pk_mul_f32 v[100:101], v[100:101], v[108:109]
	v_pk_mul_f32 v[98:99], v[98:99], v[106:107]
	v_pk_mul_f32 v[96:97], v[96:97], v[104:105]
	v_mad_i64_i32 v[112:113], s[30:31], v112, s83, v[144:145]
	v_pk_mul_f32 v[102:103], v[102:103], v[114:115]
	v_pk_mul_f32 v[100:101], v[100:101], v[116:117]
	v_pk_mul_f32 v[104:105], v[98:99], v[118:119]
	v_pk_mul_f32 v[98:99], v[96:97], v[120:121]
	v_lshl_add_u64 v[112:113], v[112:113], 0, v[146:147]
	v_cvt_pk_bf16_f32 v96, v100, v101
	v_cvt_pk_bf16_f32 v97, v102, v103
	v_cvt_pk_bf16_f32 v98, v98, v99
	v_cvt_pk_bf16_f32 v99, v104, v105
	global_store_dwordx4 v[112:113], v[96:99], off sc1
	v_pk_mul_f32 v[100:101], v[92:93], s[8:9] op_sel_hi:[1,0]
	v_pk_mul_f32 v[102:103], v[90:91], s[8:9] op_sel_hi:[1,0]
	v_pk_mul_f32 v[98:99], v[94:95], s[8:9] op_sel_hi:[1,0]
	v_pk_mul_f32 v[104:105], v[88:89], s[8:9] op_sel_hi:[1,0]
	v_exp_f32_e32 v100, v100
	v_exp_f32_e32 v104, v104
	v_exp_f32_e32 v101, v101
	v_exp_f32_e32 v98, v98
	v_exp_f32_e32 v99, v99
	v_exp_f32_e32 v102, v102
	v_exp_f32_e32 v103, v103
	v_exp_f32_e32 v105, v105
	v_pk_add_f32 v[98:99], v[98:99], 1.0 op_sel_hi:[1,0]
	v_pk_add_f32 v[100:101], v[100:101], 1.0 op_sel_hi:[1,0]
	v_pk_add_f32 v[102:103], v[102:103], 1.0 op_sel_hi:[1,0]
	v_pk_add_f32 v[104:105], v[104:105], 1.0 op_sel_hi:[1,0]
	v_rcp_f32_e32 v100, v100
	v_rcp_f32_e32 v104, v104
	v_rcp_f32_e32 v101, v101
	v_rcp_f32_e32 v105, v105
	v_rcp_f32_e32 v98, v98
	v_rcp_f32_e32 v102, v102
	v_rcp_f32_e32 v99, v99
	v_rcp_f32_e32 v103, v103
	v_or_b32_e32 v96, 32, v166
	v_pk_mul_f32 v[86:87], v[86:87], v[94:95]
	v_pk_mul_f32 v[84:85], v[84:85], v[92:93]
	v_pk_mul_f32 v[82:83], v[82:83], v[90:91]
	v_pk_mul_f32 v[80:81], v[80:81], v[88:89]
	v_mad_i64_i32 v[96:97], s[30:31], v96, s83, v[144:145]
	v_pk_mul_f32 v[86:87], v[86:87], v[98:99]
	v_pk_mul_f32 v[84:85], v[84:85], v[100:101]
	v_pk_mul_f32 v[88:89], v[82:83], v[102:103]
	v_pk_mul_f32 v[82:83], v[80:81], v[104:105]
	v_lshl_add_u64 v[96:97], v[96:97], 0, v[146:147]
	v_cvt_pk_bf16_f32 v80, v84, v85
	v_cvt_pk_bf16_f32 v81, v86, v87
	v_cvt_pk_bf16_f32 v82, v82, v83
	v_cvt_pk_bf16_f32 v83, v88, v89
	global_store_dwordx4 v[96:97], v[80:83], off sc1
	v_pk_mul_f32 v[84:85], v[76:77], s[8:9] op_sel_hi:[1,0]
	v_pk_mul_f32 v[86:87], v[74:75], s[8:9] op_sel_hi:[1,0]
	v_pk_mul_f32 v[82:83], v[78:79], s[8:9] op_sel_hi:[1,0]
	v_pk_mul_f32 v[88:89], v[72:73], s[8:9] op_sel_hi:[1,0]
	v_exp_f32_e32 v84, v84
	v_exp_f32_e32 v88, v88
	v_exp_f32_e32 v85, v85
	v_exp_f32_e32 v82, v82
	v_exp_f32_e32 v83, v83
	v_exp_f32_e32 v86, v86
	v_exp_f32_e32 v87, v87
	v_exp_f32_e32 v89, v89
	v_pk_add_f32 v[82:83], v[82:83], 1.0 op_sel_hi:[1,0]
	v_pk_add_f32 v[84:85], v[84:85], 1.0 op_sel_hi:[1,0]
	v_pk_add_f32 v[86:87], v[86:87], 1.0 op_sel_hi:[1,0]
	v_pk_add_f32 v[88:89], v[88:89], 1.0 op_sel_hi:[1,0]
	v_rcp_f32_e32 v84, v84
	v_rcp_f32_e32 v88, v88
	v_rcp_f32_e32 v85, v85
	v_rcp_f32_e32 v89, v89
	v_rcp_f32_e32 v82, v82
	v_rcp_f32_e32 v86, v86
	v_rcp_f32_e32 v83, v83
	v_rcp_f32_e32 v87, v87
	v_or_b32_e32 v80, 48, v166
	v_pk_mul_f32 v[70:71], v[70:71], v[78:79]
	v_pk_mul_f32 v[68:69], v[68:69], v[76:77]
	v_pk_mul_f32 v[66:67], v[66:67], v[74:75]
	v_pk_mul_f32 v[64:65], v[64:65], v[72:73]
	v_mad_i64_i32 v[80:81], s[30:31], v80, s83, v[144:145]
	v_pk_mul_f32 v[70:71], v[70:71], v[82:83]
	v_pk_mul_f32 v[68:69], v[68:69], v[84:85]
	v_pk_mul_f32 v[72:73], v[66:67], v[86:87]
	v_pk_mul_f32 v[66:67], v[64:65], v[88:89]
	v_lshl_add_u64 v[80:81], v[80:81], 0, v[146:147]
	v_cvt_pk_bf16_f32 v64, v68, v69
	v_cvt_pk_bf16_f32 v65, v70, v71
	v_cvt_pk_bf16_f32 v66, v66, v67
	v_cvt_pk_bf16_f32 v67, v72, v73
	global_store_dwordx4 v[80:81], v[64:67], off sc1
	v_pk_mul_f32 v[68:69], v[60:61], s[8:9] op_sel_hi:[1,0]
	v_pk_mul_f32 v[70:71], v[58:59], s[8:9] op_sel_hi:[1,0]
	v_pk_mul_f32 v[66:67], v[62:63], s[8:9] op_sel_hi:[1,0]
	v_pk_mul_f32 v[72:73], v[56:57], s[8:9] op_sel_hi:[1,0]
	v_exp_f32_e32 v68, v68
	v_exp_f32_e32 v72, v72
	v_exp_f32_e32 v69, v69
	v_exp_f32_e32 v66, v66
	v_exp_f32_e32 v67, v67
	v_exp_f32_e32 v70, v70
	v_exp_f32_e32 v71, v71
	v_exp_f32_e32 v73, v73
	v_pk_add_f32 v[66:67], v[66:67], 1.0 op_sel_hi:[1,0]
	v_pk_add_f32 v[68:69], v[68:69], 1.0 op_sel_hi:[1,0]
	v_pk_add_f32 v[70:71], v[70:71], 1.0 op_sel_hi:[1,0]
	v_pk_add_f32 v[72:73], v[72:73], 1.0 op_sel_hi:[1,0]
	v_rcp_f32_e32 v68, v68
	v_rcp_f32_e32 v72, v72
	v_rcp_f32_e32 v69, v69
	v_rcp_f32_e32 v73, v73
	v_rcp_f32_e32 v66, v66
	v_rcp_f32_e32 v70, v70
	v_rcp_f32_e32 v67, v67
	v_rcp_f32_e32 v71, v71
	v_add_u32_e32 v64, 0x80, v166
	v_pk_mul_f32 v[54:55], v[54:55], v[62:63]
	v_pk_mul_f32 v[52:53], v[52:53], v[60:61]
	v_pk_mul_f32 v[50:51], v[50:51], v[58:59]
	v_pk_mul_f32 v[48:49], v[48:49], v[56:57]
	v_mad_i64_i32 v[64:65], s[30:31], v64, s83, v[144:145]
	v_pk_mul_f32 v[54:55], v[54:55], v[66:67]
	v_pk_mul_f32 v[52:53], v[52:53], v[68:69]
	v_pk_mul_f32 v[56:57], v[50:51], v[70:71]
	v_pk_mul_f32 v[50:51], v[48:49], v[72:73]
	v_lshl_add_u64 v[64:65], v[64:65], 0, v[146:147]
	v_cvt_pk_bf16_f32 v48, v52, v53
	v_cvt_pk_bf16_f32 v49, v54, v55
	v_cvt_pk_bf16_f32 v50, v50, v51
	v_cvt_pk_bf16_f32 v51, v56, v57
	global_store_dwordx4 v[64:65], v[48:51], off sc1
	v_pk_mul_f32 v[52:53], v[44:45], s[8:9] op_sel_hi:[1,0]
	v_pk_mul_f32 v[54:55], v[42:43], s[8:9] op_sel_hi:[1,0]
	v_pk_mul_f32 v[50:51], v[46:47], s[8:9] op_sel_hi:[1,0]
	v_pk_mul_f32 v[56:57], v[40:41], s[8:9] op_sel_hi:[1,0]
	v_exp_f32_e32 v52, v52
	v_exp_f32_e32 v56, v56
	v_exp_f32_e32 v53, v53
	v_exp_f32_e32 v50, v50
	v_exp_f32_e32 v51, v51
	v_exp_f32_e32 v54, v54
	v_exp_f32_e32 v55, v55
	v_exp_f32_e32 v57, v57
	v_pk_add_f32 v[50:51], v[50:51], 1.0 op_sel_hi:[1,0]
	v_pk_add_f32 v[52:53], v[52:53], 1.0 op_sel_hi:[1,0]
	v_pk_add_f32 v[54:55], v[54:55], 1.0 op_sel_hi:[1,0]
	v_pk_add_f32 v[56:57], v[56:57], 1.0 op_sel_hi:[1,0]
	v_rcp_f32_e32 v52, v52
	v_rcp_f32_e32 v56, v56
	v_rcp_f32_e32 v53, v53
	v_rcp_f32_e32 v57, v57
	v_rcp_f32_e32 v50, v50
	v_rcp_f32_e32 v54, v54
	v_rcp_f32_e32 v51, v51
	v_rcp_f32_e32 v55, v55
	v_add_u32_e32 v48, 0x90, v166
	v_pk_mul_f32 v[38:39], v[38:39], v[46:47]
	v_pk_mul_f32 v[36:37], v[36:37], v[44:45]
	v_pk_mul_f32 v[34:35], v[34:35], v[42:43]
	v_pk_mul_f32 v[32:33], v[32:33], v[40:41]
	v_mad_i64_i32 v[48:49], s[30:31], v48, s83, v[144:145]
	v_pk_mul_f32 v[38:39], v[38:39], v[50:51]
	v_pk_mul_f32 v[36:37], v[36:37], v[52:53]
	v_pk_mul_f32 v[40:41], v[34:35], v[54:55]
	v_pk_mul_f32 v[34:35], v[32:33], v[56:57]
	v_lshl_add_u64 v[48:49], v[48:49], 0, v[146:147]
	v_cvt_pk_bf16_f32 v32, v36, v37
	v_cvt_pk_bf16_f32 v33, v38, v39
	v_cvt_pk_bf16_f32 v34, v34, v35
	v_cvt_pk_bf16_f32 v35, v40, v41
	global_store_dwordx4 v[48:49], v[32:35], off sc1
	v_pk_mul_f32 v[36:37], v[28:29], s[8:9] op_sel_hi:[1,0]
	v_pk_mul_f32 v[38:39], v[26:27], s[8:9] op_sel_hi:[1,0]
	v_pk_mul_f32 v[34:35], v[30:31], s[8:9] op_sel_hi:[1,0]
	v_pk_mul_f32 v[40:41], v[24:25], s[8:9] op_sel_hi:[1,0]
	v_exp_f32_e32 v36, v36
	v_exp_f32_e32 v40, v40
	v_exp_f32_e32 v37, v37
	v_exp_f32_e32 v34, v34
	v_exp_f32_e32 v35, v35
	v_exp_f32_e32 v38, v38
	v_exp_f32_e32 v39, v39
	v_exp_f32_e32 v41, v41
	v_pk_add_f32 v[34:35], v[34:35], 1.0 op_sel_hi:[1,0]
	v_pk_add_f32 v[36:37], v[36:37], 1.0 op_sel_hi:[1,0]
	v_pk_add_f32 v[38:39], v[38:39], 1.0 op_sel_hi:[1,0]
	v_pk_add_f32 v[40:41], v[40:41], 1.0 op_sel_hi:[1,0]
	v_rcp_f32_e32 v36, v36
	v_rcp_f32_e32 v40, v40
	v_rcp_f32_e32 v37, v37
	v_rcp_f32_e32 v41, v41
	v_rcp_f32_e32 v34, v34
	v_rcp_f32_e32 v38, v38
	v_rcp_f32_e32 v35, v35
	v_rcp_f32_e32 v39, v39
	v_add_u32_e32 v32, 0xa0, v166
	v_pk_mul_f32 v[22:23], v[22:23], v[30:31]
	v_pk_mul_f32 v[20:21], v[20:21], v[28:29]
	v_pk_mul_f32 v[18:19], v[18:19], v[26:27]
	v_pk_mul_f32 v[16:17], v[16:17], v[24:25]
	v_mad_i64_i32 v[32:33], s[30:31], v32, s83, v[144:145]
	v_pk_mul_f32 v[22:23], v[22:23], v[34:35]
	v_pk_mul_f32 v[20:21], v[20:21], v[36:37]
	v_pk_mul_f32 v[24:25], v[18:19], v[38:39]
	v_pk_mul_f32 v[18:19], v[16:17], v[40:41]
	v_lshl_add_u64 v[32:33], v[32:33], 0, v[146:147]
	v_cvt_pk_bf16_f32 v16, v20, v21
	v_cvt_pk_bf16_f32 v17, v22, v23
	v_cvt_pk_bf16_f32 v18, v18, v19
	v_cvt_pk_bf16_f32 v19, v24, v25
	global_store_dwordx4 v[32:33], v[16:19], off sc1
	v_pk_mul_f32 v[20:21], v[12:13], s[8:9] op_sel_hi:[1,0]
	v_pk_mul_f32 v[22:23], v[10:11], s[8:9] op_sel_hi:[1,0]
	v_pk_mul_f32 v[18:19], v[14:15], s[8:9] op_sel_hi:[1,0]
	v_pk_mul_f32 v[24:25], v[8:9], s[8:9] op_sel_hi:[1,0]
	v_exp_f32_e32 v20, v20
	v_exp_f32_e32 v24, v24
	v_exp_f32_e32 v21, v21
	v_exp_f32_e32 v18, v18
	v_exp_f32_e32 v19, v19
	v_exp_f32_e32 v22, v22
	v_exp_f32_e32 v23, v23
	v_exp_f32_e32 v25, v25
	v_pk_add_f32 v[18:19], v[18:19], 1.0 op_sel_hi:[1,0]
	v_pk_add_f32 v[20:21], v[20:21], 1.0 op_sel_hi:[1,0]
	v_pk_add_f32 v[22:23], v[22:23], 1.0 op_sel_hi:[1,0]
	v_pk_add_f32 v[24:25], v[24:25], 1.0 op_sel_hi:[1,0]
	v_rcp_f32_e32 v20, v20
	v_rcp_f32_e32 v24, v24
	v_rcp_f32_e32 v21, v21
	v_rcp_f32_e32 v25, v25
	v_rcp_f32_e32 v18, v18
	v_rcp_f32_e32 v22, v22
	v_rcp_f32_e32 v19, v19
	v_rcp_f32_e32 v23, v23
	v_add_u32_e32 v16, 0xb0, v166
	v_pk_mul_f32 v[6:7], v[6:7], v[14:15]
	v_pk_mul_f32 v[4:5], v[4:5], v[12:13]
	v_pk_mul_f32 v[2:3], v[2:3], v[10:11]
	v_pk_mul_f32 v[0:1], v[0:1], v[8:9]
	v_mad_i64_i32 v[16:17], s[30:31], v16, s83, v[144:145]
	v_pk_mul_f32 v[6:7], v[6:7], v[18:19]
	v_pk_mul_f32 v[4:5], v[4:5], v[20:21]
	v_pk_mul_f32 v[8:9], v[2:3], v[22:23]
	v_pk_mul_f32 v[2:3], v[0:1], v[24:25]
	v_lshl_add_u64 v[16:17], v[16:17], 0, v[146:147]
	v_cvt_pk_bf16_f32 v0, v4, v5
	v_cvt_pk_bf16_f32 v1, v6, v7
	v_cvt_pk_bf16_f32 v2, v2, v3
	v_cvt_pk_bf16_f32 v3, v8, v9
	s_andn2_b64 vcc, exec, s[0:1]
	s_mov_b64 s[0:1], -1
	global_store_dwordx4 v[16:17], v[0:3], off sc1
	s_cbranch_vccnz .LBB0_174
	s_andn2_b64 vcc, exec, s[2:3]
	s_cbranch_vccnz .LBB0_173
	s_barrier
	s_branch .LBB0_173

.LBB0_236:
	s_waitcnt vmcnt(22)
	v_cvt_pk_bf16_f32 v96, v96, v104
	v_cvt_pk_bf16_f32 v97, v97, v105
	ds_write2_b32 v143, v96, v97 offset1:32
	v_cvt_pk_bf16_f32 v96, v98, v106
	v_cvt_pk_bf16_f32 v97, v99, v107
	ds_write2_b32 v143, v96, v97 offset0:64 offset1:96
	s_waitcnt vmcnt(20)
	v_cvt_pk_bf16_f32 v96, v116, v124
	v_cvt_pk_bf16_f32 v97, v117, v125
	ds_write2_b32 v144, v96, v97 offset1:32
	v_cvt_pk_bf16_f32 v96, v118, v126
	v_cvt_pk_bf16_f32 v97, v119, v127
	ds_write2_b32 v144, v96, v97 offset0:64 offset1:96
	s_waitcnt vmcnt(18)
	v_cvt_pk_bf16_f32 v96, v108, v120
	v_cvt_pk_bf16_f32 v97, v109, v121
	ds_write2_b32 v145, v96, v97 offset1:32
	v_cvt_pk_bf16_f32 v96, v110, v122
	v_cvt_pk_bf16_f32 v97, v111, v123
	ds_write2_b32 v145, v96, v97 offset0:64 offset1:96
	s_waitcnt vmcnt(16)
	v_cvt_pk_bf16_f32 v96, v100, v112
	v_cvt_pk_bf16_f32 v97, v101, v113
	ds_write2_b32 v146, v96, v97 offset1:32
	v_cvt_pk_bf16_f32 v96, v102, v114
	v_cvt_pk_bf16_f32 v97, v103, v115
	s_waitcnt vmcnt(14)
	v_cvt_pk_bf16_f32 v84, v84, v92
	v_cvt_pk_bf16_f32 v85, v85, v93
	ds_write2_b32 v146, v96, v97 offset0:64 offset1:96
	ds_write2_b32 v147, v84, v85 offset1:32
	v_cvt_pk_bf16_f32 v84, v86, v94
	v_cvt_pk_bf16_f32 v85, v87, v95
	s_waitcnt vmcnt(12)
	v_cvt_pk_bf16_f32 v76, v76, v88
	v_cvt_pk_bf16_f32 v77, v77, v89
	s_add_u32 s30, s90, s74
	ds_write2_b32 v147, v84, v85 offset0:64 offset1:96
	ds_write2_b32 v148, v76, v77 offset1:32
	v_cvt_pk_bf16_f32 v76, v78, v90
	v_cvt_pk_bf16_f32 v77, v79, v91
	s_waitcnt vmcnt(10)
	v_cvt_pk_bf16_f32 v68, v68, v80
	v_cvt_pk_bf16_f32 v69, v69, v81
	s_addc_u32 s31, s91, s75
	ds_write2_b32 v148, v76, v77 offset0:64 offset1:96
	ds_write2_b32 v149, v68, v69 offset1:32
	v_cvt_pk_bf16_f32 v68, v70, v82
	v_cvt_pk_bf16_f32 v69, v71, v83
	s_waitcnt vmcnt(8)
	v_cvt_pk_bf16_f32 v64, v64, v72
	v_cvt_pk_bf16_f32 v65, v65, v73
	s_sub_i32 s34, s39, 32
	ds_write2_b32 v149, v68, v69 offset0:64 offset1:96
	ds_write2_b32 v150, v64, v65 offset1:32
	v_cvt_pk_bf16_f32 v64, v66, v74
	v_cvt_pk_bf16_f32 v65, v67, v75
	v_mov_b32_e32 v74, s34
	v_mov_b32_e32 v75, s38
	ds_write2_b32 v150, v64, v65 offset0:64 offset1:96
	v_cndmask_b32_e64 v68, v74, v75, s[2:3]
	s_waitcnt lgkmcnt(0)
	v_add_u32_e32 v68, v68, v131
	v_ashrrev_i32_e32 v69, 31, v68
	ds_read_b128 v[64:67], v151
	v_mul_lo_u32 v70, s72, v69
	v_mul_lo_u32 v71, s73, v68
	v_mad_u64_u32 v[68:69], s[38:39], s72, v68, 0
	v_add3_u32 v69, v69, v70, v71
	s_ashr_i32 s81, s80, 31
	v_lshl_add_u64 v[68:69], v[68:69], 1, s[30:31]
	s_lshl_b64 s[74:75], s[80:81], 1
	v_lshl_add_u64 v[68:69], v[68:69], 0, s[74:75]
	v_mov_b32_e32 v133, v129
	v_lshl_add_u64 v[72:73], v[68:69], 0, v[132:133]
	ds_read_b128 v[68:71], v152
	s_waitcnt lgkmcnt(1)
	global_store_dwordx4 v[72:73], v[64:67], off sc1
	s_nop 1
	v_cndmask_b32_e64 v64, v74, v75, s[4:5]
	v_add_u32_e32 v64, v64, v135
	v_ashrrev_i32_e32 v65, 31, v64
	v_mul_lo_u32 v66, s72, v65
	v_mul_lo_u32 v67, s73, v64
	v_mad_u64_u32 v[64:65], s[38:39], s72, v64, 0
	v_add3_u32 v65, v65, v66, v67
	v_lshl_add_u64 v[64:65], v[64:65], 1, s[30:31]
	v_lshl_add_u64 v[64:65], v[64:65], 0, s[74:75]
	v_lshl_add_u64 v[64:65], v[64:65], 0, v[132:133]
	s_waitcnt lgkmcnt(0)
	global_store_dwordx4 v[64:65], v[68:71], off sc1
	ds_read_b128 v[64:67], v153
	s_nop 0
	v_cndmask_b32_e64 v68, v74, v75, s[6:7]
	v_add_u32_e32 v68, v68, v136
	v_ashrrev_i32_e32 v69, 31, v68
	v_mul_lo_u32 v70, s72, v69
	v_mul_lo_u32 v71, s73, v68
	v_mad_u64_u32 v[68:69], s[38:39], s72, v68, 0
	v_add3_u32 v69, v69, v70, v71
	v_lshl_add_u64 v[68:69], v[68:69], 1, s[30:31]
	v_lshl_add_u64 v[68:69], v[68:69], 0, s[74:75]
	v_lshl_add_u64 v[72:73], v[68:69], 0, v[132:133]
	ds_read_b128 v[68:71], v154
	s_waitcnt lgkmcnt(1)
	global_store_dwordx4 v[72:73], v[64:67], off sc1
	s_nop 1
	v_cndmask_b32_e64 v64, v74, v75, s[8:9]
	v_add_u32_e32 v64, v64, v137
	v_ashrrev_i32_e32 v65, 31, v64
	v_mul_lo_u32 v66, s72, v65
	v_mul_lo_u32 v67, s73, v64
	v_mad_u64_u32 v[64:65], s[38:39], s72, v64, 0
	v_add3_u32 v65, v65, v66, v67
	v_lshl_add_u64 v[64:65], v[64:65], 1, s[30:31]
	v_lshl_add_u64 v[64:65], v[64:65], 0, s[74:75]
	v_lshl_add_u64 v[64:65], v[64:65], 0, v[132:133]
	s_waitcnt lgkmcnt(0)
	global_store_dwordx4 v[64:65], v[68:71], off sc1
	ds_read_b128 v[64:67], v155
	s_nop 0
	v_cndmask_b32_e64 v68, v74, v75, s[10:11]
	v_add_u32_e32 v68, v68, v138
	v_ashrrev_i32_e32 v69, 31, v68
	v_mul_lo_u32 v70, s72, v69
	v_mul_lo_u32 v71, s73, v68
	v_mad_u64_u32 v[68:69], s[38:39], s72, v68, 0
	v_add3_u32 v69, v69, v70, v71
	v_lshl_add_u64 v[68:69], v[68:69], 1, s[30:31]
	v_lshl_add_u64 v[68:69], v[68:69], 0, s[74:75]
	v_lshl_add_u64 v[72:73], v[68:69], 0, v[132:133]
	ds_read_b128 v[68:71], v156
	s_waitcnt lgkmcnt(1)
	global_store_dwordx4 v[72:73], v[64:67], off sc1
	s_nop 1
	v_cndmask_b32_e64 v64, v74, v75, s[12:13]
	v_add_u32_e32 v64, v64, v139
	v_ashrrev_i32_e32 v65, 31, v64
	v_mul_lo_u32 v66, s72, v65
	v_mul_lo_u32 v67, s73, v64
	v_mad_u64_u32 v[64:65], s[38:39], s72, v64, 0
	v_add3_u32 v65, v65, v66, v67
	v_lshl_add_u64 v[64:65], v[64:65], 1, s[30:31]
	v_lshl_add_u64 v[64:65], v[64:65], 0, s[74:75]
	v_lshl_add_u64 v[64:65], v[64:65], 0, v[132:133]
	s_waitcnt lgkmcnt(0)
	global_store_dwordx4 v[64:65], v[68:71], off sc1
	ds_read_b128 v[64:67], v157
	s_nop 0
	v_cndmask_b32_e64 v68, v74, v75, s[14:15]
	v_add_u32_e32 v68, v68, v140
	v_ashrrev_i32_e32 v69, 31, v68
	v_mul_lo_u32 v70, s72, v69
	v_mul_lo_u32 v71, s73, v68
	v_mad_u64_u32 v[68:69], s[38:39], s72, v68, 0
	v_add3_u32 v69, v69, v70, v71
	v_lshl_add_u64 v[68:69], v[68:69], 1, s[30:31]
	v_lshl_add_u64 v[68:69], v[68:69], 0, s[74:75]
	v_lshl_add_u64 v[72:73], v[68:69], 0, v[132:133]
	ds_read_b128 v[68:71], v158
	s_waitcnt lgkmcnt(1)
	global_store_dwordx4 v[72:73], v[64:67], off sc1
	s_nop 1
	v_cndmask_b32_e64 v64, v74, v75, s[16:17]
	v_add_u32_e32 v64, v64, v141
	v_ashrrev_i32_e32 v65, 31, v64
	v_mul_lo_u32 v66, s72, v65
	v_mul_lo_u32 v67, s73, v64
	v_mad_u64_u32 v[64:65], s[38:39], s72, v64, 0
	v_add3_u32 v65, v65, v66, v67
	v_lshl_add_u64 v[64:65], v[64:65], 1, s[30:31]
	v_lshl_add_u64 v[64:65], v[64:65], 0, s[74:75]
	v_lshl_add_u64 v[64:65], v[64:65], 0, v[132:133]
	s_waitcnt lgkmcnt(0)
	global_store_dwordx4 v[64:65], v[68:71], off sc1
	s_waitcnt lgkmcnt(0)
	s_add_i32 s53, s53, 16
	s_and_b64 vcc, exec, s[82:83]
	s_mov_b32 s40, s41
	s_cbranch_vccnz .LBB0_190

.LBB0_275:
	s_lshl_b32 s80, s41, 6
	v_add_u32_e32 v64, s80, v134
	v_ashrrev_i32_e32 v67, 31, v64
	v_mad_u64_u32 v[64:65], s[30:31], v64, s34, 0
	v_mov_b32_e32 v66, v65
	v_mad_u64_u32 v[66:67], s[30:31], v67, s34, v[66:67]
	v_mov_b32_e32 v65, v66
	v_lshl_add_u64 v[64:65], v[64:65], 2, s[82:83]
	s_ashr_i32 s93, s92, 31
	v_lshl_add_u64 v[64:65], s[92:93], 2, v[64:65]
	v_lshl_add_u64 v[64:65], v[64:65], 0, v[128:129]
	s_lshl_b64 s[30:31], s[34:35], 2
	v_lshl_add_u64 v[66:67], v[64:65], 0, s[30:31]
	s_mul_i32 s34, s34, 28
	global_load_dwordx4 v[96:99], v[64:65], off nt
	global_load_dwordx4 v[104:107], v[66:67], off nt
	v_lshl_add_u64 v[64:65], v[66:67], 0, s[34:35]
	v_lshl_add_u64 v[66:67], v[64:65], 0, s[30:31]
	global_load_dwordx4 v[116:119], v[64:65], off nt
	global_load_dwordx4 v[124:127], v[66:67], off nt
	v_lshl_add_u64 v[64:65], v[66:67], 0, s[34:35]
	v_lshl_add_u64 v[66:67], v[64:65], 0, s[30:31]
	global_load_dwordx4 v[108:111], v[64:65], off nt
	global_load_dwordx4 v[120:123], v[66:67], off nt
	v_lshl_add_u64 v[64:65], v[66:67], 0, s[34:35]
	v_lshl_add_u64 v[66:67], v[64:65], 0, s[30:31]
	global_load_dwordx4 v[100:103], v[64:65], off nt
	global_load_dwordx4 v[112:115], v[66:67], off nt
	v_lshl_add_u64 v[64:65], v[66:67], 0, s[34:35]
	global_load_dwordx4 v[84:87], v[64:65], off nt
	v_lshl_add_u64 v[64:65], v[64:65], 0, s[30:31]
	global_load_dwordx4 v[92:95], v[64:65], off nt
	v_lshl_add_u64 v[64:65], v[64:65], 0, s[34:35]
	global_load_dwordx4 v[76:79], v[64:65], off nt
	v_lshl_add_u64 v[64:65], v[64:65], 0, s[30:31]
	global_load_dwordx4 v[88:91], v[64:65], off nt
	v_lshl_add_u64 v[64:65], v[64:65], 0, s[34:35]
	global_load_dwordx4 v[68:71], v[64:65], off nt
	v_lshl_add_u64 v[64:65], v[64:65], 0, s[30:31]
	v_lshl_add_u64 v[72:73], v[64:65], 0, s[34:35]
	global_load_dwordx4 v[80:83], v[64:65], off nt
	s_nop 0
	global_load_dwordx4 v[64:67], v[72:73], off nt
	v_lshl_add_u64 v[72:73], v[72:73], 0, s[30:31]
	global_load_dwordx4 v[72:75], v[72:73], off nt
	s_waitcnt vmcnt(30)
	v_cvt_pk_bf16_f32 v132, v0, v4
	v_cvt_pk_bf16_f32 v133, v1, v5
	ds_write2_b32 v143, v132, v133 offset1:32
	v_cvt_pk_bf16_f32 v132, v2, v6
	v_cvt_pk_bf16_f32 v133, v3, v7
	ds_write2_b32 v143, v132, v133 offset0:64 offset1:96
	s_waitcnt vmcnt(28)
	v_cvt_pk_bf16_f32 v132, v8, v12
	v_cvt_pk_bf16_f32 v133, v9, v13
	ds_write2_b32 v144, v132, v133 offset1:32
	v_cvt_pk_bf16_f32 v132, v10, v14
	v_cvt_pk_bf16_f32 v133, v11, v15
	ds_write2_b32 v144, v132, v133 offset0:64 offset1:96
	s_waitcnt vmcnt(26)
	v_cvt_pk_bf16_f32 v132, v16, v20
	v_cvt_pk_bf16_f32 v133, v17, v21
	ds_write2_b32 v145, v132, v133 offset1:32
	v_cvt_pk_bf16_f32 v132, v18, v22
	v_cvt_pk_bf16_f32 v133, v19, v23
	ds_write2_b32 v145, v132, v133 offset0:64 offset1:96
	s_waitcnt vmcnt(24)
	v_cvt_pk_bf16_f32 v132, v24, v28
	v_cvt_pk_bf16_f32 v133, v25, v29
	ds_write2_b32 v146, v132, v133 offset1:32
	v_cvt_pk_bf16_f32 v132, v26, v30
	v_cvt_pk_bf16_f32 v133, v27, v31
	ds_write2_b32 v146, v132, v133 offset0:64 offset1:96
	s_waitcnt vmcnt(22)
	v_cvt_pk_bf16_f32 v132, v32, v36
	v_cvt_pk_bf16_f32 v133, v33, v37
	ds_write2_b32 v147, v132, v133 offset1:32
	v_cvt_pk_bf16_f32 v132, v34, v38
	v_cvt_pk_bf16_f32 v133, v35, v39
	ds_write2_b32 v147, v132, v133 offset0:64 offset1:96
	s_waitcnt vmcnt(20)
	v_cvt_pk_bf16_f32 v132, v40, v44
	v_cvt_pk_bf16_f32 v133, v41, v45
	ds_write2_b32 v148, v132, v133 offset1:32
	v_cvt_pk_bf16_f32 v132, v42, v46
	v_cvt_pk_bf16_f32 v133, v43, v47
	ds_write2_b32 v148, v132, v133 offset0:64 offset1:96
	s_waitcnt vmcnt(18)
	v_cvt_pk_bf16_f32 v132, v48, v52
	v_cvt_pk_bf16_f32 v133, v49, v53
	ds_write2_b32 v149, v132, v133 offset1:32
	v_cvt_pk_bf16_f32 v132, v50, v54
	v_cvt_pk_bf16_f32 v133, v51, v55
	ds_write2_b32 v149, v132, v133 offset0:64 offset1:96
	s_waitcnt vmcnt(16)
	v_cvt_pk_bf16_f32 v132, v56, v60
	v_cvt_pk_bf16_f32 v133, v57, v61
	s_sub_i32 s30, s37, 32
	ds_write2_b32 v150, v132, v133 offset1:32
	v_cvt_pk_bf16_f32 v132, v58, v62
	v_cvt_pk_bf16_f32 v133, v59, v63
	v_mov_b32_e32 v159, s30
	v_mov_b32_e32 v168, s36
	ds_write2_b32 v150, v132, v133 offset0:64 offset1:96
	v_cndmask_b32_e64 v132, v159, v168, s[2:3]
	v_add_u32_e32 v132, v132, v131
	s_waitcnt lgkmcnt(0)
	v_ashrrev_i32_e32 v165, 31, v132
	v_mad_u64_u32 v[132:133], s[30:31], v132, s29, 0
	v_mov_b32_e32 v164, v133
	ds_read_b128 v[160:163], v151
	v_mad_u64_u32 v[164:165], s[30:31], v165, s29, v[164:165]
	v_mov_b32_e32 v133, v164
	s_ashr_i32 s79, s78, 31
	v_lshl_add_u64 v[132:133], v[132:133], 1, s[76:77]
	s_lshl_b64 s[30:31], s[78:79], 1
	v_lshl_add_u64 v[164:165], v[132:133], 0, s[30:31]
	v_lshlrev_b32_e32 v132, 1, v130
	v_mov_b32_e32 v133, v129
	v_lshl_add_u64 v[164:165], v[164:165], 0, v[132:133]
	s_waitcnt lgkmcnt(0)
	global_store_dwordx4 v[164:165], v[160:163], off sc1
	v_cndmask_b32_e64 v164, v159, v168, s[4:5]
	v_add_u32_e32 v164, v164, v135
	v_ashrrev_i32_e32 v167, 31, v164
	v_mad_u64_u32 v[164:165], s[42:43], v164, s29, 0
	v_mov_b32_e32 v166, v165
	ds_read_b128 v[160:163], v152
	v_mad_u64_u32 v[166:167], s[42:43], v167, s29, v[166:167]
	v_mov_b32_e32 v165, v166
	v_lshl_add_u64 v[164:165], v[164:165], 1, s[76:77]
	v_lshl_add_u64 v[164:165], v[164:165], 0, s[30:31]
	v_lshl_add_u64 v[164:165], v[164:165], 0, v[132:133]
	s_waitcnt lgkmcnt(0)
	global_store_dwordx4 v[164:165], v[160:163], off sc1
	v_cndmask_b32_e64 v164, v159, v168, s[6:7]
	v_add_u32_e32 v164, v164, v136
	v_ashrrev_i32_e32 v167, 31, v164
	v_mad_u64_u32 v[164:165], s[42:43], v164, s29, 0
	v_mov_b32_e32 v166, v165
	ds_read_b128 v[160:163], v153
	v_mad_u64_u32 v[166:167], s[42:43], v167, s29, v[166:167]
	v_mov_b32_e32 v165, v166
	v_lshl_add_u64 v[164:165], v[164:165], 1, s[76:77]
	v_lshl_add_u64 v[164:165], v[164:165], 0, s[30:31]
	v_lshl_add_u64 v[164:165], v[164:165], 0, v[132:133]
	s_waitcnt lgkmcnt(0)
	global_store_dwordx4 v[164:165], v[160:163], off sc1
	v_cndmask_b32_e64 v164, v159, v168, s[8:9]
	v_add_u32_e32 v164, v164, v137
	v_ashrrev_i32_e32 v167, 31, v164
	v_mad_u64_u32 v[164:165], s[42:43], v164, s29, 0
	v_mov_b32_e32 v166, v165
	ds_read_b128 v[160:163], v154
	v_mad_u64_u32 v[166:167], s[42:43], v167, s29, v[166:167]
	v_mov_b32_e32 v165, v166
	v_lshl_add_u64 v[164:165], v[164:165], 1, s[76:77]
	v_lshl_add_u64 v[164:165], v[164:165], 0, s[30:31]
	v_lshl_add_u64 v[164:165], v[164:165], 0, v[132:133]
	s_waitcnt lgkmcnt(0)
	global_store_dwordx4 v[164:165], v[160:163], off sc1
	v_cndmask_b32_e64 v164, v159, v168, s[10:11]
	v_add_u32_e32 v164, v164, v138
	v_ashrrev_i32_e32 v167, 31, v164
	v_mad_u64_u32 v[164:165], s[42:43], v164, s29, 0
	v_mov_b32_e32 v166, v165
	ds_read_b128 v[160:163], v155
	v_mad_u64_u32 v[166:167], s[42:43], v167, s29, v[166:167]
	v_mov_b32_e32 v165, v166
	v_lshl_add_u64 v[164:165], v[164:165], 1, s[76:77]
	v_lshl_add_u64 v[164:165], v[164:165], 0, s[30:31]
	v_lshl_add_u64 v[164:165], v[164:165], 0, v[132:133]
	s_waitcnt lgkmcnt(0)
	global_store_dwordx4 v[164:165], v[160:163], off sc1
	v_cndmask_b32_e64 v164, v159, v168, s[12:13]
	v_add_u32_e32 v164, v164, v139
	v_ashrrev_i32_e32 v167, 31, v164
	v_mad_u64_u32 v[164:165], s[42:43], v164, s29, 0
	v_mov_b32_e32 v166, v165
	ds_read_b128 v[160:163], v156
	v_mad_u64_u32 v[166:167], s[42:43], v167, s29, v[166:167]
	v_mov_b32_e32 v165, v166
	v_lshl_add_u64 v[164:165], v[164:165], 1, s[76:77]
	v_lshl_add_u64 v[164:165], v[164:165], 0, s[30:31]
	v_lshl_add_u64 v[164:165], v[164:165], 0, v[132:133]
	s_waitcnt lgkmcnt(0)
	global_store_dwordx4 v[164:165], v[160:163], off sc1
	v_cndmask_b32_e64 v164, v159, v168, s[14:15]
	v_add_u32_e32 v164, v164, v140
	v_ashrrev_i32_e32 v167, 31, v164
	v_mad_u64_u32 v[164:165], s[42:43], v164, s29, 0
	v_mov_b32_e32 v166, v165
	ds_read_b128 v[160:163], v157
	v_mad_u64_u32 v[166:167], s[42:43], v167, s29, v[166:167]
	v_mov_b32_e32 v165, v166
	v_lshl_add_u64 v[164:165], v[164:165], 1, s[76:77]
	v_lshl_add_u64 v[164:165], v[164:165], 0, s[30:31]
	v_cndmask_b32_e64 v159, v159, v168, s[16:17]
	v_lshl_add_u64 v[164:165], v[164:165], 0, v[132:133]
	v_add_u32_e32 v159, v159, v141
	s_waitcnt lgkmcnt(0)
	global_store_dwordx4 v[164:165], v[160:163], off sc1
	v_mad_u64_u32 v[164:165], s[42:43], v159, s29, 0
	v_ashrrev_i32_e32 v167, 31, v159
	v_mov_b32_e32 v166, v165
	ds_read_b128 v[160:163], v158
	v_mad_u64_u32 v[166:167], s[42:43], v167, s29, v[166:167]
	v_mov_b32_e32 v165, v166
	v_lshl_add_u64 v[164:165], v[164:165], 1, s[76:77]
	v_lshl_add_u64 v[164:165], v[164:165], 0, s[30:31]
	v_lshl_add_u64 v[164:165], v[164:165], 0, v[132:133]
	s_waitcnt lgkmcnt(0)
	global_store_dwordx4 v[164:165], v[160:163], off sc1
	s_waitcnt lgkmcnt(0)
	s_add_i32 s41, s40, 2
	s_cmp_gt_u32 s40, 5
	s_cselect_b64 s[82:83], -1, 0
	s_and_b64 vcc, exec, s[82:83]
	s_cbranch_vccnz .LBB0_236
	s_lshl_b32 s29, s41, 3
	s_add_i32 s36, s29, s28
	s_cmpk_lt_i32 s53, 0x2b00
	s_movk_i32 s29, 0x2b00
	s_cbranch_scc1 .LBB0_284
	s_cmpk_gt_u32 s53, 0x413f
	s_cbranch_scc0 .LBB0_285
	s_cmpk_gt_u32 s53, 0x443f
	s_cbranch_scc0 .LBB0_286
	s_cmpk_gt_u32 s53, 0x463f
	s_cbranch_scc0 .LBB0_287
	v_readlane_b32 s56, v252, 54
	v_readlane_b32 s66, v253, 0
	v_readlane_b32 s67, v253, 1
	s_cmpk_gt_u32 s53, 0x563f
	s_mov_b64 s[78:79], -1
	s_mov_b64 s[86:87], s[66:67]
	s_mov_b64 s[30:31], -1
	v_readlane_b32 s57, v252, 55
	v_readlane_b32 s58, v252, 56
	v_readlane_b32 s59, v252, 57
	v_readlane_b32 s60, v252, 58
	v_readlane_b32 s61, v252, 59
	v_readlane_b32 s62, v252, 60
	v_readlane_b32 s63, v252, 61
	v_readlane_b32 s64, v252, 62
	v_readlane_b32 s65, v252, 63
	v_readlane_b32 s68, v253, 2
	v_readlane_b32 s69, v253, 3
	v_readlane_b32 s70, v253, 4
	v_readlane_b32 s71, v253, 5
	s_cbranch_scc0 .LBB0_282
	s_add_i32 s37, s53, 0xffffa9c0
	s_mov_b64 s[30:31], 0
	s_mov_b64 s[86:87], s[20:21]

.LBB0_404:
	v_lshl_or_b32 v162, s86, 8, v168
	v_ashrrev_i32_e32 v163, 31, v162
	v_lshl_add_u32 v142, s83, 8, v166
	s_cmp_lt_i32 s4, 0
	s_mov_b64 s[30:31], -1
	v_lshlrev_b64 v[144:145], 2, v[162:163]
	s_cbranch_scc0 .LBB0_410
	v_lshl_add_u64 v[154:155], s[8:9], 0, v[144:145]
	global_load_dwordx4 v[146:149], v[154:155], off offset:16
	global_load_dwordx4 v[150:153], v[154:155], off
	v_readlane_b32 s44, v252, 22
	v_or_b32_e32 v236, 16, v142
	v_or_b32_e32 v238, 32, v142
	v_or_b32_e32 v240, 48, v142
	v_readlane_b32 s45, v252, 23
	v_ashrrev_i32_e32 v143, 31, v142
	v_ashrrev_i32_e32 v237, 31, v236
	v_ashrrev_i32_e32 v239, 31, v238
	v_ashrrev_i32_e32 v241, 31, v240
	v_lshl_add_u64 v[164:165], s[44:45], 0, v[144:145]
	v_lshlrev_b64 v[188:189], 14, v[236:237]
	v_lshlrev_b64 v[204:205], 14, v[238:239]
	v_lshlrev_b64 v[220:221], 14, v[240:241]
	v_lshl_add_u64 v[200:201], v[164:165], 0, v[188:189]
	v_lshl_add_u64 v[216:217], v[164:165], 0, v[204:205]
	v_lshl_add_u64 v[232:233], v[164:165], 0, v[220:221]
	v_readlane_b32 s46, v252, 24
	v_readlane_b32 s47, v252, 25
	v_readlane_b32 s48, v252, 26
	v_readlane_b32 s49, v252, 27
	v_readlane_b32 s50, v252, 28
	v_readlane_b32 s51, v252, 29
	v_readlane_b32 s52, v252, 30
	v_readlane_b32 s53, v252, 31
	v_readlane_b32 s54, v252, 32
	v_readlane_b32 s55, v252, 33
	v_readlane_b32 s56, v252, 34
	v_readlane_b32 s57, v252, 35
	v_readlane_b32 s58, v252, 36
	v_readlane_b32 s59, v252, 37
	s_waitcnt vmcnt(0)
	v_pk_mul_f32 v[158:159], v[152:153], 0.5 op_sel_hi:[1,0]
	v_pk_mul_f32 v[160:161], v[150:151], 0.5 op_sel_hi:[1,0]
	v_pk_mul_f32 v[150:151], v[148:149], 0.5 op_sel_hi:[1,0]
	v_pk_mul_f32 v[152:153], v[146:147], 0.5 op_sel_hi:[1,0]
	global_load_dwordx4 v[172:175], v[154:155], off offset:528
	global_load_dwordx4 v[146:149], v[154:155], off offset:512
	s_waitcnt vmcnt(0)
	v_pk_mul_f32 v[154:155], v[148:149], 0.5 op_sel_hi:[1,0]
	v_pk_mul_f32 v[148:149], v[172:173], 0.5 op_sel_hi:[1,0]
	v_lshlrev_b64 v[172:173], 14, v[142:143]
	v_lshl_add_u64 v[184:185], v[164:165], 0, v[172:173]
	v_pk_mul_f32 v[156:157], v[146:147], 0.5 op_sel_hi:[1,0]
	v_pk_mul_f32 v[146:147], v[174:175], 0.5 op_sel_hi:[1,0]
	global_load_dwordx4 v[172:175], v[184:185], off offset:16
	global_load_dwordx4 v[176:179], v[184:185], off
	global_load_dwordx4 v[180:183], v[184:185], off offset:528
	s_nop 0
	global_load_dwordx4 v[184:187], v[184:185], off offset:512
	s_nop 0
	global_load_dwordx4 v[188:191], v[200:201], off offset:16
	global_load_dwordx4 v[192:195], v[200:201], off
	global_load_dwordx4 v[196:199], v[200:201], off offset:528
	s_nop 0
	global_load_dwordx4 v[200:203], v[200:201], off offset:512
	s_nop 0
	global_load_dwordx4 v[204:207], v[216:217], off offset:16
	global_load_dwordx4 v[208:211], v[216:217], off
	global_load_dwordx4 v[212:215], v[216:217], off offset:528
	s_nop 0
	global_load_dwordx4 v[216:219], v[216:217], off offset:512
	s_nop 0
	global_load_dwordx4 v[220:223], v[232:233], off offset:16
	global_load_dwordx4 v[224:227], v[232:233], off
	global_load_dwordx4 v[228:231], v[232:233], off offset:528
	s_nop 0
	global_load_dwordx4 v[232:235], v[232:233], off offset:512
	s_waitcnt vmcnt(0)
	v_pk_mul_f32 v[176:177], v[176:177], s[14:15] op_sel_hi:[1,0]
	v_lshlrev_b64 v[242:243], 13, v[142:143]
	v_pk_mul_f32 v[178:179], v[178:179], s[14:15] op_sel_hi:[1,0]
	v_pk_fma_f32 v[176:177], v[124:125], v[160:161], v[176:177]
	v_pk_mul_f32 v[174:175], v[174:175], s[14:15] op_sel_hi:[1,0]
	v_pk_mul_f32 v[172:173], v[172:173], s[14:15] op_sel_hi:[1,0]
	v_pk_fma_f32 v[178:179], v[126:127], v[158:159], v[178:179]
	v_pk_fma_f32 v[244:245], v[122:123], v[150:151], v[174:175]
	v_pk_fma_f32 v[174:175], v[120:121], v[152:153], v[172:173]
	v_cvt_pk_bf16_f32 v172, v176, v177
	v_lshl_add_u64 v[176:177], s[20:21], 0, v[242:243]
	v_lshlrev_b64 v[162:163], 1, v[162:163]
	v_cvt_pk_bf16_f32 v173, v178, v179
	v_cvt_pk_bf16_f32 v174, v174, v175
	v_cvt_pk_bf16_f32 v175, v244, v245
	v_lshl_add_u64 v[176:177], v[176:177], 0, v[162:163]
	global_store_dwordx4 v[176:177], v[172:175], off sc1
	v_pk_mul_f32 v[180:181], v[180:181], s[14:15] op_sel_hi:[1,0]
	s_nop 0
	v_pk_mul_f32 v[172:173], v[186:187], s[14:15] op_sel_hi:[1,0]
	v_pk_mul_f32 v[174:175], v[184:185], s[14:15] op_sel_hi:[1,0]
	v_pk_fma_f32 v[178:179], v[118:119], v[154:155], v[172:173]
	v_pk_fma_f32 v[172:173], v[116:117], v[156:157], v[174:175]
	v_pk_mul_f32 v[174:175], v[182:183], s[14:15] op_sel_hi:[1,0]
	v_cvt_pk_bf16_f32 v172, v172, v173
	v_pk_fma_f32 v[182:183], v[114:115], v[146:147], v[174:175]
	v_pk_fma_f32 v[174:175], v[112:113], v[148:149], v[180:181]
	v_cvt_pk_bf16_f32 v173, v178, v179
	v_cvt_pk_bf16_f32 v174, v174, v175
	v_cvt_pk_bf16_f32 v175, v182, v183
	global_store_dwordx4 v[176:177], v[172:175], off offset:256 sc1
	v_lshlrev_b64 v[176:177], 13, v[236:237]
	v_pk_mul_f32 v[180:181], v[188:189], s[14:15] op_sel_hi:[1,0]
	v_pk_mul_f32 v[172:173], v[194:195], s[14:15] op_sel_hi:[1,0]
	v_pk_mul_f32 v[174:175], v[192:193], s[14:15] op_sel_hi:[1,0]
	v_pk_fma_f32 v[178:179], v[110:111], v[158:159], v[172:173]
	v_pk_fma_f32 v[172:173], v[108:109], v[160:161], v[174:175]
	v_pk_mul_f32 v[174:175], v[190:191], s[14:15] op_sel_hi:[1,0]
	v_lshl_add_u64 v[176:177], s[20:21], 0, v[176:177]
	v_pk_fma_f32 v[182:183], v[106:107], v[150:151], v[174:175]
	v_pk_fma_f32 v[174:175], v[104:105], v[152:153], v[180:181]
	v_cvt_pk_bf16_f32 v172, v172, v173
	v_cvt_pk_bf16_f32 v173, v178, v179
	v_cvt_pk_bf16_f32 v174, v174, v175
	v_cvt_pk_bf16_f32 v175, v182, v183
	v_lshl_add_u64 v[176:177], v[176:177], 0, v[162:163]
	global_store_dwordx4 v[176:177], v[172:175], off sc1
	v_pk_mul_f32 v[180:181], v[196:197], s[14:15] op_sel_hi:[1,0]
	s_nop 0
	v_pk_mul_f32 v[172:173], v[202:203], s[14:15] op_sel_hi:[1,0]
	v_pk_mul_f32 v[174:175], v[200:201], s[14:15] op_sel_hi:[1,0]
	v_pk_fma_f32 v[178:179], v[102:103], v[154:155], v[172:173]
	v_pk_fma_f32 v[172:173], v[100:101], v[156:157], v[174:175]
	v_pk_mul_f32 v[174:175], v[198:199], s[14:15] op_sel_hi:[1,0]
	v_cvt_pk_bf16_f32 v172, v172, v173
	v_pk_fma_f32 v[182:183], v[98:99], v[146:147], v[174:175]
	v_pk_fma_f32 v[174:175], v[96:97], v[148:149], v[180:181]
	v_cvt_pk_bf16_f32 v173, v178, v179
	v_cvt_pk_bf16_f32 v174, v174, v175
	v_cvt_pk_bf16_f32 v175, v182, v183
	global_store_dwordx4 v[176:177], v[172:175], off offset:256 sc1
	v_lshlrev_b64 v[176:177], 13, v[238:239]
	v_pk_mul_f32 v[180:181], v[204:205], s[14:15] op_sel_hi:[1,0]
	v_pk_mul_f32 v[172:173], v[210:211], s[14:15] op_sel_hi:[1,0]
	v_pk_mul_f32 v[174:175], v[208:209], s[14:15] op_sel_hi:[1,0]
	v_pk_fma_f32 v[178:179], v[94:95], v[158:159], v[172:173]
	v_pk_fma_f32 v[172:173], v[92:93], v[160:161], v[174:175]
	v_pk_mul_f32 v[174:175], v[206:207], s[14:15] op_sel_hi:[1,0]
	v_lshl_add_u64 v[176:177], s[20:21], 0, v[176:177]
	v_pk_fma_f32 v[182:183], v[90:91], v[150:151], v[174:175]
	v_pk_fma_f32 v[174:175], v[88:89], v[152:153], v[180:181]
	v_cvt_pk_bf16_f32 v172, v172, v173
	v_cvt_pk_bf16_f32 v173, v178, v179
	v_cvt_pk_bf16_f32 v174, v174, v175
	v_cvt_pk_bf16_f32 v175, v182, v183
	v_lshl_add_u64 v[176:177], v[176:177], 0, v[162:163]
	global_store_dwordx4 v[176:177], v[172:175], off sc1
	v_pk_mul_f32 v[180:181], v[212:213], s[14:15] op_sel_hi:[1,0]
	s_nop 0
	v_pk_mul_f32 v[172:173], v[218:219], s[14:15] op_sel_hi:[1,0]
	v_pk_mul_f32 v[174:175], v[216:217], s[14:15] op_sel_hi:[1,0]
	v_pk_fma_f32 v[178:179], v[86:87], v[154:155], v[172:173]
	v_pk_fma_f32 v[172:173], v[84:85], v[156:157], v[174:175]
	v_pk_mul_f32 v[174:175], v[214:215], s[14:15] op_sel_hi:[1,0]
	v_cvt_pk_bf16_f32 v172, v172, v173
	v_pk_fma_f32 v[182:183], v[82:83], v[146:147], v[174:175]
	v_pk_fma_f32 v[174:175], v[80:81], v[148:149], v[180:181]
	v_cvt_pk_bf16_f32 v173, v178, v179
	v_cvt_pk_bf16_f32 v174, v174, v175
	v_cvt_pk_bf16_f32 v175, v182, v183
	global_store_dwordx4 v[176:177], v[172:175], off offset:256 sc1
	v_lshlrev_b64 v[176:177], 13, v[240:241]
	v_pk_mul_f32 v[180:181], v[220:221], s[14:15] op_sel_hi:[1,0]
	v_pk_mul_f32 v[172:173], v[226:227], s[14:15] op_sel_hi:[1,0]
	v_pk_mul_f32 v[174:175], v[224:225], s[14:15] op_sel_hi:[1,0]
	v_pk_fma_f32 v[178:179], v[78:79], v[158:159], v[172:173]
	v_pk_fma_f32 v[172:173], v[76:77], v[160:161], v[174:175]
	v_pk_mul_f32 v[174:175], v[222:223], s[14:15] op_sel_hi:[1,0]
	v_lshl_add_u64 v[176:177], s[20:21], 0, v[176:177]
	v_pk_fma_f32 v[182:183], v[74:75], v[150:151], v[174:175]
	v_pk_fma_f32 v[174:175], v[72:73], v[152:153], v[180:181]
	v_cvt_pk_bf16_f32 v172, v172, v173
	v_cvt_pk_bf16_f32 v173, v178, v179
	v_cvt_pk_bf16_f32 v174, v174, v175
	v_cvt_pk_bf16_f32 v175, v182, v183
	v_lshl_add_u64 v[176:177], v[176:177], 0, v[162:163]
	global_store_dwordx4 v[176:177], v[172:175], off sc1
	v_pk_mul_f32 v[180:181], v[228:229], s[14:15] op_sel_hi:[1,0]
	s_nop 0
	v_pk_mul_f32 v[172:173], v[234:235], s[14:15] op_sel_hi:[1,0]
	v_pk_mul_f32 v[174:175], v[232:233], s[14:15] op_sel_hi:[1,0]
	v_pk_fma_f32 v[178:179], v[70:71], v[154:155], v[172:173]
	v_pk_fma_f32 v[172:173], v[68:69], v[156:157], v[174:175]
	v_pk_mul_f32 v[174:175], v[230:231], s[14:15] op_sel_hi:[1,0]
	v_cvt_pk_bf16_f32 v172, v172, v173
	v_pk_fma_f32 v[182:183], v[66:67], v[146:147], v[174:175]
	v_pk_fma_f32 v[174:175], v[64:65], v[148:149], v[180:181]
	v_cvt_pk_bf16_f32 v173, v178, v179
	v_cvt_pk_bf16_f32 v174, v174, v175
	v_cvt_pk_bf16_f32 v175, v182, v183
	global_store_dwordx4 v[176:177], v[172:175], off offset:256 sc1
	v_add_u32_e32 v236, 0x80, v142
	v_add_u32_e32 v238, 0x90, v142
	v_add_u32_e32 v240, 0xa0, v142
	v_add_u32_e32 v242, 0xb0, v142
	v_ashrrev_i32_e32 v237, 31, v236
	v_ashrrev_i32_e32 v239, 31, v238
	v_ashrrev_i32_e32 v241, 31, v240
	v_ashrrev_i32_e32 v243, 31, v242
	v_lshlrev_b64 v[172:173], 14, v[236:237]
	v_lshlrev_b64 v[188:189], 14, v[238:239]
	v_lshlrev_b64 v[204:205], 14, v[240:241]
	v_lshlrev_b64 v[220:221], 14, v[242:243]
	v_lshl_add_u64 v[184:185], v[164:165], 0, v[172:173]
	v_lshl_add_u64 v[200:201], v[164:165], 0, v[188:189]
	v_lshl_add_u64 v[216:217], v[164:165], 0, v[204:205]
	v_lshl_add_u64 v[164:165], v[164:165], 0, v[220:221]
	global_load_dwordx4 v[172:175], v[184:185], off offset:16
	global_load_dwordx4 v[176:179], v[184:185], off
	global_load_dwordx4 v[180:183], v[184:185], off offset:528
	s_nop 0
	global_load_dwordx4 v[184:187], v[184:185], off offset:512
	s_nop 0
	global_load_dwordx4 v[188:191], v[200:201], off offset:16
	global_load_dwordx4 v[192:195], v[200:201], off
	global_load_dwordx4 v[196:199], v[200:201], off offset:528
	s_nop 0
	global_load_dwordx4 v[200:203], v[200:201], off offset:512
	s_nop 0
	global_load_dwordx4 v[204:207], v[216:217], off offset:16
	global_load_dwordx4 v[208:211], v[216:217], off
	global_load_dwordx4 v[212:215], v[216:217], off offset:528
	s_nop 0
	global_load_dwordx4 v[216:219], v[216:217], off offset:512
	s_nop 0
	global_load_dwordx4 v[220:223], v[164:165], off offset:16
	global_load_dwordx4 v[224:227], v[164:165], off
	global_load_dwordx4 v[228:231], v[164:165], off offset:528
	global_load_dwordx4 v[232:235], v[164:165], off offset:512
	v_lshlrev_b64 v[164:165], 13, v[236:237]
	s_waitcnt vmcnt(0)
	v_pk_mul_f32 v[178:179], v[178:179], s[14:15] op_sel_hi:[1,0]
	v_pk_mul_f32 v[176:177], v[176:177], s[14:15] op_sel_hi:[1,0]
	v_pk_mul_f32 v[174:175], v[174:175], s[14:15] op_sel_hi:[1,0]
	v_pk_mul_f32 v[172:173], v[172:173], s[14:15] op_sel_hi:[1,0]
	v_pk_fma_f32 v[178:179], v[62:63], v[158:159], v[178:179]
	v_pk_fma_f32 v[176:177], v[60:61], v[160:161], v[176:177]
	v_pk_fma_f32 v[236:237], v[58:59], v[150:151], v[174:175]
	v_pk_fma_f32 v[174:175], v[56:57], v[152:153], v[172:173]
	v_lshl_add_u64 v[164:165], s[20:21], 0, v[164:165]
	v_cvt_pk_bf16_f32 v172, v176, v177
	v_cvt_pk_bf16_f32 v173, v178, v179
	v_cvt_pk_bf16_f32 v174, v174, v175
	v_cvt_pk_bf16_f32 v175, v236, v237
	v_lshl_add_u64 v[164:165], v[164:165], 0, v[162:163]
	global_store_dwordx4 v[164:165], v[172:175], off sc1
	v_pk_mul_f32 v[178:179], v[180:181], s[14:15] op_sel_hi:[1,0]
	s_nop 0
	v_pk_mul_f32 v[172:173], v[186:187], s[14:15] op_sel_hi:[1,0]
	v_pk_mul_f32 v[174:175], v[184:185], s[14:15] op_sel_hi:[1,0]
	v_pk_fma_f32 v[176:177], v[54:55], v[154:155], v[172:173]
	v_pk_fma_f32 v[172:173], v[52:53], v[156:157], v[174:175]
	v_pk_mul_f32 v[174:175], v[182:183], s[14:15] op_sel_hi:[1,0]
	v_cvt_pk_bf16_f32 v172, v172, v173
	v_pk_fma_f32 v[180:181], v[50:51], v[146:147], v[174:175]
	v_pk_fma_f32 v[174:175], v[48:49], v[148:149], v[178:179]
	v_cvt_pk_bf16_f32 v173, v176, v177
	v_cvt_pk_bf16_f32 v174, v174, v175
	v_cvt_pk_bf16_f32 v175, v180, v181
	global_store_dwordx4 v[164:165], v[172:175], off offset:256 sc1
	v_lshlrev_b64 v[164:165], 13, v[238:239]
	v_pk_mul_f32 v[178:179], v[188:189], s[14:15] op_sel_hi:[1,0]
	v_pk_mul_f32 v[172:173], v[194:195], s[14:15] op_sel_hi:[1,0]
	v_pk_mul_f32 v[174:175], v[192:193], s[14:15] op_sel_hi:[1,0]
	v_pk_fma_f32 v[176:177], v[46:47], v[158:159], v[172:173]
	v_pk_fma_f32 v[172:173], v[44:45], v[160:161], v[174:175]
	v_pk_mul_f32 v[174:175], v[190:191], s[14:15] op_sel_hi:[1,0]
	v_lshl_add_u64 v[164:165], s[20:21], 0, v[164:165]
	v_pk_fma_f32 v[180:181], v[42:43], v[150:151], v[174:175]
	v_pk_fma_f32 v[174:175], v[40:41], v[152:153], v[178:179]
	v_cvt_pk_bf16_f32 v172, v172, v173
	v_cvt_pk_bf16_f32 v173, v176, v177
	v_cvt_pk_bf16_f32 v174, v174, v175
	v_cvt_pk_bf16_f32 v175, v180, v181
	v_lshl_add_u64 v[164:165], v[164:165], 0, v[162:163]
	global_store_dwordx4 v[164:165], v[172:175], off sc1
	v_pk_mul_f32 v[178:179], v[196:197], s[14:15] op_sel_hi:[1,0]
	s_nop 0
	v_pk_mul_f32 v[172:173], v[202:203], s[14:15] op_sel_hi:[1,0]
	v_pk_mul_f32 v[174:175], v[200:201], s[14:15] op_sel_hi:[1,0]
	v_pk_fma_f32 v[176:177], v[38:39], v[154:155], v[172:173]
	v_pk_fma_f32 v[172:173], v[36:37], v[156:157], v[174:175]
	v_pk_mul_f32 v[174:175], v[198:199], s[14:15] op_sel_hi:[1,0]
	v_cvt_pk_bf16_f32 v172, v172, v173
	v_pk_fma_f32 v[180:181], v[34:35], v[146:147], v[174:175]
	v_pk_fma_f32 v[174:175], v[32:33], v[148:149], v[178:179]
	v_cvt_pk_bf16_f32 v173, v176, v177
	v_cvt_pk_bf16_f32 v174, v174, v175
	v_cvt_pk_bf16_f32 v175, v180, v181
	global_store_dwordx4 v[164:165], v[172:175], off offset:256 sc1
	v_lshlrev_b64 v[164:165], 13, v[240:241]
	v_pk_mul_f32 v[178:179], v[204:205], s[14:15] op_sel_hi:[1,0]
	v_pk_mul_f32 v[172:173], v[210:211], s[14:15] op_sel_hi:[1,0]
	v_pk_mul_f32 v[174:175], v[208:209], s[14:15] op_sel_hi:[1,0]
	v_pk_fma_f32 v[176:177], v[30:31], v[158:159], v[172:173]
	v_pk_fma_f32 v[172:173], v[28:29], v[160:161], v[174:175]
	v_pk_mul_f32 v[174:175], v[206:207], s[14:15] op_sel_hi:[1,0]
	v_lshl_add_u64 v[164:165], s[20:21], 0, v[164:165]
	v_pk_fma_f32 v[180:181], v[26:27], v[150:151], v[174:175]
	v_pk_fma_f32 v[174:175], v[24:25], v[152:153], v[178:179]
	v_cvt_pk_bf16_f32 v172, v172, v173
	v_cvt_pk_bf16_f32 v173, v176, v177
	v_cvt_pk_bf16_f32 v174, v174, v175
	v_cvt_pk_bf16_f32 v175, v180, v181
	v_lshl_add_u64 v[164:165], v[164:165], 0, v[162:163]
	global_store_dwordx4 v[164:165], v[172:175], off sc1
	v_pk_mul_f32 v[178:179], v[212:213], s[14:15] op_sel_hi:[1,0]
	s_nop 0
	v_pk_mul_f32 v[172:173], v[218:219], s[14:15] op_sel_hi:[1,0]
	v_pk_mul_f32 v[174:175], v[216:217], s[14:15] op_sel_hi:[1,0]
	v_pk_fma_f32 v[176:177], v[22:23], v[154:155], v[172:173]
	v_pk_fma_f32 v[172:173], v[20:21], v[156:157], v[174:175]
	v_pk_mul_f32 v[174:175], v[214:215], s[14:15] op_sel_hi:[1,0]
	v_cvt_pk_bf16_f32 v172, v172, v173
	v_pk_fma_f32 v[180:181], v[18:19], v[146:147], v[174:175]
	v_pk_fma_f32 v[174:175], v[16:17], v[148:149], v[178:179]
	v_cvt_pk_bf16_f32 v173, v176, v177
	v_cvt_pk_bf16_f32 v174, v174, v175
	v_cvt_pk_bf16_f32 v175, v180, v181
	global_store_dwordx4 v[164:165], v[172:175], off offset:256 sc1
	v_lshlrev_b64 v[164:165], 13, v[242:243]
	s_nop 0
	v_pk_mul_f32 v[172:173], v[226:227], s[14:15] op_sel_hi:[1,0]
	v_pk_mul_f32 v[174:175], v[224:225], s[14:15] op_sel_hi:[1,0]
	v_pk_fma_f32 v[158:159], v[14:15], v[158:159], v[172:173]
	v_pk_fma_f32 v[160:161], v[12:13], v[160:161], v[174:175]
	v_pk_mul_f32 v[172:173], v[222:223], s[14:15] op_sel_hi:[1,0]
	v_pk_mul_f32 v[174:175], v[220:221], s[14:15] op_sel_hi:[1,0]
	v_pk_fma_f32 v[172:173], v[10:11], v[150:151], v[172:173]
	v_pk_fma_f32 v[152:153], v[8:9], v[152:153], v[174:175]
	v_cvt_pk_bf16_f32 v151, v158, v159
	v_lshl_add_u64 v[158:159], s[20:21], 0, v[164:165]
	v_cvt_pk_bf16_f32 v150, v160, v161
	v_cvt_pk_bf16_f32 v152, v152, v153
	v_cvt_pk_bf16_f32 v153, v172, v173
	v_lshl_add_u64 v[158:159], v[158:159], 0, v[162:163]
	global_store_dwordx4 v[158:159], v[150:153], off sc1
	s_nop 1
	v_pk_mul_f32 v[150:151], v[234:235], s[14:15] op_sel_hi:[1,0]
	v_pk_mul_f32 v[152:153], v[232:233], s[14:15] op_sel_hi:[1,0]
	v_pk_fma_f32 v[150:151], v[6:7], v[154:155], v[150:151]
	v_pk_fma_f32 v[152:153], v[4:5], v[156:157], v[152:153]
	v_pk_mul_f32 v[154:155], v[230:231], s[14:15] op_sel_hi:[1,0]
	v_pk_mul_f32 v[156:157], v[228:229], s[14:15] op_sel_hi:[1,0]
	v_pk_fma_f32 v[154:155], v[2:3], v[146:147], v[154:155]
	v_pk_fma_f32 v[148:149], v[0:1], v[148:149], v[156:157]
	v_cvt_pk_bf16_f32 v146, v152, v153
	v_cvt_pk_bf16_f32 v147, v150, v151
	v_cvt_pk_bf16_f32 v148, v148, v149
	v_cvt_pk_bf16_f32 v149, v154, v155
	global_store_dwordx4 v[158:159], v[146:149], off offset:256 sc1
	s_cbranch_execz .LBB0_411

.LBB0_411:
	s_nop 0
	v_add_u32_e32 v146, 0xffffe000, v142
	s_lshl_b64 s[30:31], s[4:5], 23
	v_readlane_b32 s4, v253, 14
	v_ashrrev_i32_e32 v147, 31, v146
	s_add_u32 s30, s4, s30
	v_readlane_b32 s4, v253, 15
	s_addc_u32 s31, s4, s31
	v_lshlrev_b64 v[146:147], 14, v[146:147]
	v_lshl_add_u64 v[146:147], s[30:31], 0, v[146:147]
	v_lshl_add_u64 v[146:147], v[146:147], 0, v[144:145]
	global_store_dwordx4 v[146:147], v[124:127], off sc1
	global_store_dwordx4 v[146:147], v[120:123], off offset:16 sc1
	global_store_dwordx4 v[146:147], v[116:119], off offset:512 sc1
	global_store_dwordx4 v[146:147], v[112:115], off offset:528 sc1
	s_nop 1
	v_add_u32_e32 v112, 0xffffe010, v142
	v_ashrrev_i32_e32 v113, 31, v112
	v_lshlrev_b64 v[112:113], 14, v[112:113]
	v_lshl_add_u64 v[112:113], s[30:31], 0, v[112:113]
	v_lshl_add_u64 v[112:113], v[112:113], 0, v[144:145]
	global_store_dwordx4 v[112:113], v[108:111], off sc1
	global_store_dwordx4 v[112:113], v[104:107], off offset:16 sc1
	global_store_dwordx4 v[112:113], v[100:103], off offset:512 sc1
	global_store_dwordx4 v[112:113], v[96:99], off offset:528 sc1
	s_nop 1
	v_add_u32_e32 v96, 0xffffe020, v142
	v_ashrrev_i32_e32 v97, 31, v96
	v_lshlrev_b64 v[96:97], 14, v[96:97]
	v_lshl_add_u64 v[96:97], s[30:31], 0, v[96:97]
	v_lshl_add_u64 v[96:97], v[96:97], 0, v[144:145]
	global_store_dwordx4 v[96:97], v[92:95], off sc1
	global_store_dwordx4 v[96:97], v[88:91], off offset:16 sc1
	global_store_dwordx4 v[96:97], v[84:87], off offset:512 sc1
	global_store_dwordx4 v[96:97], v[80:83], off offset:528 sc1
	s_nop 1
	v_add_u32_e32 v80, 0xffffe030, v142
	v_ashrrev_i32_e32 v81, 31, v80
	v_lshlrev_b64 v[80:81], 14, v[80:81]
	v_lshl_add_u64 v[80:81], s[30:31], 0, v[80:81]
	v_lshl_add_u64 v[80:81], v[80:81], 0, v[144:145]
	global_store_dwordx4 v[80:81], v[76:79], off sc1
	global_store_dwordx4 v[80:81], v[72:75], off offset:16 sc1
	global_store_dwordx4 v[80:81], v[68:71], off offset:512 sc1
	global_store_dwordx4 v[80:81], v[64:67], off offset:528 sc1
	s_nop 1
	v_add_u32_e32 v64, 0xffffe080, v142
	v_ashrrev_i32_e32 v65, 31, v64
	v_lshlrev_b64 v[64:65], 14, v[64:65]
	v_lshl_add_u64 v[64:65], s[30:31], 0, v[64:65]
	v_lshl_add_u64 v[64:65], v[64:65], 0, v[144:145]
	global_store_dwordx4 v[64:65], v[60:63], off sc1
	global_store_dwordx4 v[64:65], v[56:59], off offset:16 sc1
	global_store_dwordx4 v[64:65], v[52:55], off offset:512 sc1
	global_store_dwordx4 v[64:65], v[48:51], off offset:528 sc1
	s_nop 1
	v_add_u32_e32 v48, 0xffffe090, v142
	v_ashrrev_i32_e32 v49, 31, v48
	v_lshlrev_b64 v[48:49], 14, v[48:49]
	v_lshl_add_u64 v[48:49], s[30:31], 0, v[48:49]
	v_lshl_add_u64 v[48:49], v[48:49], 0, v[144:145]
	global_store_dwordx4 v[48:49], v[44:47], off sc1
	global_store_dwordx4 v[48:49], v[40:43], off offset:16 sc1
	global_store_dwordx4 v[48:49], v[36:39], off offset:512 sc1
	global_store_dwordx4 v[48:49], v[32:35], off offset:528 sc1
	s_nop 1
	v_add_u32_e32 v32, 0xffffe0a0, v142
	v_ashrrev_i32_e32 v33, 31, v32
	v_lshlrev_b64 v[32:33], 14, v[32:33]
	v_lshl_add_u64 v[32:33], s[30:31], 0, v[32:33]
	v_lshl_add_u64 v[32:33], v[32:33], 0, v[144:145]
	global_store_dwordx4 v[32:33], v[28:31], off sc1
	global_store_dwordx4 v[32:33], v[24:27], off offset:16 sc1
	global_store_dwordx4 v[32:33], v[20:23], off offset:512 sc1
	global_store_dwordx4 v[32:33], v[16:19], off offset:528 sc1
	s_nop 1
	v_add_u32_e32 v16, 0xffffe0b0, v142
	v_ashrrev_i32_e32 v17, 31, v16
	v_lshlrev_b64 v[16:17], 14, v[16:17]
	v_lshl_add_u64 v[16:17], s[30:31], 0, v[16:17]
	v_lshl_add_u64 v[16:17], v[16:17], 0, v[144:145]
	global_store_dwordx4 v[16:17], v[12:15], off sc1
	global_store_dwordx4 v[16:17], v[8:11], off offset:16 sc1
	global_store_dwordx4 v[16:17], v[4:7], off offset:512 sc1
	global_store_dwordx4 v[16:17], v[0:3], off offset:528 sc1
	s_and_b64 vcc, exec, s[2:3]
	s_mov_b64 s[2:3], -1
	s_cbranch_vccnz .LBB0_385

.LBB0_582:
	s_cmp_lt_i32 s8, 8
	s_cselect_b64 vcc, -1, 0
	v_lshl_or_b32 v145, s8, 8, v148
	s_and_b64 s[6:7], vcc, exec
	v_add_u32_e32 v153, 0xfffff800, v145
	s_movk_i32 s6, 0x800
	v_cndmask_b32_e32 v154, v153, v145, vcc
	s_cselect_b32 s8, s6, 0xe00
	s_cselect_b32 s6, s97, s69
	s_cselect_b32 s7, s96, s68
	v_mov_b32_e32 v156, s7
	v_mov_b32_e32 v157, s6
	v_ashrrev_i32_e32 v155, 31, v154
	v_lshl_add_u64 v[158:159], v[154:155], 1, v[156:157]
	v_mad_i64_i32 v[154:155], s[6:7], s8, v144, 0
	v_cvt_pk_bf16_f32 v124, v124, v125
	v_cvt_pk_bf16_f32 v125, v126, v127
	v_cvt_pk_bf16_f32 v126, v120, v121
	v_or_b32_e32 v120, 16, v144
	v_lshl_add_u64 v[160:161], v[154:155], 1, v[158:159]
	v_cvt_pk_bf16_f32 v127, v122, v123
	v_mad_i64_i32 v[120:121], s[6:7], s8, v120, 0
	v_cvt_pk_bf16_f32 v116, v116, v117
	v_cvt_pk_bf16_f32 v117, v118, v119
	v_cvt_pk_bf16_f32 v118, v112, v113
	v_or_b32_e32 v112, 32, v144
	v_cvt_pk_bf16_f32 v154, v60, v61
	v_cvt_pk_bf16_f32 v155, v62, v63
	v_cvt_pk_bf16_f32 v156, v56, v57
	v_cvt_pk_bf16_f32 v157, v58, v59
	global_store_dwordx4 v[160:161], v[124:127], off offset:256 sc1
	v_cvt_pk_bf16_f32 v119, v114, v115
	v_mad_i64_i32 v[112:113], s[6:7], s8, v112, 0
	v_lshl_add_u64 v[124:125], v[120:121], 1, v[158:159]
	v_cvt_pk_bf16_f32 v108, v108, v109
	v_cvt_pk_bf16_f32 v109, v110, v111
	v_cvt_pk_bf16_f32 v110, v104, v105
	v_or_b32_e32 v104, 48, v144
	global_store_dwordx4 v[160:161], v[154:157], off sc1
	v_cvt_pk_bf16_f32 v120, v52, v53
	v_cvt_pk_bf16_f32 v121, v54, v55
	v_cvt_pk_bf16_f32 v122, v48, v49
	v_cvt_pk_bf16_f32 v123, v50, v51
	global_store_dwordx4 v[124:125], v[116:119], off offset:256 sc1
	v_cvt_pk_bf16_f32 v111, v106, v107
	v_mad_i64_i32 v[104:105], s[6:7], s8, v104, 0
	v_lshl_add_u64 v[116:117], v[112:113], 1, v[158:159]
	v_cvt_pk_bf16_f32 v100, v100, v101
	v_cvt_pk_bf16_f32 v101, v102, v103
	v_cvt_pk_bf16_f32 v102, v96, v97
	v_add_u32_e32 v96, 0x80, v144
	global_store_dwordx4 v[124:125], v[120:123], off sc1
	v_cvt_pk_bf16_f32 v112, v44, v45
	v_cvt_pk_bf16_f32 v113, v46, v47
	v_cvt_pk_bf16_f32 v114, v40, v41
	v_cvt_pk_bf16_f32 v115, v42, v43
	global_store_dwordx4 v[116:117], v[108:111], off offset:256 sc1
	v_cvt_pk_bf16_f32 v103, v98, v99
	v_mad_i64_i32 v[96:97], s[6:7], s8, v96, 0
	v_lshl_add_u64 v[108:109], v[104:105], 1, v[158:159]
	v_cvt_pk_bf16_f32 v92, v92, v93
	v_cvt_pk_bf16_f32 v93, v94, v95
	v_cvt_pk_bf16_f32 v94, v88, v89
	v_add_u32_e32 v88, 0x90, v144
	global_store_dwordx4 v[116:117], v[112:115], off sc1
	v_cvt_pk_bf16_f32 v104, v36, v37
	v_cvt_pk_bf16_f32 v105, v38, v39
	v_cvt_pk_bf16_f32 v106, v32, v33
	v_cvt_pk_bf16_f32 v107, v34, v35
	global_store_dwordx4 v[108:109], v[100:103], off offset:256 sc1
	v_cvt_pk_bf16_f32 v95, v90, v91
	v_mad_i64_i32 v[88:89], s[6:7], s8, v88, 0
	v_lshl_add_u64 v[100:101], v[96:97], 1, v[158:159]
	v_cvt_pk_bf16_f32 v84, v84, v85
	v_cvt_pk_bf16_f32 v85, v86, v87
	v_cvt_pk_bf16_f32 v86, v80, v81
	v_add_u32_e32 v80, 0xa0, v144
	global_store_dwordx4 v[108:109], v[104:107], off sc1
	v_cvt_pk_bf16_f32 v96, v28, v29
	v_cvt_pk_bf16_f32 v97, v30, v31
	v_cvt_pk_bf16_f32 v98, v24, v25
	v_cvt_pk_bf16_f32 v99, v26, v27
	global_store_dwordx4 v[100:101], v[92:95], off offset:256 sc1
	v_cvt_pk_bf16_f32 v87, v82, v83
	v_mad_i64_i32 v[80:81], s[6:7], s8, v80, 0
	v_lshl_add_u64 v[92:93], v[88:89], 1, v[158:159]
	v_cvt_pk_bf16_f32 v76, v76, v77
	v_cvt_pk_bf16_f32 v77, v78, v79
	v_cvt_pk_bf16_f32 v78, v72, v73
	v_add_u32_e32 v72, 0xb0, v144
	global_store_dwordx4 v[100:101], v[96:99], off sc1
	v_cvt_pk_bf16_f32 v88, v20, v21
	v_cvt_pk_bf16_f32 v89, v22, v23
	v_cvt_pk_bf16_f32 v90, v16, v17
	v_cvt_pk_bf16_f32 v91, v18, v19
	global_store_dwordx4 v[92:93], v[84:87], off offset:256 sc1
	v_cvt_pk_bf16_f32 v79, v74, v75
	v_mad_i64_i32 v[72:73], s[6:7], s8, v72, 0
	v_lshl_add_u64 v[84:85], v[80:81], 1, v[158:159]
	global_store_dwordx4 v[92:93], v[88:91], off sc1
	v_cvt_pk_bf16_f32 v80, v12, v13
	v_cvt_pk_bf16_f32 v81, v14, v15
	v_cvt_pk_bf16_f32 v82, v8, v9
	v_cvt_pk_bf16_f32 v83, v10, v11
	global_store_dwordx4 v[84:85], v[76:79], off offset:256 sc1
	v_cvt_pk_bf16_f32 v74, v0, v1
	v_cvt_pk_bf16_f32 v75, v2, v3
	v_lshl_add_u64 v[76:77], v[72:73], 1, v[158:159]
	v_cvt_pk_bf16_f32 v72, v4, v5
	v_cvt_pk_bf16_f32 v73, v6, v7
	v_cvt_pk_bf16_f32 v68, v68, v69
	v_cvt_pk_bf16_f32 v69, v70, v71
	v_cvt_pk_bf16_f32 v70, v64, v65
	v_cvt_pk_bf16_f32 v71, v66, v67
	global_store_dwordx4 v[84:85], v[80:83], off sc1
	global_store_dwordx4 v[76:77], v[72:75], off sc1
	global_store_dwordx4 v[76:77], v[68:71], off offset:256 sc1
	s_cbranch_execnz .LBB0_585
.LBB0_583:
	s_andn2_b64 vcc, exec, s[12:13]
	s_cbranch_vccnz .LBB0_585
	v_ashrrev_i32_e32 v145, 31, v144
	v_mad_u64_u32 v[64:65], s[6:7], s29, v152, v[144:145]
	v_lshlrev_b64 v[64:65], 8, v[64:65]
	v_lshl_add_u64 v[64:65], v[136:137], 0, v[64:65]
	global_store_dwordx4 v[64:65], v[60:63], off sc1
	global_store_dwordx4 v[64:65], v[56:59], off offset:16 sc1
	s_nop 1
	v_or_b32_e32 v56, 16, v144
	v_ashrrev_i32_e32 v57, 31, v56
	v_mad_u64_u32 v[56:57], s[6:7], s29, v152, v[56:57]
	v_lshlrev_b64 v[56:57], 8, v[56:57]
	v_lshl_add_u64 v[56:57], v[136:137], 0, v[56:57]
	global_store_dwordx4 v[56:57], v[52:55], off sc1
	global_store_dwordx4 v[56:57], v[48:51], off offset:16 sc1
	s_nop 1
	v_or_b32_e32 v48, 32, v144
	v_ashrrev_i32_e32 v49, 31, v48
	v_mad_u64_u32 v[48:49], s[6:7], s29, v152, v[48:49]
	v_lshlrev_b64 v[48:49], 8, v[48:49]
	v_lshl_add_u64 v[48:49], v[136:137], 0, v[48:49]
	global_store_dwordx4 v[48:49], v[44:47], off sc1
	global_store_dwordx4 v[48:49], v[40:43], off offset:16 sc1
	s_nop 1
	v_or_b32_e32 v40, 48, v144
	v_ashrrev_i32_e32 v41, 31, v40
	v_mad_u64_u32 v[40:41], s[6:7], s29, v152, v[40:41]
	v_lshlrev_b64 v[40:41], 8, v[40:41]
	v_lshl_add_u64 v[40:41], v[136:137], 0, v[40:41]
	global_store_dwordx4 v[40:41], v[36:39], off sc1
	global_store_dwordx4 v[40:41], v[32:35], off offset:16 sc1
	s_nop 1
	v_add_u32_e32 v32, 0x80, v144
	v_ashrrev_i32_e32 v33, 31, v32
	v_mad_u64_u32 v[32:33], s[6:7], s29, v152, v[32:33]
	v_lshlrev_b64 v[32:33], 8, v[32:33]
	v_lshl_add_u64 v[32:33], v[136:137], 0, v[32:33]
	global_store_dwordx4 v[32:33], v[28:31], off sc1
	global_store_dwordx4 v[32:33], v[24:27], off offset:16 sc1
	s_nop 1
	v_add_u32_e32 v24, 0x90, v144
	v_ashrrev_i32_e32 v25, 31, v24
	v_mad_u64_u32 v[24:25], s[6:7], s29, v152, v[24:25]
	v_lshlrev_b64 v[24:25], 8, v[24:25]
	v_lshl_add_u64 v[24:25], v[136:137], 0, v[24:25]
	global_store_dwordx4 v[24:25], v[20:23], off sc1
	global_store_dwordx4 v[24:25], v[16:19], off offset:16 sc1
	s_nop 1
	v_add_u32_e32 v16, 0xa0, v144
	v_ashrrev_i32_e32 v17, 31, v16
	v_mad_u64_u32 v[16:17], s[6:7], s29, v152, v[16:17]
	v_lshlrev_b64 v[16:17], 8, v[16:17]
	v_lshl_add_u64 v[16:17], v[136:137], 0, v[16:17]
	global_store_dwordx4 v[16:17], v[12:15], off sc1
	global_store_dwordx4 v[16:17], v[8:11], off offset:16 sc1
	s_nop 1
	v_add_u32_e32 v8, 0xb0, v144
	v_ashrrev_i32_e32 v9, 31, v8
	v_mad_u64_u32 v[8:9], s[6:7], s29, v152, v[8:9]
	v_lshlrev_b64 v[8:9], 8, v[8:9]
	v_lshl_add_u64 v[8:9], v[136:137], 0, v[8:9]
	global_store_dwordx4 v[8:9], v[4:7], off sc1
	global_store_dwordx4 v[8:9], v[0:3], off offset:16 sc1

.LBB0_1144:
	v_lshl_or_b32 v164, s46, 8, v176
	v_lshl_add_u32 v162, s44, 8, v174
	s_cmp_gt_i32 s4, -1
	v_ashrrev_i32_e32 v165, 31, v164
	s_mov_b64 s[44:45], -1
	s_cbranch_scc1 .LBB0_1150
	v_lshlrev_b64 v[166:167], 1, v[164:165]
	v_ashrrev_i32_e32 v163, 31, v162
	v_lshl_add_u64 v[168:169], s[80:81], 0, v[166:167]
	v_lshlrev_b64 v[170:171], 13, v[162:163]
	v_lshl_add_u64 v[132:133], v[164:165], 2, s[8:9]
	v_lshl_add_u64 v[144:145], v[168:169], 0, v[170:171]
	global_load_dwordx4 v[136:139], v[132:133], off offset:16
	global_load_dwordx4 v[140:143], v[132:133], off
	global_load_dwordx4 v[128:131], v[132:133], off offset:528
	s_nop 0
	global_load_dwordx4 v[132:135], v[132:133], off offset:512
	s_nop 0
	global_load_dwordx4 v[180:183], v[144:145], off
	global_load_dwordx4 v[184:187], v[144:145], off offset:256
	v_or_b32_e32 v144, 16, v162
	v_ashrrev_i32_e32 v145, 31, v144
	v_lshlrev_b64 v[210:211], 13, v[144:145]
	v_lshl_add_u64 v[144:145], v[168:169], 0, v[210:211]
	global_load_dwordx4 v[188:191], v[144:145], off
	global_load_dwordx4 v[192:195], v[144:145], off offset:256
	v_or_b32_e32 v144, 32, v162
	v_ashrrev_i32_e32 v145, 31, v144
	v_lshlrev_b64 v[212:213], 13, v[144:145]
	v_lshl_add_u64 v[144:145], v[168:169], 0, v[212:213]
	global_load_dwordx4 v[196:199], v[144:145], off
	global_load_dwordx4 v[202:205], v[144:145], off offset:256
	v_or_b32_e32 v144, 48, v162
	v_ashrrev_i32_e32 v145, 31, v144
	v_lshlrev_b64 v[172:173], 13, v[144:145]
	v_lshl_add_u64 v[144:145], v[168:169], 0, v[172:173]
	global_load_dwordx4 v[206:209], v[144:145], off
	s_nop 0
	global_load_dwordx4 v[144:147], v[144:145], off offset:256
	s_waitcnt vmcnt(0)
	v_lshlrev_b32_e32 v214, 16, v180
	v_and_b32_e32 v215, 0xffff0000, v180
	v_lshlrev_b32_e32 v180, 16, v181
	v_and_b32_e32 v181, 0xffff0000, v181
	v_lshlrev_b32_e32 v216, 16, v182
	v_and_b32_e32 v217, 0xffff0000, v182
	v_lshlrev_b32_e32 v182, 16, v183
	v_and_b32_e32 v183, 0xffff0000, v183
	v_pk_mul_f32 v[214:215], v[214:215], s[16:17] op_sel_hi:[1,0]
	v_pk_mul_f32 v[180:181], v[180:181], s[16:17] op_sel_hi:[1,0]
	v_pk_mul_f32 v[182:183], v[182:183], s[16:17] op_sel_hi:[1,0]
	v_pk_fma_f32 v[218:219], v[126:127], v[142:143], v[180:181]
	v_pk_fma_f32 v[180:181], v[124:125], v[140:141], v[214:215]
	v_pk_mul_f32 v[214:215], v[216:217], s[16:17] op_sel_hi:[1,0]
	v_pk_fma_f32 v[216:217], v[122:123], v[138:139], v[182:183]
	v_pk_fma_f32 v[182:183], v[120:121], v[136:137], v[214:215]
	v_lshl_add_u64 v[214:215], s[20:21], 0, v[170:171]
	v_cvt_pk_bf16_f32 v180, v180, v181
	v_cvt_pk_bf16_f32 v181, v218, v219
	v_cvt_pk_bf16_f32 v182, v182, v183
	v_cvt_pk_bf16_f32 v183, v216, v217
	v_lshl_add_u64 v[214:215], v[214:215], 0, v[166:167]
	global_store_dwordx4 v[214:215], v[180:183], off sc1
	v_lshl_add_u64 v[172:173], s[20:21], 0, v[172:173]
	v_lshl_add_u64 v[172:173], v[172:173], 0, v[166:167]
	v_lshlrev_b32_e32 v180, 16, v184
	v_and_b32_e32 v181, 0xffff0000, v184
	v_lshlrev_b32_e32 v182, 16, v185
	v_and_b32_e32 v183, 0xffff0000, v185
	v_lshlrev_b32_e32 v184, 16, v186
	v_and_b32_e32 v185, 0xffff0000, v186
	v_lshlrev_b32_e32 v186, 16, v187
	v_and_b32_e32 v187, 0xffff0000, v187
	v_pk_mul_f32 v[180:181], v[180:181], s[16:17] op_sel_hi:[1,0]
	v_pk_mul_f32 v[182:183], v[182:183], s[16:17] op_sel_hi:[1,0]
	v_pk_mul_f32 v[184:185], v[184:185], s[16:17] op_sel_hi:[1,0]
	v_pk_mul_f32 v[186:187], v[186:187], s[16:17] op_sel_hi:[1,0]
	v_pk_fma_f32 v[182:183], v[118:119], v[134:135], v[182:183]
	v_pk_fma_f32 v[180:181], v[116:117], v[132:133], v[180:181]
	v_pk_fma_f32 v[186:187], v[114:115], v[130:131], v[186:187]
	v_pk_fma_f32 v[184:185], v[112:113], v[128:129], v[184:185]
	v_cvt_pk_bf16_f32 v180, v180, v181
	v_cvt_pk_bf16_f32 v181, v182, v183
	v_cvt_pk_bf16_f32 v182, v184, v185
	v_cvt_pk_bf16_f32 v183, v186, v187
	global_store_dwordx4 v[214:215], v[180:183], off offset:256 sc1
	v_lshlrev_b32_e32 v184, 16, v190
	v_and_b32_e32 v185, 0xffff0000, v190
	v_lshlrev_b32_e32 v180, 16, v188
	v_and_b32_e32 v181, 0xffff0000, v188
	v_lshlrev_b32_e32 v182, 16, v189
	v_and_b32_e32 v183, 0xffff0000, v189
	v_lshlrev_b32_e32 v186, 16, v191
	v_and_b32_e32 v187, 0xffff0000, v191
	v_pk_mul_f32 v[180:181], v[180:181], s[16:17] op_sel_hi:[1,0]
	v_pk_mul_f32 v[182:183], v[182:183], s[16:17] op_sel_hi:[1,0]
	v_pk_mul_f32 v[184:185], v[184:185], s[16:17] op_sel_hi:[1,0]
	v_pk_fma_f32 v[182:183], v[110:111], v[142:143], v[182:183]
	v_pk_fma_f32 v[180:181], v[108:109], v[140:141], v[180:181]
	v_pk_mul_f32 v[186:187], v[186:187], s[16:17] op_sel_hi:[1,0]
	v_pk_fma_f32 v[184:185], v[104:105], v[136:137], v[184:185]
	v_pk_fma_f32 v[186:187], v[106:107], v[138:139], v[186:187]
	v_cvt_pk_bf16_f32 v180, v180, v181
	v_cvt_pk_bf16_f32 v181, v182, v183
	v_cvt_pk_bf16_f32 v182, v184, v185
	v_lshl_add_u64 v[184:185], s[20:21], 0, v[210:211]
	v_cvt_pk_bf16_f32 v183, v186, v187
	v_lshl_add_u64 v[184:185], v[184:185], 0, v[166:167]
	global_store_dwordx4 v[184:185], v[180:183], off sc1
	v_lshlrev_b32_e32 v186, 16, v194
	v_and_b32_e32 v187, 0xffff0000, v194
	v_lshlrev_b32_e32 v180, 16, v192
	v_and_b32_e32 v181, 0xffff0000, v192
	v_lshlrev_b32_e32 v182, 16, v193
	v_and_b32_e32 v183, 0xffff0000, v193
	v_lshlrev_b32_e32 v188, 16, v195
	v_and_b32_e32 v189, 0xffff0000, v195
	v_pk_mul_f32 v[180:181], v[180:181], s[16:17] op_sel_hi:[1,0]
	v_pk_mul_f32 v[182:183], v[182:183], s[16:17] op_sel_hi:[1,0]
	v_pk_mul_f32 v[186:187], v[186:187], s[16:17] op_sel_hi:[1,0]
	v_pk_mul_f32 v[188:189], v[188:189], s[16:17] op_sel_hi:[1,0]
	v_pk_fma_f32 v[182:183], v[102:103], v[134:135], v[182:183]
	v_pk_fma_f32 v[180:181], v[100:101], v[132:133], v[180:181]
	v_pk_fma_f32 v[188:189], v[98:99], v[130:131], v[188:189]
	v_pk_fma_f32 v[186:187], v[96:97], v[128:129], v[186:187]
	v_cvt_pk_bf16_f32 v180, v180, v181
	v_cvt_pk_bf16_f32 v181, v182, v183
	v_cvt_pk_bf16_f32 v182, v186, v187
	v_cvt_pk_bf16_f32 v183, v188, v189
	global_store_dwordx4 v[184:185], v[180:183], off offset:256 sc1
	v_lshlrev_b32_e32 v184, 16, v198
	v_and_b32_e32 v185, 0xffff0000, v198
	v_lshlrev_b32_e32 v180, 16, v196
	v_and_b32_e32 v181, 0xffff0000, v196
	v_lshlrev_b32_e32 v182, 16, v197
	v_and_b32_e32 v183, 0xffff0000, v197
	v_lshlrev_b32_e32 v186, 16, v199
	v_and_b32_e32 v187, 0xffff0000, v199
	v_pk_mul_f32 v[180:181], v[180:181], s[16:17] op_sel_hi:[1,0]
	v_pk_mul_f32 v[182:183], v[182:183], s[16:17] op_sel_hi:[1,0]
	v_pk_mul_f32 v[184:185], v[184:185], s[16:17] op_sel_hi:[1,0]
	v_pk_fma_f32 v[182:183], v[94:95], v[142:143], v[182:183]
	v_pk_fma_f32 v[180:181], v[92:93], v[140:141], v[180:181]
	v_pk_mul_f32 v[186:187], v[186:187], s[16:17] op_sel_hi:[1,0]
	v_pk_fma_f32 v[184:185], v[88:89], v[136:137], v[184:185]
	v_pk_fma_f32 v[186:187], v[90:91], v[138:139], v[186:187]
	v_cvt_pk_bf16_f32 v180, v180, v181
	v_cvt_pk_bf16_f32 v181, v182, v183
	v_cvt_pk_bf16_f32 v182, v184, v185
	v_lshl_add_u64 v[184:185], s[20:21], 0, v[212:213]
	v_cvt_pk_bf16_f32 v183, v186, v187
	v_lshl_add_u64 v[184:185], v[184:185], 0, v[166:167]
	global_store_dwordx4 v[184:185], v[180:183], off sc1
	v_lshlrev_b32_e32 v186, 16, v204
	v_and_b32_e32 v187, 0xffff0000, v204
	v_lshlrev_b32_e32 v180, 16, v202
	v_and_b32_e32 v181, 0xffff0000, v202
	v_lshlrev_b32_e32 v182, 16, v203
	v_and_b32_e32 v183, 0xffff0000, v203
	v_lshlrev_b32_e32 v188, 16, v205
	v_and_b32_e32 v189, 0xffff0000, v205
	v_pk_mul_f32 v[180:181], v[180:181], s[16:17] op_sel_hi:[1,0]
	v_pk_mul_f32 v[182:183], v[182:183], s[16:17] op_sel_hi:[1,0]
	v_pk_mul_f32 v[186:187], v[186:187], s[16:17] op_sel_hi:[1,0]
	v_pk_mul_f32 v[188:189], v[188:189], s[16:17] op_sel_hi:[1,0]
	v_pk_fma_f32 v[182:183], v[86:87], v[134:135], v[182:183]
	v_pk_fma_f32 v[180:181], v[84:85], v[132:133], v[180:181]
	v_pk_fma_f32 v[188:189], v[82:83], v[130:131], v[188:189]
	v_pk_fma_f32 v[186:187], v[80:81], v[128:129], v[186:187]
	v_cvt_pk_bf16_f32 v180, v180, v181
	v_cvt_pk_bf16_f32 v181, v182, v183
	v_cvt_pk_bf16_f32 v182, v186, v187
	v_cvt_pk_bf16_f32 v183, v188, v189
	global_store_dwordx4 v[184:185], v[180:183], off offset:256 sc1
	v_lshlrev_b32_e32 v184, 16, v208
	v_and_b32_e32 v185, 0xffff0000, v208
	v_lshlrev_b32_e32 v180, 16, v206
	v_and_b32_e32 v181, 0xffff0000, v206
	v_lshlrev_b32_e32 v182, 16, v207
	v_and_b32_e32 v183, 0xffff0000, v207
	v_lshlrev_b32_e32 v186, 16, v209
	v_and_b32_e32 v187, 0xffff0000, v209
	v_pk_mul_f32 v[180:181], v[180:181], s[16:17] op_sel_hi:[1,0]
	v_pk_mul_f32 v[182:183], v[182:183], s[16:17] op_sel_hi:[1,0]
	v_pk_mul_f32 v[184:185], v[184:185], s[16:17] op_sel_hi:[1,0]
	v_pk_mul_f32 v[186:187], v[186:187], s[16:17] op_sel_hi:[1,0]
	v_pk_fma_f32 v[182:183], v[78:79], v[142:143], v[182:183]
	v_pk_fma_f32 v[180:181], v[76:77], v[140:141], v[180:181]
	v_pk_fma_f32 v[186:187], v[74:75], v[138:139], v[186:187]
	v_pk_fma_f32 v[184:185], v[72:73], v[136:137], v[184:185]
	v_cvt_pk_bf16_f32 v180, v180, v181
	v_cvt_pk_bf16_f32 v181, v182, v183
	v_cvt_pk_bf16_f32 v182, v184, v185
	v_cvt_pk_bf16_f32 v183, v186, v187
	global_store_dwordx4 v[172:173], v[180:183], off sc1
	s_nop 1
	v_lshlrev_b32_e32 v180, 16, v144
	v_and_b32_e32 v181, 0xffff0000, v144
	v_lshlrev_b32_e32 v144, 16, v145
	v_and_b32_e32 v145, 0xffff0000, v145
	v_lshlrev_b32_e32 v182, 16, v146
	v_and_b32_e32 v183, 0xffff0000, v146
	v_lshlrev_b32_e32 v146, 16, v147
	v_and_b32_e32 v147, 0xffff0000, v147
	v_pk_mul_f32 v[180:181], v[180:181], s[16:17] op_sel_hi:[1,0]
	v_pk_mul_f32 v[144:145], v[144:145], s[16:17] op_sel_hi:[1,0]
	v_pk_mul_f32 v[146:147], v[146:147], s[16:17] op_sel_hi:[1,0]
	v_pk_fma_f32 v[184:185], v[70:71], v[134:135], v[144:145]
	v_pk_fma_f32 v[144:145], v[68:69], v[132:133], v[180:181]
	v_pk_mul_f32 v[180:181], v[182:183], s[16:17] op_sel_hi:[1,0]
	v_pk_fma_f32 v[182:183], v[66:67], v[130:131], v[146:147]
	v_pk_fma_f32 v[146:147], v[64:65], v[128:129], v[180:181]
	v_cvt_pk_bf16_f32 v144, v144, v145
	v_cvt_pk_bf16_f32 v145, v184, v185
	v_cvt_pk_bf16_f32 v146, v146, v147
	v_cvt_pk_bf16_f32 v147, v182, v183
	global_store_dwordx4 v[172:173], v[144:147], off offset:256 sc1
	s_mov_b64 s[44:45], 0x100000
	v_lshl_add_u64 v[172:173], v[170:171], 0, s[44:45]
	s_mov_b64 s[44:45], 0x120000
	v_lshl_add_u64 v[144:145], v[168:169], 0, v[172:173]
	v_lshl_add_u64 v[210:211], v[170:171], 0, s[44:45]
	global_load_dwordx4 v[180:183], v[144:145], off
	global_load_dwordx4 v[184:187], v[144:145], off offset:256
	v_lshl_add_u64 v[144:145], v[168:169], 0, v[210:211]
	v_lshl_add_u64 v[212:213], v[170:171], 0, s[28:29]
	global_load_dwordx4 v[188:191], v[144:145], off
	global_load_dwordx4 v[192:195], v[144:145], off offset:256
	v_lshl_add_u64 v[144:145], v[168:169], 0, v[212:213]
	v_lshl_add_u64 v[170:171], v[170:171], 0, s[30:31]
	global_load_dwordx4 v[196:199], v[144:145], off
	global_load_dwordx4 v[202:205], v[144:145], off offset:256
	v_lshl_add_u64 v[144:145], v[168:169], 0, v[170:171]
	global_load_dwordx4 v[206:209], v[144:145], off
	s_nop 0
	global_load_dwordx4 v[144:147], v[144:145], off offset:256
	s_waitcnt vmcnt(0)
	v_lshlrev_b32_e32 v168, 16, v180
	v_and_b32_e32 v169, 0xffff0000, v180
	v_lshlrev_b32_e32 v180, 16, v181
	v_and_b32_e32 v181, 0xffff0000, v181
	v_lshlrev_b32_e32 v214, 16, v182
	v_and_b32_e32 v215, 0xffff0000, v182
	v_lshlrev_b32_e32 v182, 16, v183
	v_and_b32_e32 v183, 0xffff0000, v183
	v_pk_mul_f32 v[168:169], v[168:169], s[16:17] op_sel_hi:[1,0]
	v_pk_mul_f32 v[180:181], v[180:181], s[16:17] op_sel_hi:[1,0]
	v_pk_fma_f32 v[168:169], v[60:61], v[140:141], v[168:169]
	v_pk_fma_f32 v[216:217], v[62:63], v[142:143], v[180:181]
	v_pk_mul_f32 v[180:181], v[214:215], s[16:17] op_sel_hi:[1,0]
	v_pk_mul_f32 v[182:183], v[182:183], s[16:17] op_sel_hi:[1,0]
	s_nop 0
	v_pk_fma_f32 v[214:215], v[58:59], v[138:139], v[182:183]
	v_pk_fma_f32 v[182:183], v[56:57], v[136:137], v[180:181]
	v_cvt_pk_bf16_f32 v180, v168, v169
	v_lshl_add_u64 v[168:169], s[20:21], 0, v[172:173]
	v_cvt_pk_bf16_f32 v181, v216, v217
	v_cvt_pk_bf16_f32 v182, v182, v183
	v_cvt_pk_bf16_f32 v183, v214, v215
	v_lshl_add_u64 v[168:169], v[168:169], 0, v[166:167]
	global_store_dwordx4 v[168:169], v[180:183], off sc1
	v_lshlrev_b32_e32 v172, 16, v184
	v_and_b32_e32 v173, 0xffff0000, v184
	v_lshlrev_b32_e32 v180, 16, v185
	v_and_b32_e32 v181, 0xffff0000, v185
	v_lshlrev_b32_e32 v182, 16, v186
	v_and_b32_e32 v183, 0xffff0000, v186
	v_lshlrev_b32_e32 v184, 16, v187
	v_and_b32_e32 v185, 0xffff0000, v187
	v_pk_mul_f32 v[180:181], v[180:181], s[16:17] op_sel_hi:[1,0]
	v_pk_mul_f32 v[172:173], v[172:173], s[16:17] op_sel_hi:[1,0]
	v_pk_fma_f32 v[186:187], v[54:55], v[134:135], v[180:181]
	v_pk_mul_f32 v[180:181], v[182:183], s[16:17] op_sel_hi:[1,0]
	v_pk_mul_f32 v[182:183], v[184:185], s[16:17] op_sel_hi:[1,0]
	v_pk_fma_f32 v[172:173], v[52:53], v[132:133], v[172:173]
	v_pk_fma_f32 v[184:185], v[50:51], v[130:131], v[182:183]
	v_pk_fma_f32 v[182:183], v[48:49], v[128:129], v[180:181]
	v_cvt_pk_bf16_f32 v180, v172, v173
	v_cvt_pk_bf16_f32 v181, v186, v187
	v_cvt_pk_bf16_f32 v182, v182, v183
	v_cvt_pk_bf16_f32 v183, v184, v185
	global_store_dwordx4 v[168:169], v[180:183], off offset:256 sc1
	v_lshlrev_b32_e32 v168, 16, v188
	v_and_b32_e32 v169, 0xffff0000, v188
	v_lshlrev_b32_e32 v172, 16, v189
	v_and_b32_e32 v173, 0xffff0000, v189
	v_lshlrev_b32_e32 v180, 16, v190
	v_and_b32_e32 v181, 0xffff0000, v190
	v_lshlrev_b32_e32 v182, 16, v191
	v_and_b32_e32 v183, 0xffff0000, v191
	v_pk_mul_f32 v[168:169], v[168:169], s[16:17] op_sel_hi:[1,0]
	v_pk_mul_f32 v[172:173], v[172:173], s[16:17] op_sel_hi:[1,0]
	v_pk_fma_f32 v[168:169], v[44:45], v[140:141], v[168:169]
	v_pk_mul_f32 v[180:181], v[180:181], s[16:17] op_sel_hi:[1,0]
	v_pk_mul_f32 v[182:183], v[182:183], s[16:17] op_sel_hi:[1,0]
	v_pk_fma_f32 v[172:173], v[46:47], v[142:143], v[172:173]
	v_pk_fma_f32 v[184:185], v[42:43], v[138:139], v[182:183]
	v_pk_fma_f32 v[182:183], v[40:41], v[136:137], v[180:181]
	v_cvt_pk_bf16_f32 v180, v168, v169
	v_lshl_add_u64 v[168:169], s[20:21], 0, v[210:211]
	v_cvt_pk_bf16_f32 v181, v172, v173
	v_cvt_pk_bf16_f32 v182, v182, v183
	v_cvt_pk_bf16_f32 v183, v184, v185
	v_lshl_add_u64 v[168:169], v[168:169], 0, v[166:167]
	global_store_dwordx4 v[168:169], v[180:183], off sc1
	v_lshlrev_b32_e32 v172, 16, v192
	v_and_b32_e32 v173, 0xffff0000, v192
	v_lshlrev_b32_e32 v180, 16, v193
	v_and_b32_e32 v181, 0xffff0000, v193
	v_lshlrev_b32_e32 v182, 16, v194
	v_and_b32_e32 v183, 0xffff0000, v194
	v_lshlrev_b32_e32 v184, 16, v195
	v_and_b32_e32 v185, 0xffff0000, v195
	v_pk_mul_f32 v[180:181], v[180:181], s[16:17] op_sel_hi:[1,0]
	v_pk_mul_f32 v[172:173], v[172:173], s[16:17] op_sel_hi:[1,0]
	v_pk_fma_f32 v[186:187], v[38:39], v[134:135], v[180:181]
	v_pk_mul_f32 v[180:181], v[182:183], s[16:17] op_sel_hi:[1,0]
	v_pk_mul_f32 v[182:183], v[184:185], s[16:17] op_sel_hi:[1,0]
	v_pk_fma_f32 v[172:173], v[36:37], v[132:133], v[172:173]
	v_pk_fma_f32 v[184:185], v[34:35], v[130:131], v[182:183]
	v_pk_fma_f32 v[182:183], v[32:33], v[128:129], v[180:181]
	v_cvt_pk_bf16_f32 v180, v172, v173
	v_cvt_pk_bf16_f32 v181, v186, v187
	v_cvt_pk_bf16_f32 v182, v182, v183
	v_cvt_pk_bf16_f32 v183, v184, v185
	global_store_dwordx4 v[168:169], v[180:183], off offset:256 sc1
	v_lshlrev_b32_e32 v168, 16, v196
	v_and_b32_e32 v169, 0xffff0000, v196
	v_lshlrev_b32_e32 v172, 16, v197
	v_and_b32_e32 v173, 0xffff0000, v197
	v_lshlrev_b32_e32 v180, 16, v198
	v_and_b32_e32 v181, 0xffff0000, v198
	v_lshlrev_b32_e32 v182, 16, v199
	v_and_b32_e32 v183, 0xffff0000, v199
	v_pk_mul_f32 v[168:169], v[168:169], s[16:17] op_sel_hi:[1,0]
	v_pk_mul_f32 v[172:173], v[172:173], s[16:17] op_sel_hi:[1,0]
	v_pk_fma_f32 v[168:169], v[28:29], v[140:141], v[168:169]
	v_pk_mul_f32 v[180:181], v[180:181], s[16:17] op_sel_hi:[1,0]
	v_pk_mul_f32 v[182:183], v[182:183], s[16:17] op_sel_hi:[1,0]
	v_pk_fma_f32 v[172:173], v[30:31], v[142:143], v[172:173]
	v_pk_fma_f32 v[184:185], v[26:27], v[138:139], v[182:183]
	v_pk_fma_f32 v[182:183], v[24:25], v[136:137], v[180:181]
	v_cvt_pk_bf16_f32 v180, v168, v169
	v_lshl_add_u64 v[168:169], s[20:21], 0, v[212:213]
	v_cvt_pk_bf16_f32 v181, v172, v173
	v_cvt_pk_bf16_f32 v182, v182, v183
	v_cvt_pk_bf16_f32 v183, v184, v185
	v_lshl_add_u64 v[168:169], v[168:169], 0, v[166:167]
	global_store_dwordx4 v[168:169], v[180:183], off sc1
	v_lshlrev_b32_e32 v172, 16, v202
	v_and_b32_e32 v173, 0xffff0000, v202
	v_lshlrev_b32_e32 v180, 16, v203
	v_and_b32_e32 v181, 0xffff0000, v203
	v_lshlrev_b32_e32 v182, 16, v204
	v_and_b32_e32 v183, 0xffff0000, v204
	v_lshlrev_b32_e32 v184, 16, v205
	v_and_b32_e32 v185, 0xffff0000, v205
	v_pk_mul_f32 v[180:181], v[180:181], s[16:17] op_sel_hi:[1,0]
	v_pk_mul_f32 v[172:173], v[172:173], s[16:17] op_sel_hi:[1,0]
	v_pk_fma_f32 v[186:187], v[22:23], v[134:135], v[180:181]
	v_pk_mul_f32 v[180:181], v[182:183], s[16:17] op_sel_hi:[1,0]
	v_pk_mul_f32 v[182:183], v[184:185], s[16:17] op_sel_hi:[1,0]
	v_pk_fma_f32 v[172:173], v[20:21], v[132:133], v[172:173]
	v_pk_fma_f32 v[184:185], v[18:19], v[130:131], v[182:183]
	v_pk_fma_f32 v[182:183], v[16:17], v[128:129], v[180:181]
	v_cvt_pk_bf16_f32 v180, v172, v173
	v_cvt_pk_bf16_f32 v181, v186, v187
	v_cvt_pk_bf16_f32 v182, v182, v183
	v_cvt_pk_bf16_f32 v183, v184, v185
	global_store_dwordx4 v[168:169], v[180:183], off offset:256 sc1
	v_lshlrev_b32_e32 v168, 16, v206
	v_and_b32_e32 v169, 0xffff0000, v206
	v_lshlrev_b32_e32 v172, 16, v207
	v_and_b32_e32 v173, 0xffff0000, v207
	v_lshlrev_b32_e32 v180, 16, v208
	v_and_b32_e32 v181, 0xffff0000, v208
	v_lshlrev_b32_e32 v182, 16, v209
	v_and_b32_e32 v183, 0xffff0000, v209
	v_pk_mul_f32 v[168:169], v[168:169], s[16:17] op_sel_hi:[1,0]
	v_pk_mul_f32 v[172:173], v[172:173], s[16:17] op_sel_hi:[1,0]
	v_pk_fma_f32 v[140:141], v[12:13], v[140:141], v[168:169]
	v_pk_fma_f32 v[142:143], v[14:15], v[142:143], v[172:173]
	v_pk_mul_f32 v[168:169], v[180:181], s[16:17] op_sel_hi:[1,0]
	v_pk_mul_f32 v[172:173], v[182:183], s[16:17] op_sel_hi:[1,0]
	s_nop 0
	v_pk_fma_f32 v[172:173], v[10:11], v[138:139], v[172:173]
	v_pk_fma_f32 v[138:139], v[8:9], v[136:137], v[168:169]
	v_cvt_pk_bf16_f32 v136, v140, v141
	v_lshl_add_u64 v[140:141], s[20:21], 0, v[170:171]
	v_cvt_pk_bf16_f32 v137, v142, v143
	v_cvt_pk_bf16_f32 v138, v138, v139
	v_cvt_pk_bf16_f32 v139, v172, v173
	v_lshl_add_u64 v[140:141], v[140:141], 0, v[166:167]
	global_store_dwordx4 v[140:141], v[136:139], off sc1
	v_lshlrev_b32_e32 v142, 16, v146
	v_and_b32_e32 v143, 0xffff0000, v146
	v_lshlrev_b32_e32 v136, 16, v144
	v_and_b32_e32 v137, 0xffff0000, v144
	v_lshlrev_b32_e32 v138, 16, v145
	v_and_b32_e32 v139, 0xffff0000, v145
	v_lshlrev_b32_e32 v144, 16, v147
	v_and_b32_e32 v145, 0xffff0000, v147
	v_pk_mul_f32 v[136:137], v[136:137], s[16:17] op_sel_hi:[1,0]
	v_pk_mul_f32 v[138:139], v[138:139], s[16:17] op_sel_hi:[1,0]
	v_pk_fma_f32 v[132:133], v[4:5], v[132:133], v[136:137]
	v_pk_fma_f32 v[134:135], v[6:7], v[134:135], v[138:139]
	v_pk_mul_f32 v[136:137], v[142:143], s[16:17] op_sel_hi:[1,0]
	v_pk_mul_f32 v[138:139], v[144:145], s[16:17] op_sel_hi:[1,0]
	s_nop 0
	v_pk_fma_f32 v[138:139], v[2:3], v[130:131], v[138:139]
	v_pk_fma_f32 v[130:131], v[0:1], v[128:129], v[136:137]
	v_cvt_pk_bf16_f32 v128, v132, v133
	v_cvt_pk_bf16_f32 v129, v134, v135
	v_cvt_pk_bf16_f32 v130, v130, v131
	v_cvt_pk_bf16_f32 v131, v138, v139
	global_store_dwordx4 v[140:141], v[128:131], off offset:256 sc1
	s_cbranch_execz .LBB0_1151

.LBB0_1151:
	s_nop 0
	v_add_u32_e32 v128, 0xffffe000, v162
	s_lshl_b64 s[44:45], s[4:5], 23
	v_ashrrev_i32_e32 v129, 31, v128
	s_add_u32 s44, s78, s44
	s_addc_u32 s45, s79, s45
	v_lshlrev_b64 v[128:129], 14, v[128:129]
	v_lshl_add_u64 v[128:129], s[44:45], 0, v[128:129]
	v_lshlrev_b64 v[130:131], 2, v[164:165]
	v_lshl_add_u64 v[128:129], v[128:129], 0, v[130:131]
	global_store_dwordx4 v[128:129], v[124:127], off sc1
	global_store_dwordx4 v[128:129], v[120:123], off offset:16 sc1
	global_store_dwordx4 v[128:129], v[116:119], off offset:512 sc1
	global_store_dwordx4 v[128:129], v[112:115], off offset:528 sc1
	s_nop 1
	v_add_u32_e32 v112, 0xffffe010, v162
	v_ashrrev_i32_e32 v113, 31, v112
	v_lshlrev_b64 v[112:113], 14, v[112:113]
	v_lshl_add_u64 v[112:113], s[44:45], 0, v[112:113]
	v_lshl_add_u64 v[112:113], v[112:113], 0, v[130:131]
	global_store_dwordx4 v[112:113], v[108:111], off sc1
	global_store_dwordx4 v[112:113], v[104:107], off offset:16 sc1
	global_store_dwordx4 v[112:113], v[100:103], off offset:512 sc1
	global_store_dwordx4 v[112:113], v[96:99], off offset:528 sc1
	s_nop 1
	v_add_u32_e32 v96, 0xffffe020, v162
	v_ashrrev_i32_e32 v97, 31, v96
	v_lshlrev_b64 v[96:97], 14, v[96:97]
	v_lshl_add_u64 v[96:97], s[44:45], 0, v[96:97]
	v_lshl_add_u64 v[96:97], v[96:97], 0, v[130:131]
	global_store_dwordx4 v[96:97], v[92:95], off sc1
	global_store_dwordx4 v[96:97], v[88:91], off offset:16 sc1
	global_store_dwordx4 v[96:97], v[84:87], off offset:512 sc1
	global_store_dwordx4 v[96:97], v[80:83], off offset:528 sc1
	s_nop 1
	v_add_u32_e32 v80, 0xffffe030, v162
	v_ashrrev_i32_e32 v81, 31, v80
	v_lshlrev_b64 v[80:81], 14, v[80:81]
	v_lshl_add_u64 v[80:81], s[44:45], 0, v[80:81]
	v_lshl_add_u64 v[80:81], v[80:81], 0, v[130:131]
	global_store_dwordx4 v[80:81], v[76:79], off sc1
	global_store_dwordx4 v[80:81], v[72:75], off offset:16 sc1
	global_store_dwordx4 v[80:81], v[68:71], off offset:512 sc1
	global_store_dwordx4 v[80:81], v[64:67], off offset:528 sc1
	s_nop 1
	v_add_u32_e32 v64, 0xffffe080, v162
	v_ashrrev_i32_e32 v65, 31, v64
	v_lshlrev_b64 v[64:65], 14, v[64:65]
	v_lshl_add_u64 v[64:65], s[44:45], 0, v[64:65]
	v_lshl_add_u64 v[64:65], v[64:65], 0, v[130:131]
	global_store_dwordx4 v[64:65], v[60:63], off sc1
	global_store_dwordx4 v[64:65], v[56:59], off offset:16 sc1
	global_store_dwordx4 v[64:65], v[52:55], off offset:512 sc1
	global_store_dwordx4 v[64:65], v[48:51], off offset:528 sc1
	s_nop 1
	v_add_u32_e32 v48, 0xffffe090, v162
	v_ashrrev_i32_e32 v49, 31, v48
	v_lshlrev_b64 v[48:49], 14, v[48:49]
	v_lshl_add_u64 v[48:49], s[44:45], 0, v[48:49]
	v_lshl_add_u64 v[48:49], v[48:49], 0, v[130:131]
	global_store_dwordx4 v[48:49], v[44:47], off sc1
	global_store_dwordx4 v[48:49], v[40:43], off offset:16 sc1
	global_store_dwordx4 v[48:49], v[36:39], off offset:512 sc1
	global_store_dwordx4 v[48:49], v[32:35], off offset:528 sc1
	s_nop 1
	v_add_u32_e32 v32, 0xffffe0a0, v162
	v_ashrrev_i32_e32 v33, 31, v32
	v_lshlrev_b64 v[32:33], 14, v[32:33]
	v_lshl_add_u64 v[32:33], s[44:45], 0, v[32:33]
	v_lshl_add_u64 v[32:33], v[32:33], 0, v[130:131]
	global_store_dwordx4 v[32:33], v[28:31], off sc1
	global_store_dwordx4 v[32:33], v[24:27], off offset:16 sc1
	global_store_dwordx4 v[32:33], v[20:23], off offset:512 sc1
	global_store_dwordx4 v[32:33], v[16:19], off offset:528 sc1
	s_nop 1
	v_add_u32_e32 v16, 0xffffe0b0, v162
	v_ashrrev_i32_e32 v17, 31, v16
	v_lshlrev_b64 v[16:17], 14, v[16:17]
	v_lshl_add_u64 v[16:17], s[44:45], 0, v[16:17]
	v_lshl_add_u64 v[16:17], v[16:17], 0, v[130:131]
	global_store_dwordx4 v[16:17], v[12:15], off sc1
	global_store_dwordx4 v[16:17], v[8:11], off offset:16 sc1
	global_store_dwordx4 v[16:17], v[4:7], off offset:512 sc1
	global_store_dwordx4 v[16:17], v[0:3], off offset:528 sc1
	s_and_b64 vcc, exec, s[2:3]
	s_mov_b64 s[2:3], -1
	s_cbranch_vccnz .LBB0_1125

.LBB0_1302:
	v_pk_mul_f32 v[158:159], v[126:127], s[8:9] op_sel_hi:[1,0]
	v_pk_mul_f32 v[160:161], v[124:125], s[8:9] op_sel_hi:[1,0]
	v_pk_mul_f32 v[162:163], v[122:123], s[8:9] op_sel_hi:[1,0]
	v_pk_mul_f32 v[164:165], v[120:121], s[8:9] op_sel_hi:[1,0]
	v_exp_f32_e32 v160, v160
	v_exp_f32_e32 v164, v164
	v_exp_f32_e32 v161, v161
	v_exp_f32_e32 v158, v158
	v_exp_f32_e32 v159, v159
	v_exp_f32_e32 v162, v162
	v_exp_f32_e32 v163, v163
	v_exp_f32_e32 v165, v165
	v_pk_add_f32 v[158:159], v[158:159], 1.0 op_sel_hi:[1,0]
	v_pk_add_f32 v[160:161], v[160:161], 1.0 op_sel_hi:[1,0]
	v_pk_add_f32 v[162:163], v[162:163], 1.0 op_sel_hi:[1,0]
	v_pk_add_f32 v[164:165], v[164:165], 1.0 op_sel_hi:[1,0]
	v_rcp_f32_e32 v160, v160
	v_rcp_f32_e32 v164, v164
	v_rcp_f32_e32 v161, v161
	v_rcp_f32_e32 v165, v165
	v_rcp_f32_e32 v158, v158
	v_rcp_f32_e32 v162, v162
	v_rcp_f32_e32 v159, v159
	v_rcp_f32_e32 v163, v163
	v_readlane_b32 s34, v253, 8
	v_lshl_or_b32 v146, s52, 7, v152
	v_readlane_b32 s35, v253, 9
	v_lshl_add_u32 v166, s30, 8, v150
	v_ashrrev_i32_e32 v147, 31, v146
	v_mov_b64_e32 v[144:145], s[34:35]
	v_pk_mul_f32 v[118:119], v[118:119], v[126:127]
	v_pk_mul_f32 v[116:117], v[116:117], v[124:125]
	v_pk_mul_f32 v[114:115], v[114:115], v[122:123]
	v_pk_mul_f32 v[112:113], v[112:113], v[120:121]
	v_mad_i64_i32 v[156:157], s[34:35], v166, s51, v[144:145]
	v_lshlrev_b64 v[146:147], 1, v[146:147]
	v_pk_mul_f32 v[118:119], v[118:119], v[158:159]
	v_pk_mul_f32 v[116:117], v[116:117], v[160:161]
	v_pk_mul_f32 v[120:121], v[114:115], v[162:163]
	v_pk_mul_f32 v[114:115], v[112:113], v[164:165]
	v_lshl_add_u64 v[156:157], v[156:157], 0, v[146:147]
	v_cvt_pk_bf16_f32 v112, v116, v117
	v_cvt_pk_bf16_f32 v113, v118, v119
	v_cvt_pk_bf16_f32 v114, v114, v115
	v_cvt_pk_bf16_f32 v115, v120, v121
	global_store_dwordx4 v[156:157], v[112:115], off sc1
	v_pk_mul_f32 v[116:117], v[108:109], s[8:9] op_sel_hi:[1,0]
	v_pk_mul_f32 v[118:119], v[106:107], s[8:9] op_sel_hi:[1,0]
	v_pk_mul_f32 v[114:115], v[110:111], s[8:9] op_sel_hi:[1,0]
	v_pk_mul_f32 v[120:121], v[104:105], s[8:9] op_sel_hi:[1,0]
	v_exp_f32_e32 v116, v116
	v_exp_f32_e32 v120, v120
	v_exp_f32_e32 v117, v117
	v_exp_f32_e32 v114, v114
	v_exp_f32_e32 v115, v115
	v_exp_f32_e32 v118, v118
	v_exp_f32_e32 v119, v119
	v_exp_f32_e32 v121, v121
	v_pk_add_f32 v[114:115], v[114:115], 1.0 op_sel_hi:[1,0]
	v_pk_add_f32 v[116:117], v[116:117], 1.0 op_sel_hi:[1,0]
	v_pk_add_f32 v[118:119], v[118:119], 1.0 op_sel_hi:[1,0]
	v_pk_add_f32 v[120:121], v[120:121], 1.0 op_sel_hi:[1,0]
	v_rcp_f32_e32 v116, v116
	v_rcp_f32_e32 v120, v120
	v_rcp_f32_e32 v117, v117
	v_rcp_f32_e32 v121, v121
	v_rcp_f32_e32 v114, v114
	v_rcp_f32_e32 v118, v118
	v_rcp_f32_e32 v115, v115
	v_rcp_f32_e32 v119, v119
	v_or_b32_e32 v112, 16, v166
	v_pk_mul_f32 v[102:103], v[102:103], v[110:111]
	v_pk_mul_f32 v[100:101], v[100:101], v[108:109]
	v_pk_mul_f32 v[98:99], v[98:99], v[106:107]
	v_pk_mul_f32 v[96:97], v[96:97], v[104:105]
	v_mad_i64_i32 v[112:113], s[34:35], v112, s51, v[144:145]
	v_pk_mul_f32 v[102:103], v[102:103], v[114:115]
	v_pk_mul_f32 v[100:101], v[100:101], v[116:117]
	v_pk_mul_f32 v[104:105], v[98:99], v[118:119]
	v_pk_mul_f32 v[98:99], v[96:97], v[120:121]
	v_lshl_add_u64 v[112:113], v[112:113], 0, v[146:147]
	v_cvt_pk_bf16_f32 v96, v100, v101
	v_cvt_pk_bf16_f32 v97, v102, v103
	v_cvt_pk_bf16_f32 v98, v98, v99
	v_cvt_pk_bf16_f32 v99, v104, v105
	global_store_dwordx4 v[112:113], v[96:99], off sc1
	v_pk_mul_f32 v[100:101], v[92:93], s[8:9] op_sel_hi:[1,0]
	v_pk_mul_f32 v[102:103], v[90:91], s[8:9] op_sel_hi:[1,0]
	v_pk_mul_f32 v[98:99], v[94:95], s[8:9] op_sel_hi:[1,0]
	v_pk_mul_f32 v[104:105], v[88:89], s[8:9] op_sel_hi:[1,0]
	v_exp_f32_e32 v100, v100
	v_exp_f32_e32 v104, v104
	v_exp_f32_e32 v101, v101
	v_exp_f32_e32 v98, v98
	v_exp_f32_e32 v99, v99
	v_exp_f32_e32 v102, v102
	v_exp_f32_e32 v103, v103
	v_exp_f32_e32 v105, v105
	v_pk_add_f32 v[98:99], v[98:99], 1.0 op_sel_hi:[1,0]
	v_pk_add_f32 v[100:101], v[100:101], 1.0 op_sel_hi:[1,0]
	v_pk_add_f32 v[102:103], v[102:103], 1.0 op_sel_hi:[1,0]
	v_pk_add_f32 v[104:105], v[104:105], 1.0 op_sel_hi:[1,0]
	v_rcp_f32_e32 v100, v100
	v_rcp_f32_e32 v104, v104
	v_rcp_f32_e32 v101, v101
	v_rcp_f32_e32 v105, v105
	v_rcp_f32_e32 v98, v98
	v_rcp_f32_e32 v102, v102
	v_rcp_f32_e32 v99, v99
	v_rcp_f32_e32 v103, v103
	v_or_b32_e32 v96, 32, v166
	v_pk_mul_f32 v[86:87], v[86:87], v[94:95]
	v_pk_mul_f32 v[84:85], v[84:85], v[92:93]
	v_pk_mul_f32 v[82:83], v[82:83], v[90:91]
	v_pk_mul_f32 v[80:81], v[80:81], v[88:89]
	v_mad_i64_i32 v[96:97], s[34:35], v96, s51, v[144:145]
	v_pk_mul_f32 v[86:87], v[86:87], v[98:99]
	v_pk_mul_f32 v[84:85], v[84:85], v[100:101]
	v_pk_mul_f32 v[88:89], v[82:83], v[102:103]
	v_pk_mul_f32 v[82:83], v[80:81], v[104:105]
	v_lshl_add_u64 v[96:97], v[96:97], 0, v[146:147]
	v_cvt_pk_bf16_f32 v80, v84, v85
	v_cvt_pk_bf16_f32 v81, v86, v87
	v_cvt_pk_bf16_f32 v82, v82, v83
	v_cvt_pk_bf16_f32 v83, v88, v89
	global_store_dwordx4 v[96:97], v[80:83], off sc1
	v_pk_mul_f32 v[84:85], v[76:77], s[8:9] op_sel_hi:[1,0]
	v_pk_mul_f32 v[86:87], v[74:75], s[8:9] op_sel_hi:[1,0]
	v_pk_mul_f32 v[82:83], v[78:79], s[8:9] op_sel_hi:[1,0]
	v_pk_mul_f32 v[88:89], v[72:73], s[8:9] op_sel_hi:[1,0]
	v_exp_f32_e32 v84, v84
	v_exp_f32_e32 v88, v88
	v_exp_f32_e32 v85, v85
	v_exp_f32_e32 v82, v82
	v_exp_f32_e32 v83, v83
	v_exp_f32_e32 v86, v86
	v_exp_f32_e32 v87, v87
	v_exp_f32_e32 v89, v89
	v_pk_add_f32 v[82:83], v[82:83], 1.0 op_sel_hi:[1,0]
	v_pk_add_f32 v[84:85], v[84:85], 1.0 op_sel_hi:[1,0]
	v_pk_add_f32 v[86:87], v[86:87], 1.0 op_sel_hi:[1,0]
	v_pk_add_f32 v[88:89], v[88:89], 1.0 op_sel_hi:[1,0]
	v_rcp_f32_e32 v84, v84
	v_rcp_f32_e32 v88, v88
	v_rcp_f32_e32 v85, v85
	v_rcp_f32_e32 v89, v89
	v_rcp_f32_e32 v82, v82
	v_rcp_f32_e32 v86, v86
	v_rcp_f32_e32 v83, v83
	v_rcp_f32_e32 v87, v87
	v_or_b32_e32 v80, 48, v166
	v_pk_mul_f32 v[70:71], v[70:71], v[78:79]
	v_pk_mul_f32 v[68:69], v[68:69], v[76:77]
	v_pk_mul_f32 v[66:67], v[66:67], v[74:75]
	v_pk_mul_f32 v[64:65], v[64:65], v[72:73]
	v_mad_i64_i32 v[80:81], s[34:35], v80, s51, v[144:145]
	v_pk_mul_f32 v[70:71], v[70:71], v[82:83]
	v_pk_mul_f32 v[68:69], v[68:69], v[84:85]
	v_pk_mul_f32 v[72:73], v[66:67], v[86:87]
	v_pk_mul_f32 v[66:67], v[64:65], v[88:89]
	v_lshl_add_u64 v[80:81], v[80:81], 0, v[146:147]
	v_cvt_pk_bf16_f32 v64, v68, v69
	v_cvt_pk_bf16_f32 v65, v70, v71
	v_cvt_pk_bf16_f32 v66, v66, v67
	v_cvt_pk_bf16_f32 v67, v72, v73
	global_store_dwordx4 v[80:81], v[64:67], off sc1
	v_pk_mul_f32 v[68:69], v[60:61], s[8:9] op_sel_hi:[1,0]
	v_pk_mul_f32 v[70:71], v[58:59], s[8:9] op_sel_hi:[1,0]
	v_pk_mul_f32 v[66:67], v[62:63], s[8:9] op_sel_hi:[1,0]
	v_pk_mul_f32 v[72:73], v[56:57], s[8:9] op_sel_hi:[1,0]
	v_exp_f32_e32 v68, v68
	v_exp_f32_e32 v72, v72
	v_exp_f32_e32 v69, v69
	v_exp_f32_e32 v66, v66
	v_exp_f32_e32 v67, v67
	v_exp_f32_e32 v70, v70
	v_exp_f32_e32 v71, v71
	v_exp_f32_e32 v73, v73
	v_pk_add_f32 v[66:67], v[66:67], 1.0 op_sel_hi:[1,0]
	v_pk_add_f32 v[68:69], v[68:69], 1.0 op_sel_hi:[1,0]
	v_pk_add_f32 v[70:71], v[70:71], 1.0 op_sel_hi:[1,0]
	v_pk_add_f32 v[72:73], v[72:73], 1.0 op_sel_hi:[1,0]
	v_rcp_f32_e32 v68, v68
	v_rcp_f32_e32 v72, v72
	v_rcp_f32_e32 v69, v69
	v_rcp_f32_e32 v73, v73
	v_rcp_f32_e32 v66, v66
	v_rcp_f32_e32 v70, v70
	v_rcp_f32_e32 v67, v67
	v_rcp_f32_e32 v71, v71
	v_add_u32_e32 v64, 0x80, v166
	v_pk_mul_f32 v[54:55], v[54:55], v[62:63]
	v_pk_mul_f32 v[52:53], v[52:53], v[60:61]
	v_pk_mul_f32 v[50:51], v[50:51], v[58:59]
	v_pk_mul_f32 v[48:49], v[48:49], v[56:57]
	v_mad_i64_i32 v[64:65], s[34:35], v64, s51, v[144:145]
	v_pk_mul_f32 v[54:55], v[54:55], v[66:67]
	v_pk_mul_f32 v[52:53], v[52:53], v[68:69]
	v_pk_mul_f32 v[56:57], v[50:51], v[70:71]
	v_pk_mul_f32 v[50:51], v[48:49], v[72:73]
	v_lshl_add_u64 v[64:65], v[64:65], 0, v[146:147]
	v_cvt_pk_bf16_f32 v48, v52, v53
	v_cvt_pk_bf16_f32 v49, v54, v55
	v_cvt_pk_bf16_f32 v50, v50, v51
	v_cvt_pk_bf16_f32 v51, v56, v57
	global_store_dwordx4 v[64:65], v[48:51], off sc1
	v_pk_mul_f32 v[52:53], v[44:45], s[8:9] op_sel_hi:[1,0]
	v_pk_mul_f32 v[54:55], v[42:43], s[8:9] op_sel_hi:[1,0]
	v_pk_mul_f32 v[50:51], v[46:47], s[8:9] op_sel_hi:[1,0]
	v_pk_mul_f32 v[56:57], v[40:41], s[8:9] op_sel_hi:[1,0]
	v_exp_f32_e32 v52, v52
	v_exp_f32_e32 v56, v56
	v_exp_f32_e32 v53, v53
	v_exp_f32_e32 v50, v50
	v_exp_f32_e32 v51, v51
	v_exp_f32_e32 v54, v54
	v_exp_f32_e32 v55, v55
	v_exp_f32_e32 v57, v57
	v_pk_add_f32 v[50:51], v[50:51], 1.0 op_sel_hi:[1,0]
	v_pk_add_f32 v[52:53], v[52:53], 1.0 op_sel_hi:[1,0]
	v_pk_add_f32 v[54:55], v[54:55], 1.0 op_sel_hi:[1,0]
	v_pk_add_f32 v[56:57], v[56:57], 1.0 op_sel_hi:[1,0]
	v_rcp_f32_e32 v52, v52
	v_rcp_f32_e32 v56, v56
	v_rcp_f32_e32 v53, v53
	v_rcp_f32_e32 v57, v57
	v_rcp_f32_e32 v50, v50
	v_rcp_f32_e32 v54, v54
	v_rcp_f32_e32 v51, v51
	v_rcp_f32_e32 v55, v55
	v_add_u32_e32 v48, 0x90, v166
	v_pk_mul_f32 v[38:39], v[38:39], v[46:47]
	v_pk_mul_f32 v[36:37], v[36:37], v[44:45]
	v_pk_mul_f32 v[34:35], v[34:35], v[42:43]
	v_pk_mul_f32 v[32:33], v[32:33], v[40:41]
	v_mad_i64_i32 v[48:49], s[34:35], v48, s51, v[144:145]
	v_pk_mul_f32 v[38:39], v[38:39], v[50:51]
	v_pk_mul_f32 v[36:37], v[36:37], v[52:53]
	v_pk_mul_f32 v[40:41], v[34:35], v[54:55]
	v_pk_mul_f32 v[34:35], v[32:33], v[56:57]
	v_lshl_add_u64 v[48:49], v[48:49], 0, v[146:147]
	v_cvt_pk_bf16_f32 v32, v36, v37
	v_cvt_pk_bf16_f32 v33, v38, v39
	v_cvt_pk_bf16_f32 v34, v34, v35
	v_cvt_pk_bf16_f32 v35, v40, v41
	global_store_dwordx4 v[48:49], v[32:35], off sc1
	v_pk_mul_f32 v[36:37], v[28:29], s[8:9] op_sel_hi:[1,0]
	v_pk_mul_f32 v[38:39], v[26:27], s[8:9] op_sel_hi:[1,0]
	v_pk_mul_f32 v[34:35], v[30:31], s[8:9] op_sel_hi:[1,0]
	v_pk_mul_f32 v[40:41], v[24:25], s[8:9] op_sel_hi:[1,0]
	v_exp_f32_e32 v36, v36
	v_exp_f32_e32 v40, v40
	v_exp_f32_e32 v37, v37
	v_exp_f32_e32 v34, v34
	v_exp_f32_e32 v35, v35
	v_exp_f32_e32 v38, v38
	v_exp_f32_e32 v39, v39
	v_exp_f32_e32 v41, v41
	v_pk_add_f32 v[34:35], v[34:35], 1.0 op_sel_hi:[1,0]
	v_pk_add_f32 v[36:37], v[36:37], 1.0 op_sel_hi:[1,0]
	v_pk_add_f32 v[38:39], v[38:39], 1.0 op_sel_hi:[1,0]
	v_pk_add_f32 v[40:41], v[40:41], 1.0 op_sel_hi:[1,0]
	v_rcp_f32_e32 v36, v36
	v_rcp_f32_e32 v40, v40
	v_rcp_f32_e32 v37, v37
	v_rcp_f32_e32 v41, v41
	v_rcp_f32_e32 v34, v34
	v_rcp_f32_e32 v38, v38
	v_rcp_f32_e32 v35, v35
	v_rcp_f32_e32 v39, v39
	v_add_u32_e32 v32, 0xa0, v166
	v_pk_mul_f32 v[22:23], v[22:23], v[30:31]
	v_pk_mul_f32 v[20:21], v[20:21], v[28:29]
	v_pk_mul_f32 v[18:19], v[18:19], v[26:27]
	v_pk_mul_f32 v[16:17], v[16:17], v[24:25]
	v_mad_i64_i32 v[32:33], s[34:35], v32, s51, v[144:145]
	v_pk_mul_f32 v[22:23], v[22:23], v[34:35]
	v_pk_mul_f32 v[20:21], v[20:21], v[36:37]
	v_pk_mul_f32 v[24:25], v[18:19], v[38:39]
	v_pk_mul_f32 v[18:19], v[16:17], v[40:41]
	v_lshl_add_u64 v[32:33], v[32:33], 0, v[146:147]
	v_cvt_pk_bf16_f32 v16, v20, v21
	v_cvt_pk_bf16_f32 v17, v22, v23
	v_cvt_pk_bf16_f32 v18, v18, v19
	v_cvt_pk_bf16_f32 v19, v24, v25
	global_store_dwordx4 v[32:33], v[16:19], off sc1
	v_pk_mul_f32 v[20:21], v[12:13], s[8:9] op_sel_hi:[1,0]
	v_pk_mul_f32 v[22:23], v[10:11], s[8:9] op_sel_hi:[1,0]
	v_pk_mul_f32 v[18:19], v[14:15], s[8:9] op_sel_hi:[1,0]
	v_pk_mul_f32 v[24:25], v[8:9], s[8:9] op_sel_hi:[1,0]
	v_exp_f32_e32 v20, v20
	v_exp_f32_e32 v24, v24
	v_exp_f32_e32 v21, v21
	v_exp_f32_e32 v18, v18
	v_exp_f32_e32 v19, v19
	v_exp_f32_e32 v22, v22
	v_exp_f32_e32 v23, v23
	v_exp_f32_e32 v25, v25
	v_pk_add_f32 v[18:19], v[18:19], 1.0 op_sel_hi:[1,0]
	v_pk_add_f32 v[20:21], v[20:21], 1.0 op_sel_hi:[1,0]
	v_pk_add_f32 v[22:23], v[22:23], 1.0 op_sel_hi:[1,0]
	v_pk_add_f32 v[24:25], v[24:25], 1.0 op_sel_hi:[1,0]
	v_rcp_f32_e32 v20, v20
	v_rcp_f32_e32 v24, v24
	v_rcp_f32_e32 v21, v21
	v_rcp_f32_e32 v25, v25
	v_rcp_f32_e32 v18, v18
	v_rcp_f32_e32 v22, v22
	v_rcp_f32_e32 v19, v19
	v_rcp_f32_e32 v23, v23
	v_add_u32_e32 v16, 0xb0, v166
	v_pk_mul_f32 v[6:7], v[6:7], v[14:15]
	v_pk_mul_f32 v[4:5], v[4:5], v[12:13]
	v_pk_mul_f32 v[2:3], v[2:3], v[10:11]
	v_pk_mul_f32 v[0:1], v[0:1], v[8:9]
	v_mad_i64_i32 v[16:17], s[34:35], v16, s51, v[144:145]
	v_pk_mul_f32 v[6:7], v[6:7], v[18:19]
	v_pk_mul_f32 v[4:5], v[4:5], v[20:21]
	v_pk_mul_f32 v[8:9], v[2:3], v[22:23]
	v_pk_mul_f32 v[2:3], v[0:1], v[24:25]
	v_lshl_add_u64 v[16:17], v[16:17], 0, v[146:147]
	v_cvt_pk_bf16_f32 v0, v4, v5
	v_cvt_pk_bf16_f32 v1, v6, v7
	v_cvt_pk_bf16_f32 v2, v2, v3
	v_cvt_pk_bf16_f32 v3, v8, v9
	s_andn2_b64 vcc, exec, s[0:1]
	s_mov_b64 s[0:1], -1
	global_store_dwordx4 v[16:17], v[0:3], off sc1
	s_cbranch_vccnz .LBB0_1291
	s_andn2_b64 vcc, exec, s[2:3]
	s_cbranch_vccnz .LBB0_1290
	s_barrier
	s_branch .LBB0_1290

.LBB0_1315:
	s_waitcnt vmcnt(22)
	v_cvt_pk_bf16_f32 v64, v64, v68
	v_cvt_pk_bf16_f32 v65, v65, v69
	ds_write2_b32 v145, v64, v65 offset1:32
	v_cvt_pk_bf16_f32 v64, v66, v70
	v_cvt_pk_bf16_f32 v65, v67, v71
	ds_write2_b32 v145, v64, v65 offset0:64 offset1:96
	s_waitcnt vmcnt(20)
	v_cvt_pk_bf16_f32 v64, v72, v76
	v_cvt_pk_bf16_f32 v65, v73, v77
	ds_write2_b32 v146, v64, v65 offset1:32
	v_cvt_pk_bf16_f32 v64, v74, v78
	v_cvt_pk_bf16_f32 v65, v75, v79
	ds_write2_b32 v146, v64, v65 offset0:64 offset1:96
	s_waitcnt vmcnt(18)
	v_cvt_pk_bf16_f32 v64, v80, v84
	v_cvt_pk_bf16_f32 v65, v81, v85
	ds_write2_b32 v147, v64, v65 offset1:32
	v_cvt_pk_bf16_f32 v64, v82, v86
	v_cvt_pk_bf16_f32 v65, v83, v87
	ds_write2_b32 v147, v64, v65 offset0:64 offset1:96
	s_waitcnt vmcnt(16)
	v_cvt_pk_bf16_f32 v64, v88, v92
	v_cvt_pk_bf16_f32 v65, v89, v93
	ds_write2_b32 v148, v64, v65 offset1:32
	v_cvt_pk_bf16_f32 v64, v90, v94
	v_cvt_pk_bf16_f32 v65, v91, v95
	ds_write2_b32 v148, v64, v65 offset0:64 offset1:96
	s_waitcnt vmcnt(14)
	v_cvt_pk_bf16_f32 v64, v96, v100
	v_cvt_pk_bf16_f32 v65, v97, v101
	ds_write2_b32 v149, v64, v65 offset1:32
	v_cvt_pk_bf16_f32 v64, v98, v102
	v_cvt_pk_bf16_f32 v65, v99, v103
	ds_write2_b32 v149, v64, v65 offset0:64 offset1:96
	s_waitcnt vmcnt(12)
	v_cvt_pk_bf16_f32 v64, v104, v108
	v_cvt_pk_bf16_f32 v65, v105, v109
	ds_write2_b32 v150, v64, v65 offset1:32
	v_cvt_pk_bf16_f32 v64, v106, v110
	v_cvt_pk_bf16_f32 v65, v107, v111
	ds_write2_b32 v150, v64, v65 offset0:64 offset1:96
	s_waitcnt vmcnt(10)
	v_cvt_pk_bf16_f32 v64, v112, v116
	v_cvt_pk_bf16_f32 v65, v113, v117
	ds_write2_b32 v151, v64, v65 offset1:32
	v_cvt_pk_bf16_f32 v64, v114, v118
	v_cvt_pk_bf16_f32 v65, v115, v119
	ds_write2_b32 v151, v64, v65 offset0:64 offset1:96
	s_waitcnt vmcnt(8)
	v_cvt_pk_bf16_f32 v64, v120, v124
	v_cvt_pk_bf16_f32 v65, v121, v125
	ds_write2_b32 v152, v64, v65 offset1:32
	v_cvt_pk_bf16_f32 v64, v122, v126
	v_cvt_pk_bf16_f32 v65, v123, v127
	ds_write2_b32 v152, v64, v65 offset0:64 offset1:96
	s_sub_i32 s35, 0, s39
	s_waitcnt lgkmcnt(0)
	s_add_i32 s35, s35, s60
	ds_read_b128 v[64:67], v153
	v_add_u32_e32 v76, s35, v131
	v_add_u32_e32 v68, 0xfffffde0, v76
	v_mov_b64_e32 v[72:73], s[28:29]
	s_ashr_i32 s39, s38, 31
	v_mad_i64_i32 v[68:69], s[64:65], v68, s58, v[72:73]
	s_lshl_b64 s[38:39], s[38:39], 1
	v_lshl_add_u64 v[68:69], v[68:69], 0, s[38:39]
	v_lshl_add_u64 v[74:75], v[68:69], 0, v[128:129]
	ds_read_b128 v[68:71], v154
	s_waitcnt lgkmcnt(1)
	global_store_dwordx4 v[74:75], v[64:67], off sc1
	s_add_i32 s59, s59, 2
	s_nop 0
	v_add_u32_e32 v64, 0xfffffde8, v76
	v_mad_i64_i32 v[64:65], s[64:65], v64, s58, v[72:73]
	v_lshl_add_u64 v[64:65], v[64:65], 0, s[38:39]
	v_lshl_add_u64 v[64:65], v[64:65], 0, v[128:129]
	s_waitcnt lgkmcnt(0)
	global_store_dwordx4 v[64:65], v[68:71], off sc1
	ds_read_b128 v[64:67], v155
	s_nop 0
	v_add_u32_e32 v68, 0xfffffdf0, v76
	v_mad_i64_i32 v[68:69], s[64:65], v68, s58, v[72:73]
	v_lshl_add_u64 v[68:69], v[68:69], 0, s[38:39]
	v_lshl_add_u64 v[74:75], v[68:69], 0, v[128:129]
	ds_read_b128 v[68:71], v156
	s_waitcnt lgkmcnt(1)
	global_store_dwordx4 v[74:75], v[64:67], off sc1
	s_nop 1
	v_add_u32_e32 v64, 0xfffffdf8, v76
	v_mad_i64_i32 v[64:65], s[64:65], v64, s58, v[72:73]
	v_lshl_add_u64 v[64:65], v[64:65], 0, s[38:39]
	v_lshl_add_u64 v[64:65], v[64:65], 0, v[128:129]
	s_waitcnt lgkmcnt(0)
	global_store_dwordx4 v[64:65], v[68:71], off sc1
	ds_read_b128 v[64:67], v157
	s_nop 0
	v_add_u32_e32 v68, 0xfffffe00, v76
	v_mad_i64_i32 v[68:69], s[64:65], v68, s58, v[72:73]
	v_lshl_add_u64 v[68:69], v[68:69], 0, s[38:39]
	v_lshl_add_u64 v[74:75], v[68:69], 0, v[128:129]
	ds_read_b128 v[68:71], v158
	s_waitcnt lgkmcnt(1)
	global_store_dwordx4 v[74:75], v[64:67], off sc1
	s_nop 1
	v_add_u32_e32 v64, 0xfffffe08, v76
	v_mad_i64_i32 v[64:65], s[64:65], v64, s58, v[72:73]
	v_lshl_add_u64 v[64:65], v[64:65], 0, s[38:39]
	v_lshl_add_u64 v[64:65], v[64:65], 0, v[128:129]
	s_waitcnt lgkmcnt(0)
	global_store_dwordx4 v[64:65], v[68:71], off sc1
	ds_read_b128 v[64:67], v159
	s_nop 0
	v_add_u32_e32 v68, 0xfffffe10, v76
	v_mad_i64_i32 v[68:69], s[64:65], v68, s58, v[72:73]
	v_lshl_add_u64 v[68:69], v[68:69], 0, s[38:39]
	v_lshl_add_u64 v[74:75], v[68:69], 0, v[128:129]
	ds_read_b128 v[68:71], v160
	s_waitcnt lgkmcnt(1)
	global_store_dwordx4 v[74:75], v[64:67], off sc1
	s_nop 1
	v_add_u32_e32 v64, 0xfffffe18, v76
	v_mad_i64_i32 v[64:65], s[64:65], v64, s58, v[72:73]
	v_lshl_add_u64 v[64:65], v[64:65], 0, s[38:39]
	v_lshl_add_u64 v[64:65], v[64:65], 0, v[128:129]
	s_waitcnt lgkmcnt(0)
	global_store_dwordx4 v[64:65], v[68:71], off sc1
	s_waitcnt lgkmcnt(0)
	s_addk_i32 s60, 0x400
	s_add_i32 s61, s61, 16
	s_and_b64 vcc, exec, s[40:41]
	s_cbranch_vccnz .LBB0_1307
.LBB0_1316:
	s_add_i32 s35, s61, -8
	s_ashr_i32 s37, s35, 31
	s_lshr_b32 s37, s37, 26
	s_add_i32 s35, s35, s37
	s_lshl_b32 s37, s35, 6
	s_and_b32 s38, s35, 0xffffffc0
	s_and_b32 s39, s37, 0xfffff000
	v_add_u32_e32 v64, s38, v136
	s_sub_i32 s37, s60, s39
	v_ashrrev_i32_e32 v65, 31, v64
	s_add_i32 s40, s37, 0xfffffde0
	v_lshlrev_b64 v[64:65], 14, v[64:65]
	v_lshl_add_u64 v[64:65], s[22:23], 0, v[64:65]
	s_ashr_i32 s41, s40, 31
	v_lshl_add_u64 v[64:65], s[40:41], 2, v[64:65]
	v_lshl_add_u64 v[120:121], v[64:65], 0, v[134:135]
	v_add_co_u32_e32 v68, vcc, s43, v120
	s_nop 1
	v_addc_co_u32_e32 v69, vcc, 0, v121, vcc
	v_add_co_u32_e32 v72, vcc, s44, v120
	global_load_dwordx4 v[64:67], v[120:121], off nt
	s_nop 0
	global_load_dwordx4 v[68:71], v[68:69], off nt
	v_addc_co_u32_e32 v73, vcc, 0, v121, vcc
	v_add_co_u32_e32 v76, vcc, s45, v120
	s_nop 1
	v_addc_co_u32_e32 v77, vcc, 0, v121, vcc
	v_add_co_u32_e32 v80, vcc, s46, v120
	global_load_dwordx4 v[72:75], v[72:73], off nt
	s_nop 0
	global_load_dwordx4 v[76:79], v[76:77], off nt
	v_addc_co_u32_e32 v81, vcc, 0, v121, vcc
	v_add_co_u32_e32 v84, vcc, s47, v120
	s_nop 1
	v_addc_co_u32_e32 v85, vcc, 0, v121, vcc
	v_add_co_u32_e32 v88, vcc, s48, v120
	global_load_dwordx4 v[80:83], v[80:81], off nt
	s_nop 0
	global_load_dwordx4 v[84:87], v[84:85], off nt
	v_addc_co_u32_e32 v89, vcc, 0, v121, vcc
	v_add_co_u32_e32 v92, vcc, s49, v120
	s_nop 1
	v_addc_co_u32_e32 v93, vcc, 0, v121, vcc
	v_add_co_u32_e32 v96, vcc, s50, v120
	global_load_dwordx4 v[88:91], v[88:89], off nt
	s_nop 0
	global_load_dwordx4 v[92:95], v[92:93], off nt
	v_addc_co_u32_e32 v97, vcc, 0, v121, vcc
	v_add_co_u32_e32 v100, vcc, s51, v120
	s_nop 1
	v_addc_co_u32_e32 v101, vcc, 0, v121, vcc
	v_add_co_u32_e32 v104, vcc, s52, v120
	global_load_dwordx4 v[96:99], v[96:97], off nt
	s_nop 0
	global_load_dwordx4 v[100:103], v[100:101], off nt
	v_addc_co_u32_e32 v105, vcc, 0, v121, vcc
	v_add_co_u32_e32 v108, vcc, s53, v120
	s_nop 1
	v_addc_co_u32_e32 v109, vcc, 0, v121, vcc
	v_add_co_u32_e32 v112, vcc, s54, v120
	global_load_dwordx4 v[104:107], v[104:105], off nt
	s_nop 0
	global_load_dwordx4 v[108:111], v[108:109], off nt
	v_addc_co_u32_e32 v113, vcc, 0, v121, vcc
	v_add_co_u32_e32 v116, vcc, s55, v120
	s_nop 1
	v_addc_co_u32_e32 v117, vcc, 0, v121, vcc
	v_add_co_u32_e32 v122, vcc, s56, v120
	global_load_dwordx4 v[112:115], v[112:113], off nt
	s_nop 0
	global_load_dwordx4 v[116:119], v[116:117], off nt
	v_addc_co_u32_e32 v123, vcc, 0, v121, vcc
	v_add_co_u32_e32 v124, vcc, s57, v120
	s_nop 1
	v_addc_co_u32_e32 v125, vcc, 0, v121, vcc
	global_load_dwordx4 v[120:123], v[122:123], off nt
	s_nop 0
	global_load_dwordx4 v[124:127], v[124:125], off nt
	s_waitcnt vmcnt(30)
	v_cvt_pk_bf16_f32 v128, v0, v4
	v_cvt_pk_bf16_f32 v133, v1, v5
	ds_write2_b32 v145, v128, v133 offset1:32
	v_cvt_pk_bf16_f32 v128, v2, v6
	v_cvt_pk_bf16_f32 v133, v3, v7
	ds_write2_b32 v145, v128, v133 offset0:64 offset1:96
	s_waitcnt vmcnt(28)
	v_cvt_pk_bf16_f32 v128, v8, v12
	v_cvt_pk_bf16_f32 v133, v9, v13
	ds_write2_b32 v146, v128, v133 offset1:32
	v_cvt_pk_bf16_f32 v128, v10, v14
	v_cvt_pk_bf16_f32 v133, v11, v15
	ds_write2_b32 v146, v128, v133 offset0:64 offset1:96
	s_waitcnt vmcnt(26)
	v_cvt_pk_bf16_f32 v128, v16, v20
	v_cvt_pk_bf16_f32 v133, v17, v21
	ds_write2_b32 v147, v128, v133 offset1:32
	v_cvt_pk_bf16_f32 v128, v18, v22
	v_cvt_pk_bf16_f32 v133, v19, v23
	ds_write2_b32 v147, v128, v133 offset0:64 offset1:96
	s_waitcnt vmcnt(24)
	v_cvt_pk_bf16_f32 v128, v24, v28
	v_cvt_pk_bf16_f32 v133, v25, v29
	ds_write2_b32 v148, v128, v133 offset1:32
	v_cvt_pk_bf16_f32 v128, v26, v30
	v_cvt_pk_bf16_f32 v133, v27, v31
	ds_write2_b32 v148, v128, v133 offset0:64 offset1:96
	s_waitcnt vmcnt(22)
	v_cvt_pk_bf16_f32 v128, v32, v36
	v_cvt_pk_bf16_f32 v133, v33, v37
	ds_write2_b32 v149, v128, v133 offset1:32
	v_cvt_pk_bf16_f32 v128, v34, v38
	v_cvt_pk_bf16_f32 v133, v35, v39
	ds_write2_b32 v149, v128, v133 offset0:64 offset1:96
	s_waitcnt vmcnt(20)
	v_cvt_pk_bf16_f32 v128, v40, v44
	v_cvt_pk_bf16_f32 v133, v41, v45
	ds_write2_b32 v150, v128, v133 offset1:32
	v_cvt_pk_bf16_f32 v128, v42, v46
	v_cvt_pk_bf16_f32 v133, v43, v47
	ds_write2_b32 v150, v128, v133 offset0:64 offset1:96
	s_waitcnt vmcnt(18)
	v_cvt_pk_bf16_f32 v128, v48, v52
	v_cvt_pk_bf16_f32 v133, v49, v53
	ds_write2_b32 v151, v128, v133 offset1:32
	v_cvt_pk_bf16_f32 v128, v50, v54
	v_cvt_pk_bf16_f32 v133, v51, v55
	ds_write2_b32 v151, v128, v133 offset0:64 offset1:96
	s_waitcnt vmcnt(16)
	v_cvt_pk_bf16_f32 v128, v56, v60
	v_cvt_pk_bf16_f32 v133, v57, v61
	ds_write2_b32 v152, v128, v133 offset1:32
	v_cvt_pk_bf16_f32 v128, v58, v62
	v_cvt_pk_bf16_f32 v133, v59, v63
	ds_write2_b32 v152, v128, v133 offset0:64 offset1:96
	s_sub_i32 s35, s62, 32
	s_waitcnt lgkmcnt(0)
	v_mov_b32_e32 v133, s35
	v_mov_b32_e32 v161, s34
	v_cndmask_b32_e64 v128, v133, v161, s[2:3]
	ds_read_b128 v[162:165], v153
	v_add_u32_e32 v128, v128, v131
	v_mov_b64_e32 v[170:171], s[28:29]
	v_mad_i64_i32 v[166:167], s[40:41], v128, s58, v[170:171]
	s_ashr_i32 s37, s36, 31
	s_lshl_b64 s[40:41], s[36:37], 1
	v_lshl_add_u64 v[166:167], v[166:167], 0, s[40:41]
	v_lshlrev_b32_e32 v128, 1, v130
	v_lshl_add_u64 v[172:173], v[166:167], 0, v[128:129]
	ds_read_b128 v[166:169], v154
	s_waitcnt lgkmcnt(1)
	global_store_dwordx4 v[172:173], v[162:165], off sc1
	s_nop 1
	v_cndmask_b32_e64 v162, v133, v161, s[4:5]
	v_add_u32_e32 v162, v162, v137
	v_mad_i64_i32 v[162:163], s[64:65], v162, s58, v[170:171]
	v_lshl_add_u64 v[162:163], v[162:163], 0, s[40:41]
	v_lshl_add_u64 v[162:163], v[162:163], 0, v[128:129]
	s_waitcnt lgkmcnt(0)
	global_store_dwordx4 v[162:163], v[166:169], off sc1
	ds_read_b128 v[162:165], v155
	s_nop 0
	v_cndmask_b32_e64 v166, v133, v161, s[6:7]
	v_add_u32_e32 v166, v166, v138
	v_mad_i64_i32 v[166:167], s[64:65], v166, s58, v[170:171]
	v_lshl_add_u64 v[166:167], v[166:167], 0, s[40:41]
	v_lshl_add_u64 v[172:173], v[166:167], 0, v[128:129]
	ds_read_b128 v[166:169], v156
	s_waitcnt lgkmcnt(1)
	global_store_dwordx4 v[172:173], v[162:165], off sc1
	s_nop 1
	v_cndmask_b32_e64 v162, v133, v161, s[8:9]
	v_add_u32_e32 v162, v162, v139
	v_mad_i64_i32 v[162:163], s[64:65], v162, s58, v[170:171]
	v_lshl_add_u64 v[162:163], v[162:163], 0, s[40:41]
	v_lshl_add_u64 v[162:163], v[162:163], 0, v[128:129]
	s_waitcnt lgkmcnt(0)
	global_store_dwordx4 v[162:163], v[166:169], off sc1
	ds_read_b128 v[162:165], v157
	s_nop 0
	v_cndmask_b32_e64 v166, v133, v161, s[10:11]
	v_add_u32_e32 v166, v166, v140
	v_mad_i64_i32 v[166:167], s[64:65], v166, s58, v[170:171]
	v_lshl_add_u64 v[166:167], v[166:167], 0, s[40:41]
	v_lshl_add_u64 v[172:173], v[166:167], 0, v[128:129]
	ds_read_b128 v[166:169], v158
	s_waitcnt lgkmcnt(1)
	global_store_dwordx4 v[172:173], v[162:165], off sc1
	s_nop 1
	v_cndmask_b32_e64 v162, v133, v161, s[12:13]
	v_add_u32_e32 v162, v162, v141
	v_mad_i64_i32 v[162:163], s[64:65], v162, s58, v[170:171]
	v_lshl_add_u64 v[162:163], v[162:163], 0, s[40:41]
	v_lshl_add_u64 v[162:163], v[162:163], 0, v[128:129]
	s_waitcnt lgkmcnt(0)
	global_store_dwordx4 v[162:163], v[166:169], off sc1
	ds_read_b128 v[162:165], v159
	s_nop 0
	v_cndmask_b32_e64 v166, v133, v161, s[14:15]
	v_add_u32_e32 v166, v166, v142
	v_mad_i64_i32 v[166:167], s[64:65], v166, s58, v[170:171]
	v_lshl_add_u64 v[166:167], v[166:167], 0, s[40:41]
	v_lshl_add_u64 v[172:173], v[166:167], 0, v[128:129]
	ds_read_b128 v[166:169], v160
	v_cndmask_b32_e64 v133, v133, v161, s[16:17]
	v_add_u32_e32 v133, v133, v143
	s_waitcnt lgkmcnt(1)
	global_store_dwordx4 v[172:173], v[162:165], off sc1
	s_nop 1
	v_mad_i64_i32 v[162:163], s[64:65], v133, s58, v[170:171]
	v_lshl_add_u64 v[162:163], v[162:163], 0, s[40:41]
	v_lshl_add_u64 v[162:163], v[162:163], 0, v[128:129]
	s_waitcnt lgkmcnt(0)
	global_store_dwordx4 v[162:163], v[166:169], off sc1
	s_waitcnt lgkmcnt(0)
	s_cmp_gt_u32 s59, 5
	s_cselect_b64 s[40:41], -1, 0
	s_and_b64 vcc, exec, s[40:41]
	s_cbranch_vccnz .LBB0_1315
	s_ashr_i32 s34, s61, 31
	s_lshr_b32 s34, s34, 26
	s_add_i32 s35, s61, s34
	s_lshl_b32 s34, s35, 6
	s_and_b32 s36, s35, 0xffffffc0
	s_and_b32 s34, s34, 0xfffff000
	v_add_u32_e32 v0, s36, v136
	s_sub_i32 s62, s60, s34
	v_ashrrev_i32_e32 v1, 31, v0
	s_sub_i32 s34, s62, 32
	v_lshlrev_b64 v[0:1], 14, v[0:1]
	v_lshl_add_u64 v[0:1], s[22:23], 0, v[0:1]
	s_ashr_i32 s35, s34, 31
	v_lshl_add_u64 v[0:1], s[34:35], 2, v[0:1]
	v_mov_b32_e32 v133, v129
	v_lshl_add_u64 v[56:57], v[0:1], 0, v[132:133]
	v_add_co_u32_e32 v4, vcc, s43, v56
	s_nop 1
	v_addc_co_u32_e32 v5, vcc, 0, v57, vcc
	v_add_co_u32_e32 v8, vcc, s44, v56
	global_load_dwordx4 v[0:3], v[56:57], off nt
	s_nop 0
	global_load_dwordx4 v[4:7], v[4:5], off nt
	v_addc_co_u32_e32 v9, vcc, 0, v57, vcc
	v_add_co_u32_e32 v12, vcc, s45, v56
	s_nop 1
	v_addc_co_u32_e32 v13, vcc, 0, v57, vcc
	v_add_co_u32_e32 v16, vcc, s46, v56
	global_load_dwordx4 v[8:11], v[8:9], off nt
	s_nop 0
	global_load_dwordx4 v[12:15], v[12:13], off nt
	v_addc_co_u32_e32 v17, vcc, 0, v57, vcc
	v_add_co_u32_e32 v20, vcc, s47, v56
	s_nop 1
	v_addc_co_u32_e32 v21, vcc, 0, v57, vcc
	v_add_co_u32_e32 v24, vcc, s48, v56
	global_load_dwordx4 v[16:19], v[16:17], off nt
	s_nop 0
	global_load_dwordx4 v[20:23], v[20:21], off nt
	v_addc_co_u32_e32 v25, vcc, 0, v57, vcc
	v_add_co_u32_e32 v28, vcc, s49, v56
	s_nop 1
	v_addc_co_u32_e32 v29, vcc, 0, v57, vcc
	v_add_co_u32_e32 v32, vcc, s50, v56
	global_load_dwordx4 v[24:27], v[24:25], off nt
	s_nop 0
	global_load_dwordx4 v[28:31], v[28:29], off nt
	v_addc_co_u32_e32 v33, vcc, 0, v57, vcc
	v_add_co_u32_e32 v36, vcc, s51, v56
	s_nop 1
	v_addc_co_u32_e32 v37, vcc, 0, v57, vcc
	v_add_co_u32_e32 v40, vcc, s52, v56
	global_load_dwordx4 v[32:35], v[32:33], off nt
	s_nop 0
	global_load_dwordx4 v[36:39], v[36:37], off nt
	v_addc_co_u32_e32 v41, vcc, 0, v57, vcc
	v_add_co_u32_e32 v44, vcc, s53, v56
	s_nop 1
	v_addc_co_u32_e32 v45, vcc, 0, v57, vcc
	v_add_co_u32_e32 v48, vcc, s54, v56
	global_load_dwordx4 v[40:43], v[40:41], off nt
	s_nop 0
	global_load_dwordx4 v[44:47], v[44:45], off nt
	v_addc_co_u32_e32 v49, vcc, 0, v57, vcc
	v_add_co_u32_e32 v52, vcc, 0xc4000, v56
	s_nop 1
	v_addc_co_u32_e32 v53, vcc, 0, v57, vcc
	v_add_co_u32_e32 v58, vcc, 0xe0000, v56
	global_load_dwordx4 v[48:51], v[48:49], off nt
	s_nop 0
	global_load_dwordx4 v[52:55], v[52:53], off nt
	v_addc_co_u32_e32 v59, vcc, 0, v57, vcc
	v_add_co_u32_e32 v60, vcc, 0xe4000, v56
	s_nop 1
	v_addc_co_u32_e32 v61, vcc, 0, v57, vcc
	global_load_dwordx4 v[56:59], v[58:59], off nt
	s_nop 0
	global_load_dwordx4 v[60:63], v[60:61], off nt
	s_branch .LBB0_1315

.LBB0_1412:
	v_lshl_or_b32 v148, s66, 8, v176
	v_lshl_add_u32 v146, s65, 8, v174
	s_cmp_gt_i32 s4, -1
	v_ashrrev_i32_e32 v149, 31, v148
	s_mov_b64 s[42:43], -1
	s_cbranch_scc1 .LBB0_1418
	v_lshlrev_b64 v[150:151], 1, v[148:149]
	v_ashrrev_i32_e32 v147, 31, v146
	v_lshl_add_u64 v[128:129], v[148:149], 2, s[8:9]
	v_lshl_add_u64 v[168:169], s[80:81], 0, v[150:151]
	v_lshlrev_b64 v[170:171], 13, v[146:147]
	global_load_dwordx4 v[152:155], v[128:129], off offset:16
	global_load_dwordx4 v[156:159], v[128:129], off
	global_load_dwordx4 v[180:183], v[128:129], off offset:528
	global_load_dwordx4 v[184:187], v[128:129], off offset:512
	v_lshl_add_u64 v[128:129], v[168:169], 0, v[170:171]
	global_load_dwordx4 v[188:191], v[128:129], off
	global_load_dwordx4 v[192:195], v[128:129], off offset:256
	v_or_b32_e32 v128, 16, v146
	v_ashrrev_i32_e32 v129, 31, v128
	v_lshlrev_b64 v[218:219], 13, v[128:129]
	v_lshl_add_u64 v[128:129], v[168:169], 0, v[218:219]
	global_load_dwordx4 v[196:199], v[128:129], off
	global_load_dwordx4 v[202:205], v[128:129], off offset:256
	v_or_b32_e32 v128, 32, v146
	v_ashrrev_i32_e32 v129, 31, v128
	v_lshlrev_b64 v[220:221], 13, v[128:129]
	v_lshl_add_u64 v[128:129], v[168:169], 0, v[220:221]
	global_load_dwordx4 v[206:209], v[128:129], off
	global_load_dwordx4 v[210:213], v[128:129], off offset:256
	v_or_b32_e32 v128, 48, v146
	v_ashrrev_i32_e32 v129, 31, v128
	v_lshlrev_b64 v[172:173], 13, v[128:129]
	v_lshl_add_u64 v[128:129], v[168:169], 0, v[172:173]
	global_load_dwordx4 v[214:217], v[128:129], off
	s_nop 0
	global_load_dwordx4 v[128:131], v[128:129], off offset:256
	s_waitcnt vmcnt(0)
	v_pk_mul_f32 v[160:161], v[154:155], 0.5 op_sel_hi:[1,0]
	v_pk_mul_f32 v[164:165], v[158:159], 0.5 op_sel_hi:[1,0]
	v_pk_mul_f32 v[166:167], v[156:157], 0.5 op_sel_hi:[1,0]
	v_pk_mul_f32 v[162:163], v[152:153], 0.5 op_sel_hi:[1,0]
	v_pk_mul_f32 v[156:157], v[186:187], 0.5 op_sel_hi:[1,0]
	v_pk_mul_f32 v[158:159], v[184:185], 0.5 op_sel_hi:[1,0]
	v_pk_mul_f32 v[152:153], v[182:183], 0.5 op_sel_hi:[1,0]
	v_pk_mul_f32 v[154:155], v[180:181], 0.5 op_sel_hi:[1,0]
	v_lshlrev_b32_e32 v180, 16, v188
	v_and_b32_e32 v181, 0xffff0000, v188
	v_lshlrev_b32_e32 v182, 16, v189
	v_and_b32_e32 v183, 0xffff0000, v189
	v_lshlrev_b32_e32 v184, 16, v190
	v_and_b32_e32 v185, 0xffff0000, v190
	v_lshlrev_b32_e32 v186, 16, v191
	v_and_b32_e32 v187, 0xffff0000, v191
	v_pk_mul_f32 v[180:181], v[180:181], s[16:17] op_sel_hi:[1,0]
	v_pk_mul_f32 v[182:183], v[182:183], s[16:17] op_sel_hi:[1,0]
	v_pk_mul_f32 v[184:185], v[184:185], s[16:17] op_sel_hi:[1,0]
	v_pk_fma_f32 v[182:183], v[126:127], v[164:165], v[182:183]
	v_pk_fma_f32 v[180:181], v[124:125], v[166:167], v[180:181]
	v_pk_mul_f32 v[186:187], v[186:187], s[16:17] op_sel_hi:[1,0]
	v_pk_fma_f32 v[184:185], v[120:121], v[162:163], v[184:185]
	v_pk_fma_f32 v[186:187], v[122:123], v[160:161], v[186:187]
	v_cvt_pk_bf16_f32 v180, v180, v181
	v_cvt_pk_bf16_f32 v181, v182, v183
	v_cvt_pk_bf16_f32 v182, v184, v185
	v_lshl_add_u64 v[184:185], s[20:21], 0, v[170:171]
	v_cvt_pk_bf16_f32 v183, v186, v187
	v_lshl_add_u64 v[184:185], v[184:185], 0, v[150:151]
	global_store_dwordx4 v[184:185], v[180:183], off sc1
	v_lshlrev_b32_e32 v186, 16, v194
	v_and_b32_e32 v187, 0xffff0000, v194
	v_lshlrev_b32_e32 v180, 16, v192
	v_and_b32_e32 v181, 0xffff0000, v192
	v_lshlrev_b32_e32 v182, 16, v193
	v_and_b32_e32 v183, 0xffff0000, v193
	v_lshlrev_b32_e32 v188, 16, v195
	v_and_b32_e32 v189, 0xffff0000, v195
	v_pk_mul_f32 v[180:181], v[180:181], s[16:17] op_sel_hi:[1,0]
	v_pk_mul_f32 v[182:183], v[182:183], s[16:17] op_sel_hi:[1,0]
	v_pk_mul_f32 v[186:187], v[186:187], s[16:17] op_sel_hi:[1,0]
	v_pk_mul_f32 v[188:189], v[188:189], s[16:17] op_sel_hi:[1,0]
	v_pk_fma_f32 v[182:183], v[118:119], v[156:157], v[182:183]
	v_pk_fma_f32 v[180:181], v[116:117], v[158:159], v[180:181]
	v_pk_fma_f32 v[188:189], v[114:115], v[152:153], v[188:189]
	v_pk_fma_f32 v[186:187], v[112:113], v[154:155], v[186:187]
	v_cvt_pk_bf16_f32 v180, v180, v181
	v_cvt_pk_bf16_f32 v181, v182, v183
	v_cvt_pk_bf16_f32 v182, v186, v187
	v_cvt_pk_bf16_f32 v183, v188, v189
	global_store_dwordx4 v[184:185], v[180:183], off offset:256 sc1
	v_lshlrev_b32_e32 v184, 16, v198
	v_and_b32_e32 v185, 0xffff0000, v198
	v_lshlrev_b32_e32 v180, 16, v196
	v_and_b32_e32 v181, 0xffff0000, v196
	v_lshlrev_b32_e32 v182, 16, v197
	v_and_b32_e32 v183, 0xffff0000, v197
	v_lshlrev_b32_e32 v186, 16, v199
	v_and_b32_e32 v187, 0xffff0000, v199
	v_pk_mul_f32 v[180:181], v[180:181], s[16:17] op_sel_hi:[1,0]
	v_pk_mul_f32 v[182:183], v[182:183], s[16:17] op_sel_hi:[1,0]
	v_pk_mul_f32 v[184:185], v[184:185], s[16:17] op_sel_hi:[1,0]
	v_pk_fma_f32 v[182:183], v[110:111], v[164:165], v[182:183]
	v_pk_fma_f32 v[180:181], v[108:109], v[166:167], v[180:181]
	v_pk_mul_f32 v[186:187], v[186:187], s[16:17] op_sel_hi:[1,0]
	v_pk_fma_f32 v[184:185], v[104:105], v[162:163], v[184:185]
	v_pk_fma_f32 v[186:187], v[106:107], v[160:161], v[186:187]
	v_cvt_pk_bf16_f32 v180, v180, v181
	v_cvt_pk_bf16_f32 v181, v182, v183
	v_cvt_pk_bf16_f32 v182, v184, v185
	v_lshl_add_u64 v[184:185], s[20:21], 0, v[218:219]
	v_cvt_pk_bf16_f32 v183, v186, v187
	v_lshl_add_u64 v[184:185], v[184:185], 0, v[150:151]
	global_store_dwordx4 v[184:185], v[180:183], off sc1
	v_lshlrev_b32_e32 v186, 16, v204
	v_and_b32_e32 v187, 0xffff0000, v204
	v_lshlrev_b32_e32 v180, 16, v202
	v_and_b32_e32 v181, 0xffff0000, v202
	v_lshlrev_b32_e32 v182, 16, v203
	v_and_b32_e32 v183, 0xffff0000, v203
	v_lshlrev_b32_e32 v188, 16, v205
	v_and_b32_e32 v189, 0xffff0000, v205
	v_pk_mul_f32 v[180:181], v[180:181], s[16:17] op_sel_hi:[1,0]
	v_pk_mul_f32 v[182:183], v[182:183], s[16:17] op_sel_hi:[1,0]
	v_pk_mul_f32 v[186:187], v[186:187], s[16:17] op_sel_hi:[1,0]
	v_pk_mul_f32 v[188:189], v[188:189], s[16:17] op_sel_hi:[1,0]
	v_pk_fma_f32 v[182:183], v[102:103], v[156:157], v[182:183]
	v_pk_fma_f32 v[180:181], v[100:101], v[158:159], v[180:181]
	v_pk_fma_f32 v[188:189], v[98:99], v[152:153], v[188:189]
	v_pk_fma_f32 v[186:187], v[96:97], v[154:155], v[186:187]
	v_cvt_pk_bf16_f32 v180, v180, v181
	v_cvt_pk_bf16_f32 v181, v182, v183
	v_cvt_pk_bf16_f32 v182, v186, v187
	v_cvt_pk_bf16_f32 v183, v188, v189
	global_store_dwordx4 v[184:185], v[180:183], off offset:256 sc1
	v_lshlrev_b32_e32 v184, 16, v208
	v_and_b32_e32 v185, 0xffff0000, v208
	v_lshlrev_b32_e32 v180, 16, v206
	v_and_b32_e32 v181, 0xffff0000, v206
	v_lshlrev_b32_e32 v182, 16, v207
	v_and_b32_e32 v183, 0xffff0000, v207
	v_lshlrev_b32_e32 v186, 16, v209
	v_and_b32_e32 v187, 0xffff0000, v209
	v_pk_mul_f32 v[180:181], v[180:181], s[16:17] op_sel_hi:[1,0]
	v_pk_mul_f32 v[182:183], v[182:183], s[16:17] op_sel_hi:[1,0]
	v_pk_mul_f32 v[184:185], v[184:185], s[16:17] op_sel_hi:[1,0]
	v_pk_fma_f32 v[182:183], v[94:95], v[164:165], v[182:183]
	v_pk_fma_f32 v[180:181], v[92:93], v[166:167], v[180:181]
	v_pk_mul_f32 v[186:187], v[186:187], s[16:17] op_sel_hi:[1,0]
	v_pk_fma_f32 v[184:185], v[88:89], v[162:163], v[184:185]
	v_pk_fma_f32 v[186:187], v[90:91], v[160:161], v[186:187]
	v_cvt_pk_bf16_f32 v180, v180, v181
	v_cvt_pk_bf16_f32 v181, v182, v183
	v_cvt_pk_bf16_f32 v182, v184, v185
	v_lshl_add_u64 v[184:185], s[20:21], 0, v[220:221]
	v_cvt_pk_bf16_f32 v183, v186, v187
	v_lshl_add_u64 v[184:185], v[184:185], 0, v[150:151]
	global_store_dwordx4 v[184:185], v[180:183], off sc1
	v_lshlrev_b32_e32 v186, 16, v212
	v_and_b32_e32 v187, 0xffff0000, v212
	v_lshlrev_b32_e32 v180, 16, v210
	v_and_b32_e32 v181, 0xffff0000, v210
	v_lshlrev_b32_e32 v182, 16, v211
	v_and_b32_e32 v183, 0xffff0000, v211
	v_lshlrev_b32_e32 v188, 16, v213
	v_and_b32_e32 v189, 0xffff0000, v213
	v_pk_mul_f32 v[180:181], v[180:181], s[16:17] op_sel_hi:[1,0]
	v_pk_mul_f32 v[182:183], v[182:183], s[16:17] op_sel_hi:[1,0]
	v_pk_mul_f32 v[186:187], v[186:187], s[16:17] op_sel_hi:[1,0]
	v_pk_mul_f32 v[188:189], v[188:189], s[16:17] op_sel_hi:[1,0]
	v_pk_fma_f32 v[182:183], v[86:87], v[156:157], v[182:183]
	v_pk_fma_f32 v[180:181], v[84:85], v[158:159], v[180:181]
	v_pk_fma_f32 v[188:189], v[82:83], v[152:153], v[188:189]
	v_pk_fma_f32 v[186:187], v[80:81], v[154:155], v[186:187]
	v_cvt_pk_bf16_f32 v180, v180, v181
	v_cvt_pk_bf16_f32 v181, v182, v183
	v_cvt_pk_bf16_f32 v182, v186, v187
	v_cvt_pk_bf16_f32 v183, v188, v189
	global_store_dwordx4 v[184:185], v[180:183], off offset:256 sc1
	v_lshlrev_b32_e32 v184, 16, v216
	v_and_b32_e32 v185, 0xffff0000, v216
	v_lshlrev_b32_e32 v180, 16, v214
	v_and_b32_e32 v181, 0xffff0000, v214
	v_lshlrev_b32_e32 v182, 16, v215
	v_and_b32_e32 v183, 0xffff0000, v215
	v_lshlrev_b32_e32 v186, 16, v217
	v_and_b32_e32 v187, 0xffff0000, v217
	v_pk_mul_f32 v[180:181], v[180:181], s[16:17] op_sel_hi:[1,0]
	v_pk_mul_f32 v[182:183], v[182:183], s[16:17] op_sel_hi:[1,0]
	v_pk_mul_f32 v[184:185], v[184:185], s[16:17] op_sel_hi:[1,0]
	v_pk_mul_f32 v[186:187], v[186:187], s[16:17] op_sel_hi:[1,0]
	v_pk_fma_f32 v[182:183], v[78:79], v[164:165], v[182:183]
	v_pk_fma_f32 v[180:181], v[76:77], v[166:167], v[180:181]
	v_pk_fma_f32 v[186:187], v[74:75], v[160:161], v[186:187]
	v_pk_fma_f32 v[184:185], v[72:73], v[162:163], v[184:185]
	v_lshl_add_u64 v[172:173], s[20:21], 0, v[172:173]
	v_cvt_pk_bf16_f32 v180, v180, v181
	v_cvt_pk_bf16_f32 v181, v182, v183
	v_cvt_pk_bf16_f32 v182, v184, v185
	v_cvt_pk_bf16_f32 v183, v186, v187
	v_lshl_add_u64 v[172:173], v[172:173], 0, v[150:151]
	global_store_dwordx4 v[172:173], v[180:183], off sc1
	s_nop 1
	v_lshlrev_b32_e32 v180, 16, v128
	v_and_b32_e32 v181, 0xffff0000, v128
	v_lshlrev_b32_e32 v128, 16, v129
	v_and_b32_e32 v129, 0xffff0000, v129
	v_lshlrev_b32_e32 v182, 16, v130
	v_and_b32_e32 v183, 0xffff0000, v130
	v_lshlrev_b32_e32 v130, 16, v131
	v_and_b32_e32 v131, 0xffff0000, v131
	v_pk_mul_f32 v[180:181], v[180:181], s[16:17] op_sel_hi:[1,0]
	v_pk_mul_f32 v[128:129], v[128:129], s[16:17] op_sel_hi:[1,0]
	v_pk_mul_f32 v[130:131], v[130:131], s[16:17] op_sel_hi:[1,0]
	v_pk_fma_f32 v[184:185], v[70:71], v[156:157], v[128:129]
	v_pk_fma_f32 v[128:129], v[68:69], v[158:159], v[180:181]
	v_pk_mul_f32 v[180:181], v[182:183], s[16:17] op_sel_hi:[1,0]
	v_pk_fma_f32 v[182:183], v[66:67], v[152:153], v[130:131]
	v_pk_fma_f32 v[130:131], v[64:65], v[154:155], v[180:181]
	v_cvt_pk_bf16_f32 v128, v128, v129
	v_cvt_pk_bf16_f32 v129, v184, v185
	v_cvt_pk_bf16_f32 v130, v130, v131
	v_cvt_pk_bf16_f32 v131, v182, v183
	global_store_dwordx4 v[172:173], v[128:131], off offset:256 sc1
	v_lshl_add_u64 v[172:173], v[170:171], 0, s[22:23]
	s_nop 0
	v_lshl_add_u64 v[128:129], v[168:169], 0, v[172:173]
	v_lshl_add_u64 v[210:211], v[170:171], 0, s[12:13]
	global_load_dwordx4 v[180:183], v[128:129], off
	global_load_dwordx4 v[184:187], v[128:129], off offset:256
	v_lshl_add_u64 v[128:129], v[168:169], 0, v[210:211]
	v_lshl_add_u64 v[212:213], v[170:171], 0, s[30:31]
	global_load_dwordx4 v[188:191], v[128:129], off
	global_load_dwordx4 v[192:195], v[128:129], off offset:256
	v_lshl_add_u64 v[128:129], v[168:169], 0, v[212:213]
	v_lshl_add_u64 v[170:171], v[170:171], 0, s[34:35]
	global_load_dwordx4 v[196:199], v[128:129], off
	global_load_dwordx4 v[202:205], v[128:129], off offset:256
	v_lshl_add_u64 v[128:129], v[168:169], 0, v[170:171]
	global_load_dwordx4 v[206:209], v[128:129], off
	s_nop 0
	global_load_dwordx4 v[128:131], v[128:129], off offset:256
	s_waitcnt vmcnt(0)
	v_lshlrev_b32_e32 v168, 16, v180
	v_and_b32_e32 v169, 0xffff0000, v180
	v_lshlrev_b32_e32 v180, 16, v181
	v_and_b32_e32 v181, 0xffff0000, v181
	v_lshlrev_b32_e32 v214, 16, v182
	v_and_b32_e32 v215, 0xffff0000, v182
	v_lshlrev_b32_e32 v182, 16, v183
	v_and_b32_e32 v183, 0xffff0000, v183
	v_pk_mul_f32 v[168:169], v[168:169], s[16:17] op_sel_hi:[1,0]
	v_pk_mul_f32 v[180:181], v[180:181], s[16:17] op_sel_hi:[1,0]
	v_pk_fma_f32 v[168:169], v[60:61], v[166:167], v[168:169]
	v_pk_fma_f32 v[216:217], v[62:63], v[164:165], v[180:181]
	v_pk_mul_f32 v[180:181], v[214:215], s[16:17] op_sel_hi:[1,0]
	v_pk_mul_f32 v[182:183], v[182:183], s[16:17] op_sel_hi:[1,0]
	s_nop 0
	v_pk_fma_f32 v[214:215], v[58:59], v[160:161], v[182:183]
	v_pk_fma_f32 v[182:183], v[56:57], v[162:163], v[180:181]
	v_cvt_pk_bf16_f32 v180, v168, v169
	v_lshl_add_u64 v[168:169], s[20:21], 0, v[172:173]
	v_cvt_pk_bf16_f32 v181, v216, v217
	v_cvt_pk_bf16_f32 v182, v182, v183
	v_cvt_pk_bf16_f32 v183, v214, v215
	v_lshl_add_u64 v[168:169], v[168:169], 0, v[150:151]
	global_store_dwordx4 v[168:169], v[180:183], off sc1
	v_lshlrev_b32_e32 v172, 16, v184
	v_and_b32_e32 v173, 0xffff0000, v184
	v_lshlrev_b32_e32 v180, 16, v185
	v_and_b32_e32 v181, 0xffff0000, v185
	v_lshlrev_b32_e32 v182, 16, v186
	v_and_b32_e32 v183, 0xffff0000, v186
	v_lshlrev_b32_e32 v184, 16, v187
	v_and_b32_e32 v185, 0xffff0000, v187
	v_pk_mul_f32 v[180:181], v[180:181], s[16:17] op_sel_hi:[1,0]
	v_pk_mul_f32 v[172:173], v[172:173], s[16:17] op_sel_hi:[1,0]
	v_pk_fma_f32 v[186:187], v[54:55], v[156:157], v[180:181]
	v_pk_mul_f32 v[180:181], v[182:183], s[16:17] op_sel_hi:[1,0]
	v_pk_mul_f32 v[182:183], v[184:185], s[16:17] op_sel_hi:[1,0]
	v_pk_fma_f32 v[172:173], v[52:53], v[158:159], v[172:173]
	v_pk_fma_f32 v[184:185], v[50:51], v[152:153], v[182:183]
	v_pk_fma_f32 v[182:183], v[48:49], v[154:155], v[180:181]
	v_cvt_pk_bf16_f32 v180, v172, v173
	v_cvt_pk_bf16_f32 v181, v186, v187
	v_cvt_pk_bf16_f32 v182, v182, v183
	v_cvt_pk_bf16_f32 v183, v184, v185
	global_store_dwordx4 v[168:169], v[180:183], off offset:256 sc1
	v_lshlrev_b32_e32 v168, 16, v188
	v_and_b32_e32 v169, 0xffff0000, v188
	v_lshlrev_b32_e32 v172, 16, v189
	v_and_b32_e32 v173, 0xffff0000, v189
	v_lshlrev_b32_e32 v180, 16, v190
	v_and_b32_e32 v181, 0xffff0000, v190
	v_lshlrev_b32_e32 v182, 16, v191
	v_and_b32_e32 v183, 0xffff0000, v191
	v_pk_mul_f32 v[168:169], v[168:169], s[16:17] op_sel_hi:[1,0]
	v_pk_mul_f32 v[172:173], v[172:173], s[16:17] op_sel_hi:[1,0]
	v_pk_fma_f32 v[168:169], v[44:45], v[166:167], v[168:169]
	v_pk_mul_f32 v[180:181], v[180:181], s[16:17] op_sel_hi:[1,0]
	v_pk_mul_f32 v[182:183], v[182:183], s[16:17] op_sel_hi:[1,0]
	v_pk_fma_f32 v[172:173], v[46:47], v[164:165], v[172:173]
	v_pk_fma_f32 v[184:185], v[42:43], v[160:161], v[182:183]
	v_pk_fma_f32 v[182:183], v[40:41], v[162:163], v[180:181]
	v_cvt_pk_bf16_f32 v180, v168, v169
	v_lshl_add_u64 v[168:169], s[20:21], 0, v[210:211]
	v_cvt_pk_bf16_f32 v181, v172, v173
	v_cvt_pk_bf16_f32 v182, v182, v183
	v_cvt_pk_bf16_f32 v183, v184, v185
	v_lshl_add_u64 v[168:169], v[168:169], 0, v[150:151]
	global_store_dwordx4 v[168:169], v[180:183], off sc1
	v_lshlrev_b32_e32 v172, 16, v192
	v_and_b32_e32 v173, 0xffff0000, v192
	v_lshlrev_b32_e32 v180, 16, v193
	v_and_b32_e32 v181, 0xffff0000, v193
	v_lshlrev_b32_e32 v182, 16, v194
	v_and_b32_e32 v183, 0xffff0000, v194
	v_lshlrev_b32_e32 v184, 16, v195
	v_and_b32_e32 v185, 0xffff0000, v195
	v_pk_mul_f32 v[180:181], v[180:181], s[16:17] op_sel_hi:[1,0]
	v_pk_mul_f32 v[172:173], v[172:173], s[16:17] op_sel_hi:[1,0]
	v_pk_fma_f32 v[186:187], v[38:39], v[156:157], v[180:181]
	v_pk_mul_f32 v[180:181], v[182:183], s[16:17] op_sel_hi:[1,0]
	v_pk_mul_f32 v[182:183], v[184:185], s[16:17] op_sel_hi:[1,0]
	v_pk_fma_f32 v[172:173], v[36:37], v[158:159], v[172:173]
	v_pk_fma_f32 v[184:185], v[34:35], v[152:153], v[182:183]
	v_pk_fma_f32 v[182:183], v[32:33], v[154:155], v[180:181]
	v_cvt_pk_bf16_f32 v180, v172, v173
	v_cvt_pk_bf16_f32 v181, v186, v187
	v_cvt_pk_bf16_f32 v182, v182, v183
	v_cvt_pk_bf16_f32 v183, v184, v185
	global_store_dwordx4 v[168:169], v[180:183], off offset:256 sc1
	v_lshlrev_b32_e32 v168, 16, v196
	v_and_b32_e32 v169, 0xffff0000, v196
	v_lshlrev_b32_e32 v172, 16, v197
	v_and_b32_e32 v173, 0xffff0000, v197
	v_lshlrev_b32_e32 v180, 16, v198
	v_and_b32_e32 v181, 0xffff0000, v198
	v_lshlrev_b32_e32 v182, 16, v199
	v_and_b32_e32 v183, 0xffff0000, v199
	v_pk_mul_f32 v[168:169], v[168:169], s[16:17] op_sel_hi:[1,0]
	v_pk_mul_f32 v[172:173], v[172:173], s[16:17] op_sel_hi:[1,0]
	v_pk_fma_f32 v[168:169], v[28:29], v[166:167], v[168:169]
	v_pk_mul_f32 v[180:181], v[180:181], s[16:17] op_sel_hi:[1,0]
	v_pk_mul_f32 v[182:183], v[182:183], s[16:17] op_sel_hi:[1,0]
	v_pk_fma_f32 v[172:173], v[30:31], v[164:165], v[172:173]
	v_pk_fma_f32 v[184:185], v[26:27], v[160:161], v[182:183]
	v_pk_fma_f32 v[182:183], v[24:25], v[162:163], v[180:181]
	v_cvt_pk_bf16_f32 v180, v168, v169
	v_lshl_add_u64 v[168:169], s[20:21], 0, v[212:213]
	v_cvt_pk_bf16_f32 v181, v172, v173
	v_cvt_pk_bf16_f32 v182, v182, v183
	v_cvt_pk_bf16_f32 v183, v184, v185
	v_lshl_add_u64 v[168:169], v[168:169], 0, v[150:151]
	global_store_dwordx4 v[168:169], v[180:183], off sc1
	v_lshlrev_b32_e32 v172, 16, v202
	v_and_b32_e32 v173, 0xffff0000, v202
	v_lshlrev_b32_e32 v180, 16, v203
	v_and_b32_e32 v181, 0xffff0000, v203
	v_lshlrev_b32_e32 v182, 16, v204
	v_and_b32_e32 v183, 0xffff0000, v204
	v_lshlrev_b32_e32 v184, 16, v205
	v_and_b32_e32 v185, 0xffff0000, v205
	v_pk_mul_f32 v[180:181], v[180:181], s[16:17] op_sel_hi:[1,0]
	v_pk_mul_f32 v[172:173], v[172:173], s[16:17] op_sel_hi:[1,0]
	v_pk_fma_f32 v[186:187], v[22:23], v[156:157], v[180:181]
	v_pk_mul_f32 v[180:181], v[182:183], s[16:17] op_sel_hi:[1,0]
	v_pk_mul_f32 v[182:183], v[184:185], s[16:17] op_sel_hi:[1,0]
	v_pk_fma_f32 v[172:173], v[20:21], v[158:159], v[172:173]
	v_pk_fma_f32 v[184:185], v[18:19], v[152:153], v[182:183]
	v_pk_fma_f32 v[182:183], v[16:17], v[154:155], v[180:181]
	v_cvt_pk_bf16_f32 v180, v172, v173
	v_cvt_pk_bf16_f32 v181, v186, v187
	v_cvt_pk_bf16_f32 v182, v182, v183
	v_cvt_pk_bf16_f32 v183, v184, v185
	global_store_dwordx4 v[168:169], v[180:183], off offset:256 sc1
	v_lshlrev_b32_e32 v168, 16, v206
	v_and_b32_e32 v169, 0xffff0000, v206
	v_lshlrev_b32_e32 v172, 16, v207
	v_and_b32_e32 v173, 0xffff0000, v207
	v_lshlrev_b32_e32 v180, 16, v208
	v_and_b32_e32 v181, 0xffff0000, v208
	v_lshlrev_b32_e32 v182, 16, v209
	v_and_b32_e32 v183, 0xffff0000, v209
	v_pk_mul_f32 v[168:169], v[168:169], s[16:17] op_sel_hi:[1,0]
	v_pk_mul_f32 v[172:173], v[172:173], s[16:17] op_sel_hi:[1,0]
	v_pk_fma_f32 v[166:167], v[12:13], v[166:167], v[168:169]
	v_pk_fma_f32 v[164:165], v[14:15], v[164:165], v[172:173]
	v_pk_mul_f32 v[168:169], v[180:181], s[16:17] op_sel_hi:[1,0]
	v_pk_mul_f32 v[172:173], v[182:183], s[16:17] op_sel_hi:[1,0]
	v_pk_fma_f32 v[162:163], v[8:9], v[162:163], v[168:169]
	v_pk_fma_f32 v[172:173], v[10:11], v[160:161], v[172:173]
	v_cvt_pk_bf16_f32 v161, v164, v165
	v_lshl_add_u64 v[164:165], s[20:21], 0, v[170:171]
	v_cvt_pk_bf16_f32 v160, v166, v167
	v_cvt_pk_bf16_f32 v162, v162, v163
	v_cvt_pk_bf16_f32 v163, v172, v173
	v_lshl_add_u64 v[150:151], v[164:165], 0, v[150:151]
	global_store_dwordx4 v[150:151], v[160:163], off sc1
	s_nop 1
	v_lshlrev_b32_e32 v160, 16, v128
	v_and_b32_e32 v161, 0xffff0000, v128
	v_lshlrev_b32_e32 v128, 16, v129
	v_and_b32_e32 v129, 0xffff0000, v129
	v_lshlrev_b32_e32 v162, 16, v130
	v_and_b32_e32 v163, 0xffff0000, v130
	v_lshlrev_b32_e32 v130, 16, v131
	v_and_b32_e32 v131, 0xffff0000, v131
	v_pk_mul_f32 v[160:161], v[160:161], s[16:17] op_sel_hi:[1,0]
	v_pk_mul_f32 v[128:129], v[128:129], s[16:17] op_sel_hi:[1,0]
	v_pk_mul_f32 v[130:131], v[130:131], s[16:17] op_sel_hi:[1,0]
	v_pk_fma_f32 v[156:157], v[6:7], v[156:157], v[128:129]
	v_pk_fma_f32 v[128:129], v[4:5], v[158:159], v[160:161]
	v_pk_mul_f32 v[158:159], v[162:163], s[16:17] op_sel_hi:[1,0]
	v_pk_fma_f32 v[152:153], v[2:3], v[152:153], v[130:131]
	v_pk_fma_f32 v[130:131], v[0:1], v[154:155], v[158:159]
	v_cvt_pk_bf16_f32 v128, v128, v129
	v_cvt_pk_bf16_f32 v129, v156, v157
	v_cvt_pk_bf16_f32 v130, v130, v131
	v_cvt_pk_bf16_f32 v131, v152, v153
	global_store_dwordx4 v[150:151], v[128:131], off offset:256 sc1
	s_cbranch_execz .LBB0_1419

.LBB0_1419:
	s_nop 0
	v_add_u32_e32 v128, 0xffffe000, v146
	s_lshl_b64 s[42:43], s[4:5], 23
	v_ashrrev_i32_e32 v129, 31, v128
	s_add_u32 s42, s78, s42
	s_addc_u32 s43, s79, s43
	v_lshlrev_b64 v[128:129], 14, v[128:129]
	v_lshl_add_u64 v[128:129], s[42:43], 0, v[128:129]
	v_lshlrev_b64 v[130:131], 2, v[148:149]
	v_lshl_add_u64 v[128:129], v[128:129], 0, v[130:131]
	global_store_dwordx4 v[128:129], v[124:127], off sc1
	global_store_dwordx4 v[128:129], v[120:123], off offset:16 sc1
	global_store_dwordx4 v[128:129], v[116:119], off offset:512 sc1
	global_store_dwordx4 v[128:129], v[112:115], off offset:528 sc1
	s_nop 1
	v_add_u32_e32 v112, 0xffffe010, v146
	v_ashrrev_i32_e32 v113, 31, v112
	v_lshlrev_b64 v[112:113], 14, v[112:113]
	v_lshl_add_u64 v[112:113], s[42:43], 0, v[112:113]
	v_lshl_add_u64 v[112:113], v[112:113], 0, v[130:131]
	global_store_dwordx4 v[112:113], v[108:111], off sc1
	global_store_dwordx4 v[112:113], v[104:107], off offset:16 sc1
	global_store_dwordx4 v[112:113], v[100:103], off offset:512 sc1
	global_store_dwordx4 v[112:113], v[96:99], off offset:528 sc1
	s_nop 1
	v_add_u32_e32 v96, 0xffffe020, v146
	v_ashrrev_i32_e32 v97, 31, v96
	v_lshlrev_b64 v[96:97], 14, v[96:97]
	v_lshl_add_u64 v[96:97], s[42:43], 0, v[96:97]
	v_lshl_add_u64 v[96:97], v[96:97], 0, v[130:131]
	global_store_dwordx4 v[96:97], v[92:95], off sc1
	global_store_dwordx4 v[96:97], v[88:91], off offset:16 sc1
	global_store_dwordx4 v[96:97], v[84:87], off offset:512 sc1
	global_store_dwordx4 v[96:97], v[80:83], off offset:528 sc1
	s_nop 1
	v_add_u32_e32 v80, 0xffffe030, v146
	v_ashrrev_i32_e32 v81, 31, v80
	v_lshlrev_b64 v[80:81], 14, v[80:81]
	v_lshl_add_u64 v[80:81], s[42:43], 0, v[80:81]
	v_lshl_add_u64 v[80:81], v[80:81], 0, v[130:131]
	global_store_dwordx4 v[80:81], v[76:79], off sc1
	global_store_dwordx4 v[80:81], v[72:75], off offset:16 sc1
	global_store_dwordx4 v[80:81], v[68:71], off offset:512 sc1
	global_store_dwordx4 v[80:81], v[64:67], off offset:528 sc1
	s_nop 1
	v_add_u32_e32 v64, 0xffffe080, v146
	v_ashrrev_i32_e32 v65, 31, v64
	v_lshlrev_b64 v[64:65], 14, v[64:65]
	v_lshl_add_u64 v[64:65], s[42:43], 0, v[64:65]
	v_lshl_add_u64 v[64:65], v[64:65], 0, v[130:131]
	global_store_dwordx4 v[64:65], v[60:63], off sc1
	global_store_dwordx4 v[64:65], v[56:59], off offset:16 sc1
	global_store_dwordx4 v[64:65], v[52:55], off offset:512 sc1
	global_store_dwordx4 v[64:65], v[48:51], off offset:528 sc1
	s_nop 1
	v_add_u32_e32 v48, 0xffffe090, v146
	v_ashrrev_i32_e32 v49, 31, v48
	v_lshlrev_b64 v[48:49], 14, v[48:49]
	v_lshl_add_u64 v[48:49], s[42:43], 0, v[48:49]
	v_lshl_add_u64 v[48:49], v[48:49], 0, v[130:131]
	global_store_dwordx4 v[48:49], v[44:47], off sc1
	global_store_dwordx4 v[48:49], v[40:43], off offset:16 sc1
	global_store_dwordx4 v[48:49], v[36:39], off offset:512 sc1
	global_store_dwordx4 v[48:49], v[32:35], off offset:528 sc1
	s_nop 1
	v_add_u32_e32 v32, 0xffffe0a0, v146
	v_ashrrev_i32_e32 v33, 31, v32
	v_lshlrev_b64 v[32:33], 14, v[32:33]
	v_lshl_add_u64 v[32:33], s[42:43], 0, v[32:33]
	v_lshl_add_u64 v[32:33], v[32:33], 0, v[130:131]
	global_store_dwordx4 v[32:33], v[28:31], off sc1
	global_store_dwordx4 v[32:33], v[24:27], off offset:16 sc1
	global_store_dwordx4 v[32:33], v[20:23], off offset:512 sc1
	global_store_dwordx4 v[32:33], v[16:19], off offset:528 sc1
	s_nop 1
	v_add_u32_e32 v16, 0xffffe0b0, v146
	v_ashrrev_i32_e32 v17, 31, v16
	v_lshlrev_b64 v[16:17], 14, v[16:17]
	v_lshl_add_u64 v[16:17], s[42:43], 0, v[16:17]
	v_lshl_add_u64 v[16:17], v[16:17], 0, v[130:131]
	global_store_dwordx4 v[16:17], v[12:15], off sc1
	global_store_dwordx4 v[16:17], v[8:11], off offset:16 sc1
	global_store_dwordx4 v[16:17], v[4:7], off offset:512 sc1
	global_store_dwordx4 v[16:17], v[0:3], off offset:528 sc1
	s_and_b64 vcc, exec, s[2:3]
	s_mov_b64 s[2:3], -1
	s_cbranch_vccnz .LBB0_1393
